# stack + first K-iteration of every GEMM unit peeled with zero C input, accumulator zeroing v_movs deleted
# speedup vs baseline: 1.0063x; 1.0063x over previous
; #define PG8_STAGE(bufoff, gbase, voff) do { _Pragma("unroll") for (int _i = 0; _i < 2; ++_i) \
;         __builtin_amdgcn_global_load_lds((const unsigned*)((const char*)(gbase) + (voff)[_i]), (LAS unsigned*)(lds + (bufoff) + ldsw + _i * 8192), 16, 0, 0); } while (0)
; #define PG8_LDA(dst, b, h) do { _Pragma("unroll") for (int m = 0; m < 4; ++m) _Pragma("unroll") for (int k = 0; k < 2; ++k) dst[m][k] = *(const LAS bf16x8*)(lds + PG8_SA(b, h) + aoff + m * 2048 + k * 1024); } while (0)
; template <class Epi>
; __device__ __forceinline__ void gemm_phase(LAS unsigned char* lds, const Gemm g, const StaticOrder S, const Epi E) {
;     ...
;     const char* cA = (const char*)g.A + (size_t)cur.pm * tstep + (size_t)cur.k0 * kstep; const char* cB = (const char*)g.Bt + (size_t)cur.pn * tstep + (size_t)cur.k0 * kstep;
;     PG8_STAGE(PG8_SB(0, 0), cB, voffA); PG8_STAGE(PG8_SA(0, 0), cA, voffA); PG8_STAGE(PG8_SB(0, 1), cB + hstep, voffA); PG8_STAGE(PG8_SA(0, 1), cA + hstep, voffA);
;     if (wr == 1) PG8_BAR;
;     PG8_WAIT_V(4); PG8_BAR;
;     PG8_STAGE(PG8_SB(1, 0), cB + kstep, voffA); PG8_STAGE(PG8_SA(1, 0), cA + kstep, voffA); PG8_STAGE(PG8_SB(1, 1), cB + hstep + kstep, voffA);
;     PG8_WAIT_V(6); PG8_BAR;
;     for (;;) {
;         const bool has_next = S.next(ui + 1, nxt);
;         const char* nA = has_next ? (const char*)g.A + (size_t)nxt.pm * tstep + (size_t)nxt.k0 * kstep : cA; const char* nB = has_next ? (const char*)g.Bt + (size_t)nxt.pn * tstep + (size_t)nxt.k0 * kstep : cB;
;         const int nt = cur.nk;
;         for (int t = 0; t < nt; t += 2) {
;             const bool last = (t == nt - 2);
;             const char* a1 = cA + (size_t)(t + 1) * kstep;
;             const char* a2 = last ? nA : cA + (size_t)(t + 2) * kstep; const char* b2 = last ? nB : cB + (size_t)(t + 2) * kstep;
;             const char* a3 = a2 + kstep; const char* b3 = b2 + kstep;
;             PG8_LDB(B0, 0, 0); PG8_SCHED; PG8_LDA(At, 0, 0); PG8_STAGE(PG8_SA(1, 1), a1 + hstep, voffA);
;             PG8_WAIT_L(8); PG8_BAR; PG8_WAIT_L(0); PG8_MMA(0, 0, At, B0); PG8_BAR; PG8_SCHED;
;             PG8_LDB(B1, 0, 1); PG8_STAGE(PG8_SB(0, 0), b2, voffA);
;             PG8_BAR; PG8_WAIT_L(0); PG8_MMA(0, 1, At, B1); PG8_BAR;
;             PG8_LDA(At, 0, 1); PG8_STAGE(PG8_SA(0, 0), a2, voffA);
;             PG8_BAR; PG8_WAIT_L(0); PG8_MMA(1, 0, At, B0); PG8_BAR; PG8_SCHED;
.LBB0_2218:
	s_ashr_i32 s11, s10, 31
	s_lshl_b64 s[28:29], s[10:11], 20
	v_readlane_b32 s3, v255, 1
	v_cmp_lt_i64_e32 vcc, s[40:41], v[180:181]
	s_add_u32 s40, s3, s28
	v_readlane_b32 s3, v255, 2
	s_addc_u32 s41, s3, s29
	s_and_b64 s[28:29], vcc, exec
	s_cselect_b32 s11, s41, s45
	s_cselect_b32 s28, s40, s44
	s_ashr_i32 s3, s2, 31
	s_lshl_b64 s[30:31], s[2:3], 20
	s_add_u32 s42, s6, s30
	s_addc_u32 s43, s7, s31
	s_and_b64 s[30:31], vcc, exec
	s_cselect_b32 s3, s43, s47
	s_cselect_b32 s29, s42, s46
	s_add_u32 s44, s44, 0x80080
	s_addc_u32 s45, s45, 0
	s_add_u32 s54, s46, 0x100
	s_addc_u32 s55, s47, 0
	s_mov_b32 s56, -2
	s_add_u32 s30, s44, 0xfff80080
	s_addc_u32 s31, s45, -1
	s_add_i32 s57, 0, 0x10000
	v_add_u32_e32 v134, s57, v137
	ds_read_b128 v[140:143], v134
	ds_read_b128 v[144:147], v134 offset:1024
	ds_read_b128 v[148:151], v134 offset:2048
	ds_read_b128 v[152:155], v134 offset:3072
	s_cmp_eq_u32 s56, 28
	s_cselect_b32 s49, s11, s31
	s_cselect_b32 s48, s28, s30
	s_cselect_b32 s47, s3, s55
	s_cselect_b32 s46, s29, s54
	v_lshl_add_u64 v[134:135], s[44:45], 0, v[130:131]
	s_add_i32 m0, s23, 0xc000
	ds_read_b128 v[156:159], v139
	ds_read_b128 v[160:163], v139 offset:1024
	ds_read_b128 v[164:167], v139 offset:2048
	ds_read_b128 v[168:171], v139 offset:3072
	ds_read_b128 v[172:175], v139 offset:4096
	ds_read_b128 v[194:197], v139 offset:5120
	ds_read_b128 v[198:201], v139 offset:6144
	ds_read_b128 v[202:205], v139 offset:7168
	global_load_lds_dwordx4 v[134:135], off
	v_lshl_add_u64 v[134:135], s[44:45], 0, v[132:133]
	s_add_i32 m0, s23, 0xe000
	s_nop 0
	global_load_lds_dwordx4 v[134:135], off
	s_waitcnt lgkmcnt(8)
	s_barrier
	s_waitcnt lgkmcnt(0)
	s_setprio 1
	v_mfma_f32_16x16x32_bf16 v[120:123], v[140:143], v[156:159], 0
	v_mfma_f32_16x16x32_bf16 v[124:127], v[148:151], v[156:159], 0
	v_mfma_f32_16x16x32_bf16 v[104:107], v[140:143], v[164:167], 0
	v_mfma_f32_16x16x32_bf16 v[108:111], v[148:151], v[164:167], 0
	v_mfma_f32_16x16x32_bf16 v[88:91], v[140:143], v[172:175], 0
	v_mfma_f32_16x16x32_bf16 v[92:95], v[148:151], v[172:175], 0
	v_mfma_f32_16x16x32_bf16 v[72:75], v[140:143], v[198:201], 0
	v_mfma_f32_16x16x32_bf16 v[76:79], v[148:151], v[198:201], 0
	v_mfma_f32_16x16x32_bf16 v[120:123], v[144:147], v[160:163], v[120:123]
	v_mfma_f32_16x16x32_bf16 v[124:127], v[152:155], v[160:163], v[124:127]
	v_mfma_f32_16x16x32_bf16 v[104:107], v[144:147], v[168:171], v[104:107]
	v_mfma_f32_16x16x32_bf16 v[108:111], v[152:155], v[168:171], v[108:111]
	v_mfma_f32_16x16x32_bf16 v[88:91], v[144:147], v[194:197], v[88:91]
	v_mfma_f32_16x16x32_bf16 v[92:95], v[152:155], v[194:197], v[92:95]
	v_mfma_f32_16x16x32_bf16 v[72:75], v[144:147], v[202:205], v[72:75]
	v_mfma_f32_16x16x32_bf16 v[76:79], v[152:155], v[202:205], v[76:79]
	s_setprio 0
	s_barrier
	s_add_i32 s58, 0, 0x14000
	v_add_u32_e32 v134, s58, v137
	s_add_i32 s30, s57, s22
	ds_read_b128 v[206:209], v134
	ds_read_b128 v[228:231], v134 offset:1024
	ds_read_b128 v[232:235], v134 offset:2048
	ds_read_b128 v[236:239], v134 offset:3072
	v_lshl_add_u64 v[134:135], s[46:47], 0, v[178:179]
	s_mov_b32 m0, s30
	v_lshl_add_u64 v[210:211], s[46:47], 0, v[128:129]
	global_load_lds_dwordx4 v[134:135], off
	s_add_i32 m0, s30, 0x2000
	s_nop 0
	global_load_lds_dwordx4 v[210:211], off
	s_barrier
	s_waitcnt lgkmcnt(0)
	s_setprio 1
	v_mfma_f32_16x16x32_bf16 v[112:115], v[206:209], v[156:159], 0
	v_mfma_f32_16x16x32_bf16 v[116:119], v[232:235], v[156:159], 0
	v_mfma_f32_16x16x32_bf16 v[96:99], v[206:209], v[164:167], 0
	v_mfma_f32_16x16x32_bf16 v[100:103], v[232:235], v[164:167], 0
	v_mfma_f32_16x16x32_bf16 v[80:83], v[206:209], v[172:175], 0
	v_mfma_f32_16x16x32_bf16 v[84:87], v[232:235], v[172:175], 0
	v_mfma_f32_16x16x32_bf16 v[64:67], v[206:209], v[198:201], 0
	v_mfma_f32_16x16x32_bf16 v[68:71], v[232:235], v[198:201], 0
	v_mfma_f32_16x16x32_bf16 v[112:115], v[228:231], v[160:163], v[112:115]
	v_mfma_f32_16x16x32_bf16 v[116:119], v[236:239], v[160:163], v[116:119]
	v_mfma_f32_16x16x32_bf16 v[96:99], v[228:231], v[168:171], v[96:99]
	v_mfma_f32_16x16x32_bf16 v[100:103], v[236:239], v[168:171], v[100:103]
	v_mfma_f32_16x16x32_bf16 v[80:83], v[228:231], v[194:197], v[80:83]
	v_mfma_f32_16x16x32_bf16 v[84:87], v[236:239], v[194:197], v[84:87]
	v_mfma_f32_16x16x32_bf16 v[64:67], v[228:231], v[202:205], v[64:67]
	v_mfma_f32_16x16x32_bf16 v[68:71], v[236:239], v[202:205], v[68:71]
	s_setprio 0
	s_barrier
	s_mov_b32 m0, s23
	v_lshl_add_u64 v[220:221], s[48:49], 0, v[178:179]
	ds_read_b128 v[156:159], v139 offset:16384
	ds_read_b128 v[160:163], v139 offset:17408
	ds_read_b128 v[164:167], v139 offset:18432
	ds_read_b128 v[168:171], v139 offset:19456
	ds_read_b128 v[172:175], v139 offset:20480
	ds_read_b128 v[194:197], v139 offset:21504
	ds_read_b128 v[198:201], v139 offset:22528
	ds_read_b128 v[202:205], v139 offset:23552
	global_load_lds_dwordx4 v[220:221], off
	v_lshl_add_u64 v[222:223], s[48:49], 0, v[128:129]
	s_mov_b32 m0, s24
	s_nop 0
	global_load_lds_dwordx4 v[222:223], off
	s_barrier
	s_waitcnt lgkmcnt(0)
	s_setprio 1
	v_mfma_f32_16x16x32_bf16 v[56:59], v[140:143], v[156:159], 0
	v_mfma_f32_16x16x32_bf16 v[60:63], v[148:151], v[156:159], 0
	v_mfma_f32_16x16x32_bf16 v[40:43], v[140:143], v[164:167], 0
	v_mfma_f32_16x16x32_bf16 v[44:47], v[148:151], v[164:167], 0
	v_mfma_f32_16x16x32_bf16 v[24:27], v[140:143], v[172:175], 0
	v_mfma_f32_16x16x32_bf16 v[28:31], v[148:151], v[172:175], 0
	v_mfma_f32_16x16x32_bf16 v[8:11], v[140:143], v[198:201], 0
	v_mfma_f32_16x16x32_bf16 v[12:15], v[148:151], v[198:201], 0
	v_mfma_f32_16x16x32_bf16 v[56:59], v[144:147], v[160:163], v[56:59]
	v_mfma_f32_16x16x32_bf16 v[60:63], v[152:155], v[160:163], v[60:63]
	v_mfma_f32_16x16x32_bf16 v[40:43], v[144:147], v[168:171], v[40:43]
	v_mfma_f32_16x16x32_bf16 v[44:47], v[152:155], v[168:171], v[44:47]
	v_mfma_f32_16x16x32_bf16 v[24:27], v[144:147], v[194:197], v[24:27]
	v_mfma_f32_16x16x32_bf16 v[28:31], v[152:155], v[194:197], v[28:31]
	v_mfma_f32_16x16x32_bf16 v[8:11], v[144:147], v[202:205], v[8:11]
	v_mfma_f32_16x16x32_bf16 v[12:15], v[152:155], v[202:205], v[12:15]
	s_setprio 0
	s_barrier
; #define PG8_STAGE(bufoff, gbase, voff) do { _Pragma("unroll") for (int _i = 0; _i < 2; ++_i) \
;         __builtin_amdgcn_global_load_lds((const unsigned*)((const char*)(gbase) + (voff)[_i]), (LAS unsigned*)(lds + (bufoff) + ldsw + _i * 8192), 16, 0, 0); } while (0)
; #define PG8_LDA(dst, b, h) do { _Pragma("unroll") for (int m = 0; m < 4; ++m) _Pragma("unroll") for (int k = 0; k < 2; ++k) dst[m][k] = *(const LAS bf16x8*)(lds + PG8_SA(b, h) + aoff + m * 2048 + k * 1024); } while (0)
; #define PG8_LDB(dst, b, h) do { _Pragma("unroll") for (int n = 0; n < 2; ++n) _Pragma("unroll") for (int k = 0; k < 2; ++k) dst[n][k] = *(const LAS bf16x8*)(lds + PG8_SB(b, h) + boff + n * 2048 + k * 1024); } while (0)
; #define PG8_MMA(ai, bj, At, Bt) do { __builtin_amdgcn_s_setprio(1); _Pragma("unroll") for (int m = 0; m < 4; ++m) _Pragma("unroll") for (int n = 0; n < 2; ++n) _Pragma("unroll") for (int k = 0; k < 2; ++k) \
;         acc[ai][bj][m][n] = __builtin_amdgcn_mfma_f32_16x16x32_bf16(Bt[n][k], At[m][k], acc[ai][bj][m][n], 0, 0, 0); __builtin_amdgcn_s_setprio(0); } while (0)
; #define PG8_WAIT_V(n) asm volatile("s_waitcnt vmcnt(" #n ")" ::: "memory")
; #define PG8_WAIT_L(n) asm volatile("s_waitcnt lgkmcnt(" #n ")" ::: "memory")
; #define PG8_BAR __builtin_amdgcn_s_barrier()
; #define PG8_SCHED __builtin_amdgcn_sched_barrier(0)
; template <class Epi>
; __device__ __forceinline__ void gemm_phase(LAS unsigned char* lds, const Gemm g, const StaticOrder S, const Epi E) {
;     ...
;             PG8_STAGE(PG8_SB(0, 1), b2 + hstep, voffA);
;             PG8_WAIT_V(6); PG8_BAR; PG8_MMA(1, 1, At, B1); PG8_BAR;
;             PG8_LDB(B0, 1, 0); PG8_SCHED; PG8_LDA(At, 1, 0); PG8_STAGE(PG8_SA(0, 1), a2 + hstep, voffA);
;             PG8_WAIT_L(8); PG8_BAR; PG8_WAIT_L(0); PG8_MMA(0, 0, At, B0); PG8_BAR; PG8_SCHED;
;             PG8_LDB(B1, 1, 1); PG8_STAGE(PG8_SB(1, 0), b3, voffA);
;             PG8_BAR; PG8_WAIT_L(0); PG8_MMA(0, 1, At, B1); PG8_BAR;
;             PG8_LDA(At, 1, 1); PG8_STAGE(PG8_SA(1, 0), a3, voffA);
	s_add_u32 s30, s46, 0x80000
	s_addc_u32 s31, s47, 0
	s_add_i32 s57, s58, s22
	v_lshl_add_u64 v[140:141], s[30:31], 0, v[178:179]
	s_mov_b32 m0, s57
	s_nop 0
	global_load_lds_dwordx4 v[140:141], off
	v_lshl_add_u64 v[140:141], s[30:31], 0, v[128:129]
	s_add_i32 m0, s57, 0x2000
	s_nop 0
	global_load_lds_dwordx4 v[140:141], off
	s_waitcnt vmcnt(6)
	s_barrier
	s_setprio 1
	v_mfma_f32_16x16x32_bf16 v[48:51], v[206:209], v[156:159], 0
	v_mfma_f32_16x16x32_bf16 v[52:55], v[232:235], v[156:159], 0
	v_mfma_f32_16x16x32_bf16 v[32:35], v[206:209], v[164:167], 0
	v_mfma_f32_16x16x32_bf16 v[36:39], v[232:235], v[164:167], 0
	v_mfma_f32_16x16x32_bf16 v[16:19], v[206:209], v[172:175], 0
	v_mfma_f32_16x16x32_bf16 v[20:23], v[232:235], v[172:175], 0
	v_mfma_f32_16x16x32_bf16 v[0:3], v[206:209], v[198:201], 0
	v_mfma_f32_16x16x32_bf16 v[4:7], v[232:235], v[198:201], 0
	v_mfma_f32_16x16x32_bf16 v[48:51], v[228:231], v[160:163], v[48:51]
	v_mfma_f32_16x16x32_bf16 v[52:55], v[236:239], v[160:163], v[52:55]
	v_mfma_f32_16x16x32_bf16 v[32:35], v[228:231], v[168:171], v[32:35]
	v_mfma_f32_16x16x32_bf16 v[36:39], v[236:239], v[168:171], v[36:39]
	v_mfma_f32_16x16x32_bf16 v[16:19], v[228:231], v[194:197], v[16:19]
	v_mfma_f32_16x16x32_bf16 v[20:23], v[236:239], v[194:197], v[20:23]
	v_mfma_f32_16x16x32_bf16 v[0:3], v[228:231], v[202:205], v[0:3]
	v_mfma_f32_16x16x32_bf16 v[4:7], v[236:239], v[202:205], v[4:7]
	s_setprio 0
	s_barrier
	s_add_i32 s57, 0, 0x18000
	v_add_u32_e32 v152, s57, v137
	ds_read_b128 v[140:143], v152
	ds_read_b128 v[144:147], v152 offset:1024
	ds_read_b128 v[148:151], v152 offset:2048
	ds_read_b128 v[152:155], v152 offset:3072
	s_add_u32 s30, s48, 0x80000
	s_addc_u32 s31, s49, 0
	s_mov_b32 m0, s25
	v_lshl_add_u64 v[206:207], s[30:31], 0, v[178:179]
	ds_read_b128 v[156:159], v139 offset:32768
	ds_read_b128 v[160:163], v139 offset:33792
	ds_read_b128 v[164:167], v139 offset:34816
	ds_read_b128 v[168:171], v139 offset:35840
	ds_read_b128 v[172:175], v139 offset:36864
	ds_read_b128 v[194:197], v139 offset:37888
	ds_read_b128 v[198:201], v139 offset:38912
	ds_read_b128 v[202:205], v139 offset:39936
	global_load_lds_dwordx4 v[206:207], off
	v_lshl_add_u64 v[206:207], s[30:31], 0, v[128:129]
	s_mov_b32 m0, s50
	s_nop 0
	global_load_lds_dwordx4 v[206:207], off
	s_waitcnt lgkmcnt(8)
	s_barrier
	s_waitcnt lgkmcnt(0)
	s_setprio 1
	v_mfma_f32_16x16x32_bf16 v[120:123], v[140:143], v[156:159], v[120:123]
	v_mfma_f32_16x16x32_bf16 v[124:127], v[148:151], v[156:159], v[124:127]
	v_mfma_f32_16x16x32_bf16 v[104:107], v[140:143], v[164:167], v[104:107]
	v_mfma_f32_16x16x32_bf16 v[108:111], v[148:151], v[164:167], v[108:111]
	v_mfma_f32_16x16x32_bf16 v[88:91], v[140:143], v[172:175], v[88:91]
	v_mfma_f32_16x16x32_bf16 v[92:95], v[148:151], v[172:175], v[92:95]
	v_mfma_f32_16x16x32_bf16 v[72:75], v[140:143], v[198:201], v[72:75]
	v_mfma_f32_16x16x32_bf16 v[76:79], v[148:151], v[198:201], v[76:79]
	v_mfma_f32_16x16x32_bf16 v[120:123], v[144:147], v[160:163], v[120:123]
	v_mfma_f32_16x16x32_bf16 v[124:127], v[152:155], v[160:163], v[124:127]
	v_mfma_f32_16x16x32_bf16 v[104:107], v[144:147], v[168:171], v[104:107]
	v_mfma_f32_16x16x32_bf16 v[108:111], v[152:155], v[168:171], v[108:111]
	v_mfma_f32_16x16x32_bf16 v[88:91], v[144:147], v[194:197], v[88:91]
	v_mfma_f32_16x16x32_bf16 v[92:95], v[152:155], v[194:197], v[92:95]
	v_mfma_f32_16x16x32_bf16 v[72:75], v[144:147], v[202:205], v[72:75]
	v_mfma_f32_16x16x32_bf16 v[76:79], v[152:155], v[202:205], v[76:79]
	s_setprio 0
	s_barrier
	s_add_i32 s48, 0, 0x1c000
	s_add_i32 s30, s57, s22
	v_add_u32_e32 v227, s48, v137
	v_lshl_add_u64 v[134:135], v[134:135], 0, s[34:35]
	s_mov_b32 m0, s30
	ds_read_b128 v[206:209], v227
	ds_read_b128 v[228:231], v227 offset:1024
	ds_read_b128 v[232:235], v227 offset:2048
	ds_read_b128 v[236:239], v227 offset:3072
	global_load_lds_dwordx4 v[134:135], off
	v_lshl_add_u64 v[134:135], v[210:211], 0, s[34:35]
	s_add_i32 m0, s30, 0x2000
	s_nop 0
	global_load_lds_dwordx4 v[134:135], off
	s_barrier
; #define PG8_STAGE(bufoff, gbase, voff) do { _Pragma("unroll") for (int _i = 0; _i < 2; ++_i) \
;         __builtin_amdgcn_global_load_lds((const unsigned*)((const char*)(gbase) + (voff)[_i]), (LAS unsigned*)(lds + (bufoff) + ldsw + _i * 8192), 16, 0, 0); } while (0)
; #define PG8_LDA(dst, b, h) do { _Pragma("unroll") for (int m = 0; m < 4; ++m) _Pragma("unroll") for (int k = 0; k < 2; ++k) dst[m][k] = *(const LAS bf16x8*)(lds + PG8_SA(b, h) + aoff + m * 2048 + k * 1024); } while (0)
; #define PG8_MMA(ai, bj, At, Bt) do { __builtin_amdgcn_s_setprio(1); _Pragma("unroll") for (int m = 0; m < 4; ++m) _Pragma("unroll") for (int n = 0; n < 2; ++n) _Pragma("unroll") for (int k = 0; k < 2; ++k) \
;         acc[ai][bj][m][n] = __builtin_amdgcn_mfma_f32_16x16x32_bf16(Bt[n][k], At[m][k], acc[ai][bj][m][n], 0, 0, 0); __builtin_amdgcn_s_setprio(0); } while (0)
; #define PG8_WAIT_V(n) asm volatile("s_waitcnt vmcnt(" #n ")" ::: "memory")
; #define PG8_WAIT_L(n) asm volatile("s_waitcnt lgkmcnt(" #n ")" ::: "memory")
; #define PG8_BAR __builtin_amdgcn_s_barrier()
; #define PG8_SCHED __builtin_amdgcn_sched_barrier(0)
; template <class Epi>
; __device__ __forceinline__ void gemm_phase(LAS unsigned char* lds, const Gemm g, const StaticOrder S, const Epi E) {
;     ...
;             PG8_BAR; PG8_WAIT_L(0); PG8_MMA(0, 1, At, B1); PG8_BAR;
;             PG8_LDA(At, 1, 1); PG8_STAGE(PG8_SA(1, 0), a3, voffA);
;             PG8_BAR; PG8_WAIT_L(0); PG8_MMA(1, 0, At, B0); PG8_BAR; PG8_SCHED;
;             PG8_STAGE(PG8_SB(1, 1), b3 + hstep, voffA);
;             PG8_WAIT_V(6); PG8_BAR; PG8_MMA(1, 1, At, B1); PG8_BAR;
;         }
	s_waitcnt lgkmcnt(0)
	s_setprio 1
	v_mfma_f32_16x16x32_bf16 v[112:115], v[206:209], v[156:159], v[112:115]
	v_mfma_f32_16x16x32_bf16 v[116:119], v[232:235], v[156:159], v[116:119]
	v_mfma_f32_16x16x32_bf16 v[96:99], v[206:209], v[164:167], v[96:99]
	v_mfma_f32_16x16x32_bf16 v[100:103], v[232:235], v[164:167], v[100:103]
	v_mfma_f32_16x16x32_bf16 v[80:83], v[206:209], v[172:175], v[80:83]
	v_mfma_f32_16x16x32_bf16 v[84:87], v[232:235], v[172:175], v[84:87]
	v_mfma_f32_16x16x32_bf16 v[64:67], v[206:209], v[198:201], v[64:67]
	v_mfma_f32_16x16x32_bf16 v[68:71], v[232:235], v[198:201], v[68:71]
	v_mfma_f32_16x16x32_bf16 v[112:115], v[228:231], v[160:163], v[112:115]
	v_mfma_f32_16x16x32_bf16 v[116:119], v[236:239], v[160:163], v[116:119]
	v_mfma_f32_16x16x32_bf16 v[96:99], v[228:231], v[168:171], v[96:99]
	v_mfma_f32_16x16x32_bf16 v[100:103], v[236:239], v[168:171], v[100:103]
	v_mfma_f32_16x16x32_bf16 v[80:83], v[228:231], v[194:197], v[80:83]
	v_mfma_f32_16x16x32_bf16 v[84:87], v[236:239], v[194:197], v[84:87]
	v_mfma_f32_16x16x32_bf16 v[64:67], v[228:231], v[202:205], v[64:67]
	v_mfma_f32_16x16x32_bf16 v[68:71], v[236:239], v[202:205], v[68:71]
	s_setprio 0
	s_barrier
	s_mov_b32 m0, s51
	v_lshl_add_u64 v[134:135], v[220:221], 0, s[34:35]
	ds_read_b128 v[156:159], v139 offset:49152
	ds_read_b128 v[160:163], v139 offset:50176
	ds_read_b128 v[164:167], v139 offset:51200
	ds_read_b128 v[168:171], v139 offset:52224
	ds_read_b128 v[172:175], v139 offset:53248
	ds_read_b128 v[194:197], v139 offset:54272
	ds_read_b128 v[198:201], v139 offset:55296
	ds_read_b128 v[202:205], v139 offset:56320
	global_load_lds_dwordx4 v[134:135], off
	v_lshl_add_u64 v[134:135], v[222:223], 0, s[34:35]
	s_mov_b32 m0, s52
	s_nop 0
	global_load_lds_dwordx4 v[134:135], off
	s_barrier
	s_waitcnt lgkmcnt(0)
	s_setprio 1
	v_mfma_f32_16x16x32_bf16 v[56:59], v[140:143], v[156:159], v[56:59]
	v_mfma_f32_16x16x32_bf16 v[60:63], v[148:151], v[156:159], v[60:63]
	v_mfma_f32_16x16x32_bf16 v[40:43], v[140:143], v[164:167], v[40:43]
	v_mfma_f32_16x16x32_bf16 v[44:47], v[148:151], v[164:167], v[44:47]
	v_mfma_f32_16x16x32_bf16 v[24:27], v[140:143], v[172:175], v[24:27]
	v_mfma_f32_16x16x32_bf16 v[28:31], v[148:151], v[172:175], v[28:31]
	v_mfma_f32_16x16x32_bf16 v[8:11], v[140:143], v[198:201], v[8:11]
	v_mfma_f32_16x16x32_bf16 v[12:15], v[148:151], v[198:201], v[12:15]
	v_mfma_f32_16x16x32_bf16 v[56:59], v[144:147], v[160:163], v[56:59]
	v_mfma_f32_16x16x32_bf16 v[60:63], v[152:155], v[160:163], v[60:63]
	v_mfma_f32_16x16x32_bf16 v[40:43], v[144:147], v[168:171], v[40:43]
	v_mfma_f32_16x16x32_bf16 v[44:47], v[152:155], v[168:171], v[44:47]
	v_mfma_f32_16x16x32_bf16 v[24:27], v[144:147], v[194:197], v[24:27]
	v_mfma_f32_16x16x32_bf16 v[28:31], v[152:155], v[194:197], v[28:31]
	v_mfma_f32_16x16x32_bf16 v[8:11], v[144:147], v[202:205], v[8:11]
	v_mfma_f32_16x16x32_bf16 v[12:15], v[152:155], v[202:205], v[12:15]
	s_setprio 0
	s_barrier
	s_add_u32 s30, s46, 0x80080
	s_addc_u32 s31, s47, 0
	s_add_i32 s46, s48, s22
	v_lshl_add_u64 v[134:135], s[30:31], 0, v[178:179]
	s_mov_b32 m0, s46
	s_nop 0
	global_load_lds_dwordx4 v[134:135], off
	v_lshl_add_u64 v[134:135], s[30:31], 0, v[128:129]
	s_add_i32 m0, s46, 0x2000
	s_nop 0
	global_load_lds_dwordx4 v[134:135], off
	s_waitcnt vmcnt(6)
	s_barrier
	s_setprio 1
	v_mfma_f32_16x16x32_bf16 v[48:51], v[206:209], v[156:159], v[48:51]
	v_mfma_f32_16x16x32_bf16 v[52:55], v[232:235], v[156:159], v[52:55]
	v_mfma_f32_16x16x32_bf16 v[32:35], v[206:209], v[164:167], v[32:35]
	v_mfma_f32_16x16x32_bf16 v[36:39], v[232:235], v[164:167], v[36:39]
	v_mfma_f32_16x16x32_bf16 v[16:19], v[206:209], v[172:175], v[16:19]
	v_mfma_f32_16x16x32_bf16 v[20:23], v[232:235], v[172:175], v[20:23]
	v_mfma_f32_16x16x32_bf16 v[0:3], v[206:209], v[198:201], v[0:3]
	v_mfma_f32_16x16x32_bf16 v[4:7], v[232:235], v[198:201], v[4:7]
	v_mfma_f32_16x16x32_bf16 v[48:51], v[228:231], v[160:163], v[48:51]
	v_mfma_f32_16x16x32_bf16 v[52:55], v[236:239], v[160:163], v[52:55]
	v_mfma_f32_16x16x32_bf16 v[32:35], v[228:231], v[168:171], v[32:35]
	v_mfma_f32_16x16x32_bf16 v[36:39], v[236:239], v[168:171], v[36:39]
	v_mfma_f32_16x16x32_bf16 v[16:19], v[228:231], v[194:197], v[16:19]
	v_mfma_f32_16x16x32_bf16 v[20:23], v[236:239], v[194:197], v[20:23]
	v_mfma_f32_16x16x32_bf16 v[0:3], v[228:231], v[202:205], v[0:3]
	v_mfma_f32_16x16x32_bf16 v[4:7], v[236:239], v[202:205], v[4:7]
	s_setprio 0
	s_barrier
	s_add_i32 s56, s56, 2
	s_add_u32 s44, s44, 0x100
	s_addc_u32 s45, s45, 0
	s_add_u32 s54, s54, 0x100
	s_addc_u32 s55, s55, 0
	s_cmp_gt_u32 s56, 29
	s_cbranch_scc0 .LBB0_2219
	s_branch .Lpeel_exit_0

; __device__ __forceinline__ unsigned cvt_pk_bf16(float lo, float hi) { unsigned r; asm("v_cvt_pk_bf16_f32 %0, %1, %2" : "=v"(r) : "v"(lo), "v"(hi)); return r; }
;     __device__ __forceinline__ void operator()(AccRef acc, const pg8::Unit& u, int wr, int wc, int fr, int fq) const {
;     ...
;             for (int m = 0; m < 4; ++m) { bf16_t* rowp = G + (size_t)(row0 + ai * 128 + m * 16) * FH + col0;
; #pragma unroll
;                 for (int bj = 0; bj < 2; ++bj) { const f32x4 gq = acc[ai][bj][m][0], uq = acc[ai][bj][m][1]; float v[4];
; #pragma unroll
;                     for (int i = 0; i < 4; ++i) v[i] = gq[i] * uq[i] * __builtin_amdgcn_rcpf(1.f + __builtin_amdgcn_exp2f(-gq[i] * LOG2E));
;                     u32x2 w; w.x = cvt_pk_bf16(v[0], v[1]); w.y = cvt_pk_bf16(v[2], v[3]);
;                     *(u32x2*)(rowp + bj * 64) = w; } }
.Lpeel_exit_0:
	v_mul_f32_e32 v116, v116, v112
	v_mul_f32_e32 v112, 0xbfb8aa3b, v112
	v_exp_f32_e32 v112, v112
	v_mul_f32_e32 v100, v100, v96
	v_mul_f32_e32 v96, 0xbfb8aa3b, v96
	v_exp_f32_e32 v96, v96
	v_mul_f32_e32 v84, v84, v80
	v_mul_f32_e32 v80, 0xbfb8aa3b, v80
	v_add_f32_e32 v112, 1.0, v112
	v_exp_f32_e32 v80, v80
	v_rcp_f32_e32 v112, v112
	v_mul_f32_e32 v68, v68, v64
	v_mul_f32_e32 v64, 0xbfb8aa3b, v64
	v_add_f32_e32 v96, 1.0, v96
	v_exp_f32_e32 v64, v64
	v_rcp_f32_e32 v96, v96
	v_mul_f32_e32 v52, v52, v48
	v_mul_f32_e32 v48, 0xbfb8aa3b, v48
	v_add_f32_e32 v80, 1.0, v80
	v_exp_f32_e32 v48, v48
	v_mul_f32_e32 v112, v116, v112
	v_mul_f32_e32 v116, v117, v113
	v_mul_f32_e32 v113, 0xbfb8aa3b, v113
	v_rcp_f32_e32 v80, v80
	v_mul_f32_e32 v36, v36, v32
	v_mul_f32_e32 v32, 0xbfb8aa3b, v32
	v_exp_f32_e32 v113, v113
	v_add_f32_e32 v64, 1.0, v64
	v_exp_f32_e32 v32, v32
	v_mul_f32_e32 v96, v100, v96
	v_mul_f32_e32 v100, v101, v97
	v_mul_f32_e32 v97, 0xbfb8aa3b, v97
	v_rcp_f32_e32 v64, v64
	v_mul_f32_e32 v20, v20, v16
	v_mul_f32_e32 v16, 0xbfb8aa3b, v16
	v_exp_f32_e32 v97, v97
	v_add_f32_e32 v48, 1.0, v48
	v_exp_f32_e32 v16, v16
	v_mul_f32_e32 v80, v84, v80
	v_mul_f32_e32 v84, v85, v81
	v_mul_f32_e32 v81, 0xbfb8aa3b, v81
	v_rcp_f32_e32 v48, v48
	v_mul_f32_e32 v124, v124, v120
	v_mul_f32_e32 v120, 0xbfb8aa3b, v120
	v_add_f32_e32 v113, 1.0, v113
	v_mul_f32_e32 v108, v108, v104
	v_mul_f32_e32 v104, 0xbfb8aa3b, v104
	v_mul_f32_e32 v92, v92, v88
	v_mul_f32_e32 v88, 0xbfb8aa3b, v88
	v_exp_f32_e32 v81, v81
	v_mul_f32_e32 v76, v76, v72
	v_mul_f32_e32 v72, 0xbfb8aa3b, v72
	v_mul_f32_e32 v60, v60, v56
	v_mul_f32_e32 v56, 0xbfb8aa3b, v56
	v_mul_f32_e32 v44, v44, v40
	v_mul_f32_e32 v40, 0xbfb8aa3b, v40
	v_add_f32_e32 v32, 1.0, v32
	v_mul_f32_e32 v28, v28, v24
	v_mul_f32_e32 v24, 0xbfb8aa3b, v24
	v_mul_f32_e32 v12, v12, v8
	v_mul_f32_e32 v8, 0xbfb8aa3b, v8
	v_mul_f32_e32 v4, v4, v0
	v_mul_f32_e32 v0, 0xbfb8aa3b, v0
	v_exp_f32_e32 v120, v120
	v_rcp_f32_e32 v113, v113
	v_exp_f32_e32 v104, v104
	v_exp_f32_e32 v88, v88
	v_exp_f32_e32 v72, v72
	v_mul_f32_e32 v64, v68, v64
	v_mul_f32_e32 v68, v69, v65
	v_mul_f32_e32 v65, 0xbfb8aa3b, v65
	v_exp_f32_e32 v56, v56
	v_exp_f32_e32 v40, v40
	v_rcp_f32_e32 v32, v32
	v_exp_f32_e32 v24, v24
	v_exp_f32_e32 v8, v8
	v_exp_f32_e32 v0, v0
	v_add_f32_e32 v97, 1.0, v97
	v_exp_f32_e32 v65, v65
	v_add_f32_e32 v16, 1.0, v16
	v_rcp_f32_e32 v97, v97
	v_mul_f32_e32 v48, v52, v48
	v_mul_f32_e32 v52, v53, v49
	v_mul_f32_e32 v49, 0xbfb8aa3b, v49
	v_rcp_f32_e32 v16, v16
	v_add_f32_e32 v81, 1.0, v81
	v_exp_f32_e32 v49, v49
	v_add_f32_e32 v120, 1.0, v120
	v_mul_f32_e32 v113, v116, v113
	v_mul_f32_e32 v116, v118, v114
	v_mul_f32_e32 v114, 0xbfb8aa3b, v114
	v_add_f32_e32 v104, 1.0, v104
	v_add_f32_e32 v88, 1.0, v88
	v_rcp_f32_e32 v81, v81
	v_add_f32_e32 v72, 1.0, v72
	v_add_f32_e32 v56, 1.0, v56
	v_add_f32_e32 v40, 1.0, v40
	v_mul_f32_e32 v32, v36, v32
	v_mul_f32_e32 v36, v37, v33
	v_mul_f32_e32 v33, 0xbfb8aa3b, v33
	v_add_f32_e32 v24, 1.0, v24
	v_add_f32_e32 v8, 1.0, v8
	v_add_f32_e32 v0, 1.0, v0
	v_rcp_f32_e32 v120, v120
	v_exp_f32_e32 v114, v114
	v_rcp_f32_e32 v104, v104
	v_rcp_f32_e32 v88, v88
	v_rcp_f32_e32 v72, v72
	v_add_f32_e32 v65, 1.0, v65
	v_rcp_f32_e32 v56, v56
	v_rcp_f32_e32 v40, v40
	v_exp_f32_e32 v33, v33
	v_rcp_f32_e32 v24, v24
	v_rcp_f32_e32 v8, v8
	v_rcp_f32_e32 v0, v0
	v_mul_f32_e32 v97, v100, v97
	v_mul_f32_e32 v100, v102, v98
	v_mul_f32_e32 v98, 0xbfb8aa3b, v98
	v_rcp_f32_e32 v65, v65
	v_mul_f32_e32 v16, v20, v16
	v_mul_f32_e32 v20, v21, v17
	v_mul_f32_e32 v17, 0xbfb8aa3b, v17
	v_exp_f32_e32 v98, v98
	v_add_f32_e32 v49, 1.0, v49
	v_exp_f32_e32 v17, v17
	v_mul_f32_e32 v81, v84, v81
	v_mul_f32_e32 v84, v86, v82
	v_mul_f32_e32 v82, 0xbfb8aa3b, v82
	v_rcp_f32_e32 v49, v49
	v_mul_f32_e32 v120, v124, v120
	v_mul_f32_e32 v124, v125, v121
	v_mul_f32_e32 v121, 0xbfb8aa3b, v121
	v_add_f32_e32 v114, 1.0, v114
	v_mul_f32_e32 v104, v108, v104
	v_mul_f32_e32 v108, v109, v105
	v_mul_f32_e32 v105, 0xbfb8aa3b, v105
	v_mul_f32_e32 v88, v92, v88
	v_mul_f32_e32 v92, v93, v89
	v_mul_f32_e32 v89, 0xbfb8aa3b, v89
	v_exp_f32_e32 v82, v82
	v_mul_f32_e32 v72, v76, v72
	v_mul_f32_e32 v76, v77, v73
	v_mul_f32_e32 v73, 0xbfb8aa3b, v73
	v_mul_f32_e32 v56, v60, v56
	v_mul_f32_e32 v60, v61, v57
	v_mul_f32_e32 v57, 0xbfb8aa3b, v57
	v_mul_f32_e32 v40, v44, v40
	v_mul_f32_e32 v44, v45, v41
	v_mul_f32_e32 v41, 0xbfb8aa3b, v41
	v_add_f32_e32 v33, 1.0, v33
	v_mul_f32_e32 v24, v28, v24
	v_mul_f32_e32 v28, v29, v25
	v_mul_f32_e32 v25, 0xbfb8aa3b, v25
	v_mul_f32_e32 v8, v12, v8
	v_mul_f32_e32 v12, v13, v9
	v_mul_f32_e32 v9, 0xbfb8aa3b, v9
	v_mul_f32_e32 v0, v4, v0
	v_mul_f32_e32 v4, v5, v1
	v_mul_f32_e32 v1, 0xbfb8aa3b, v1
	v_exp_f32_e32 v121, v121
	v_rcp_f32_e32 v114, v114
	v_exp_f32_e32 v105, v105
	v_exp_f32_e32 v89, v89
	v_exp_f32_e32 v73, v73
	v_mul_f32_e32 v65, v68, v65
	v_mul_f32_e32 v68, v70, v66
	v_mul_f32_e32 v66, 0xbfb8aa3b, v66
	v_exp_f32_e32 v57, v57
	v_exp_f32_e32 v41, v41
	v_rcp_f32_e32 v33, v33
	v_exp_f32_e32 v25, v25
	v_exp_f32_e32 v9, v9
	v_exp_f32_e32 v1, v1
	v_add_f32_e32 v98, 1.0, v98
	v_exp_f32_e32 v66, v66
	v_add_f32_e32 v17, 1.0, v17
	v_rcp_f32_e32 v98, v98
	v_mul_f32_e32 v49, v52, v49
	v_mul_f32_e32 v52, v54, v50
	v_mul_f32_e32 v50, 0xbfb8aa3b, v50
	v_rcp_f32_e32 v17, v17
	v_add_f32_e32 v82, 1.0, v82
	v_exp_f32_e32 v50, v50
	v_add_f32_e32 v121, 1.0, v121
	v_mul_f32_e32 v114, v116, v114
	v_mul_f32_e32 v116, v119, v115
	v_mul_f32_e32 v115, 0xbfb8aa3b, v115
	v_add_f32_e32 v105, 1.0, v105
	v_add_f32_e32 v89, 1.0, v89
	v_rcp_f32_e32 v82, v82
	v_add_f32_e32 v73, 1.0, v73
	v_add_f32_e32 v57, 1.0, v57
	v_add_f32_e32 v41, 1.0, v41
; __device__ __forceinline__ unsigned cvt_pk_bf16(float lo, float hi) { unsigned r; asm("v_cvt_pk_bf16_f32 %0, %1, %2" : "=v"(r) : "v"(lo), "v"(hi)); return r; }
;     __device__ __forceinline__ void operator()(AccRef acc, const pg8::Unit& u, int wr, int wc, int fr, int fq) const {
;     ...
;             for (int m = 0; m < 4; ++m) { bf16_t* rowp = G + (size_t)(row0 + ai * 128 + m * 16) * FH + col0;
; #pragma unroll
;                 for (int bj = 0; bj < 2; ++bj) { const f32x4 gq = acc[ai][bj][m][0], uq = acc[ai][bj][m][1]; float v[4];
; #pragma unroll
;                     for (int i = 0; i < 4; ++i) v[i] = gq[i] * uq[i] * __builtin_amdgcn_rcpf(1.f + __builtin_amdgcn_exp2f(-gq[i] * LOG2E));
;                     u32x2 w; w.x = cvt_pk_bf16(v[0], v[1]); w.y = cvt_pk_bf16(v[2], v[3]);
;                     *(u32x2*)(rowp + bj * 64) = w; } }
	v_mul_f32_e32 v33, v36, v33
	v_mul_f32_e32 v36, v38, v34
	v_mul_f32_e32 v34, 0xbfb8aa3b, v34
	v_add_f32_e32 v25, 1.0, v25
	v_add_f32_e32 v9, 1.0, v9
	v_add_f32_e32 v1, 1.0, v1
	v_rcp_f32_e32 v121, v121
	v_exp_f32_e32 v115, v115
	v_rcp_f32_e32 v105, v105
	v_rcp_f32_e32 v89, v89
	v_rcp_f32_e32 v73, v73
	v_add_f32_e32 v66, 1.0, v66
	v_rcp_f32_e32 v57, v57
	v_rcp_f32_e32 v41, v41
	v_exp_f32_e32 v34, v34
	v_rcp_f32_e32 v25, v25
	v_rcp_f32_e32 v9, v9
	v_rcp_f32_e32 v1, v1
	v_mul_f32_e32 v98, v100, v98
	v_mul_f32_e32 v100, v103, v99
	v_mul_f32_e32 v99, 0xbfb8aa3b, v99
	v_rcp_f32_e32 v66, v66
	v_mul_f32_e32 v17, v20, v17
	v_mul_f32_e32 v20, v22, v18
	v_mul_f32_e32 v18, 0xbfb8aa3b, v18
	v_exp_f32_e32 v99, v99
	v_add_f32_e32 v50, 1.0, v50
	v_exp_f32_e32 v18, v18
	v_mul_f32_e32 v82, v84, v82
	v_mul_f32_e32 v84, v87, v83
	v_mul_f32_e32 v83, 0xbfb8aa3b, v83
	v_rcp_f32_e32 v50, v50
	v_mul_f32_e32 v121, v124, v121
	v_mul_f32_e32 v124, v126, v122
	v_mul_f32_e32 v122, 0xbfb8aa3b, v122
	v_add_f32_e32 v115, 1.0, v115
	v_mul_f32_e32 v105, v108, v105
	v_mul_f32_e32 v108, v110, v106
	v_mul_f32_e32 v106, 0xbfb8aa3b, v106
	v_mul_f32_e32 v89, v92, v89
	v_mul_f32_e32 v92, v94, v90
	v_mul_f32_e32 v90, 0xbfb8aa3b, v90
	v_exp_f32_e32 v83, v83
	v_mul_f32_e32 v73, v76, v73
	v_mul_f32_e32 v76, v78, v74
	v_mul_f32_e32 v74, 0xbfb8aa3b, v74
	v_mul_f32_e32 v57, v60, v57
	v_mul_f32_e32 v60, v62, v58
	v_mul_f32_e32 v58, 0xbfb8aa3b, v58
	v_mul_f32_e32 v41, v44, v41
	v_mul_f32_e32 v44, v46, v42
	v_mul_f32_e32 v42, 0xbfb8aa3b, v42
	v_add_f32_e32 v34, 1.0, v34
	v_mul_f32_e32 v25, v28, v25
	v_mul_f32_e32 v28, v30, v26
	v_mul_f32_e32 v26, 0xbfb8aa3b, v26
	v_mul_f32_e32 v9, v12, v9
	v_mul_f32_e32 v12, v14, v10
	v_mul_f32_e32 v10, 0xbfb8aa3b, v10
	v_mul_f32_e32 v1, v4, v1
	v_mul_f32_e32 v4, v6, v2
	v_mul_f32_e32 v2, 0xbfb8aa3b, v2
	v_lshl_or_b32 v134, s26, 7, v138
	v_exp_f32_e32 v122, v122
	v_rcp_f32_e32 v115, v115
	v_exp_f32_e32 v106, v106
	v_exp_f32_e32 v90, v90
	v_exp_f32_e32 v74, v74
	v_mul_f32_e32 v66, v68, v66
	v_mul_f32_e32 v68, v71, v67
	v_mul_f32_e32 v67, 0xbfb8aa3b, v67
	v_exp_f32_e32 v58, v58
	v_exp_f32_e32 v42, v42
	v_rcp_f32_e32 v34, v34
	v_exp_f32_e32 v26, v26
	v_exp_f32_e32 v10, v10
	v_exp_f32_e32 v2, v2
	v_ashrrev_i32_e32 v135, 31, v134
	v_add_f32_e32 v99, 1.0, v99
	v_exp_f32_e32 v67, v67
	v_add_f32_e32 v18, 1.0, v18
	v_lshl_add_u32 v140, s27, 8, v136
	v_lshl_add_u64 v[134:135], v[134:135], 1, s[74:75]
	v_rcp_f32_e32 v99, v99
	v_mul_f32_e32 v50, v52, v50
	v_mul_f32_e32 v52, v55, v51
	v_mul_f32_e32 v51, 0xbfb8aa3b, v51
	v_rcp_f32_e32 v18, v18
	v_mad_i64_i32 v[142:143], s[26:27], v140, s33, v[134:135]
	v_cvt_pk_bf16_f32 v112, v112, v113
	v_add_f32_e32 v83, 1.0, v83
	v_exp_f32_e32 v51, v51
	v_add_f32_e32 v122, 1.0, v122
	v_mul_f32_e32 v115, v116, v115
	v_cvt_pk_bf16_f32 v113, v114, v115
	global_store_dwordx2 v[142:143], v[112:113], off offset:128
	v_or_b32_e32 v112, 16, v140
	v_add_f32_e32 v106, 1.0, v106
	v_add_f32_e32 v90, 1.0, v90
	v_rcp_f32_e32 v83, v83
	v_add_f32_e32 v74, 1.0, v74
	v_add_f32_e32 v58, 1.0, v58
	v_add_f32_e32 v42, 1.0, v42
	v_mul_f32_e32 v34, v36, v34
	v_mul_f32_e32 v36, v39, v35
	v_mul_f32_e32 v35, 0xbfb8aa3b, v35
	v_add_f32_e32 v26, 1.0, v26
	v_add_f32_e32 v10, 1.0, v10
	v_add_f32_e32 v2, 1.0, v2
	v_rcp_f32_e32 v122, v122
	v_mad_i64_i32 v[112:113], s[26:27], v112, s33, v[134:135]
	v_rcp_f32_e32 v106, v106
	v_cvt_pk_bf16_f32 v96, v96, v97
	v_rcp_f32_e32 v90, v90
	v_rcp_f32_e32 v74, v74
	v_add_f32_e32 v67, 1.0, v67
	v_rcp_f32_e32 v58, v58
	v_rcp_f32_e32 v42, v42
	v_exp_f32_e32 v35, v35
	v_rcp_f32_e32 v26, v26
	v_rcp_f32_e32 v10, v10
	v_rcp_f32_e32 v2, v2
	v_mul_f32_e32 v99, v100, v99
	v_cvt_pk_bf16_f32 v97, v98, v99
	global_store_dwordx2 v[112:113], v[96:97], off offset:128
	v_or_b32_e32 v96, 32, v140
	v_rcp_f32_e32 v67, v67
	v_mul_f32_e32 v18, v20, v18
	v_mul_f32_e32 v20, v23, v19
	v_mul_f32_e32 v19, 0xbfb8aa3b, v19
	v_mad_i64_i32 v[96:97], s[26:27], v96, s33, v[134:135]
	v_cvt_pk_bf16_f32 v80, v80, v81
	v_add_f32_e32 v51, 1.0, v51
	v_exp_f32_e32 v19, v19
	v_mul_f32_e32 v83, v84, v83
	v_cvt_pk_bf16_f32 v81, v82, v83
	global_store_dwordx2 v[96:97], v[80:81], off offset:128
	v_or_b32_e32 v80, 48, v140
	v_rcp_f32_e32 v51, v51
; __device__ __forceinline__ unsigned cvt_pk_bf16(float lo, float hi) { unsigned r; asm("v_cvt_pk_bf16_f32 %0, %1, %2" : "=v"(r) : "v"(lo), "v"(hi)); return r; }
; #define PG8_WAIT_V(n) asm volatile("s_waitcnt vmcnt(" #n ")" ::: "memory")
; #define PG8_BAR __builtin_amdgcn_s_barrier()
; template <class Epi>
; __device__ __forceinline__ void gemm_phase(LAS unsigned char* lds, const Gemm g, const StaticOrder S, const Epi E) {
;     ...
;         if (!has_next) break;
; #pragma unroll
;         for (int a = 0; a < 2; ++a)
; #pragma unroll
;             for (int b = 0; b < 2; ++b)
; #pragma unroll
;                 for (int m = 0; m < 4; ++m)
; #pragma unroll
;                     for (int n = 0; n < 2; ++n) acc[a][b][m][n] = (f32x4){0.f, 0.f, 0.f, 0.f};
;         cur = nxt; cA = nA; cB = nB; ++ui;
;     }
;     PG8_WAIT_V(0);
;     if (wr == 0) PG8_BAR;
;     PG8_BAR;
;     __device__ __forceinline__ void operator()(AccRef acc, const pg8::Unit& u, int wr, int wc, int fr, int fq) const {
;     ...
;             for (int m = 0; m < 4; ++m) { bf16_t* rowp = G + (size_t)(row0 + ai * 128 + m * 16) * FH + col0;
; #pragma unroll
;                 for (int bj = 0; bj < 2; ++bj) { const f32x4 gq = acc[ai][bj][m][0], uq = acc[ai][bj][m][1]; float v[4];
; #pragma unroll
;                     for (int i = 0; i < 4; ++i) v[i] = gq[i] * uq[i] * __builtin_amdgcn_rcpf(1.f + __builtin_amdgcn_exp2f(-gq[i] * LOG2E));
;                     u32x2 w; w.x = cvt_pk_bf16(v[0], v[1]); w.y = cvt_pk_bf16(v[2], v[3]);
;                     *(u32x2*)(rowp + bj * 64) = w; } }
	v_mul_f32_e32 v122, v124, v122
	v_mul_f32_e32 v124, v127, v123
	v_mul_f32_e32 v123, 0xbfb8aa3b, v123
	v_mul_f32_e32 v106, v108, v106
	v_mul_f32_e32 v108, v111, v107
	v_mul_f32_e32 v107, 0xbfb8aa3b, v107
	v_mul_f32_e32 v90, v92, v90
	v_mul_f32_e32 v92, v95, v91
	v_mul_f32_e32 v91, 0xbfb8aa3b, v91
	v_mad_i64_i32 v[80:81], s[26:27], v80, s33, v[134:135]
	v_mul_f32_e32 v74, v76, v74
	v_mul_f32_e32 v76, v79, v75
	v_mul_f32_e32 v75, 0xbfb8aa3b, v75
	v_cvt_pk_bf16_f32 v64, v64, v65
	v_mul_f32_e32 v58, v60, v58
	v_mul_f32_e32 v60, v63, v59
	v_mul_f32_e32 v59, 0xbfb8aa3b, v59
	v_mul_f32_e32 v42, v44, v42
	v_mul_f32_e32 v44, v47, v43
	v_mul_f32_e32 v43, 0xbfb8aa3b, v43
	v_add_f32_e32 v35, 1.0, v35
	v_mul_f32_e32 v26, v28, v26
	v_mul_f32_e32 v28, v31, v27
	v_mul_f32_e32 v27, 0xbfb8aa3b, v27
	v_mul_f32_e32 v10, v12, v10
	v_mul_f32_e32 v12, v15, v11
	v_mul_f32_e32 v11, 0xbfb8aa3b, v11
	v_mul_f32_e32 v2, v4, v2
	v_mul_f32_e32 v4, v7, v3
	v_mul_f32_e32 v3, 0xbfb8aa3b, v3
	v_exp_f32_e32 v123, v123
	v_exp_f32_e32 v107, v107
	v_exp_f32_e32 v91, v91
	v_exp_f32_e32 v75, v75
	v_mul_f32_e32 v67, v68, v67
	v_cvt_pk_bf16_f32 v65, v66, v67
	global_store_dwordx2 v[80:81], v[64:65], off offset:128
	v_add_u32_e32 v64, 0x80, v140
	v_exp_f32_e32 v59, v59
	v_exp_f32_e32 v43, v43
	v_rcp_f32_e32 v35, v35
	v_exp_f32_e32 v27, v27
	v_exp_f32_e32 v11, v11
	v_exp_f32_e32 v3, v3
	v_mad_i64_i32 v[64:65], s[26:27], v64, s33, v[134:135]
	v_cvt_pk_bf16_f32 v48, v48, v49
	v_add_f32_e32 v19, 1.0, v19
	v_mul_f32_e32 v51, v52, v51
	v_cvt_pk_bf16_f32 v49, v50, v51
	global_store_dwordx2 v[64:65], v[48:49], off offset:128
	v_add_u32_e32 v48, 0x90, v140
	v_rcp_f32_e32 v19, v19
	v_mad_i64_i32 v[48:49], s[26:27], v48, s33, v[134:135]
	v_cvt_pk_bf16_f32 v32, v32, v33
	v_add_f32_e32 v123, 1.0, v123
	v_add_f32_e32 v107, 1.0, v107
	v_add_f32_e32 v91, 1.0, v91
	v_add_f32_e32 v75, 1.0, v75
	v_add_f32_e32 v59, 1.0, v59
	v_add_f32_e32 v43, 1.0, v43
	v_mul_f32_e32 v35, v36, v35
	v_cvt_pk_bf16_f32 v33, v34, v35
	global_store_dwordx2 v[48:49], v[32:33], off offset:128
	v_add_u32_e32 v32, 0xa0, v140
	v_add_f32_e32 v27, 1.0, v27
	v_add_f32_e32 v11, 1.0, v11
	v_add_f32_e32 v3, 1.0, v3
	v_rcp_f32_e32 v123, v123
	v_rcp_f32_e32 v107, v107
	v_rcp_f32_e32 v91, v91
	v_rcp_f32_e32 v75, v75
	v_rcp_f32_e32 v59, v59
	v_rcp_f32_e32 v43, v43
	v_mad_i64_i32 v[32:33], s[26:27], v32, s33, v[134:135]
	v_rcp_f32_e32 v27, v27
	v_cvt_pk_bf16_f32 v16, v16, v17
	v_rcp_f32_e32 v11, v11
	v_rcp_f32_e32 v3, v3
	v_mul_f32_e32 v19, v20, v19
	v_cvt_pk_bf16_f32 v17, v18, v19
	global_store_dwordx2 v[32:33], v[16:17], off offset:128
	v_add_u32_e32 v16, 0xb0, v140
	v_mad_i64_i32 v[16:17], s[26:27], v16, s33, v[134:135]
	s_and_b64 vcc, exec, s[38:39]
	s_mov_b32 s26, s2
	s_mov_b32 s27, s10
	s_mov_b64 s[46:47], s[42:43]
	s_mov_b64 s[44:45], s[40:41]
	v_mul_f32_e32 v123, v124, v123
	v_cvt_pk_bf16_f32 v120, v120, v121
	v_cvt_pk_bf16_f32 v121, v122, v123
	global_store_dwordx2 v[142:143], v[120:121], off
	v_mul_f32_e32 v107, v108, v107
	v_cvt_pk_bf16_f32 v104, v104, v105
	v_cvt_pk_bf16_f32 v105, v106, v107
	global_store_dwordx2 v[112:113], v[104:105], off
	v_mul_f32_e32 v91, v92, v91
	v_cvt_pk_bf16_f32 v88, v88, v89
	v_cvt_pk_bf16_f32 v89, v90, v91
	global_store_dwordx2 v[96:97], v[88:89], off
	v_mul_f32_e32 v75, v76, v75
	v_cvt_pk_bf16_f32 v72, v72, v73
	v_cvt_pk_bf16_f32 v73, v74, v75
	global_store_dwordx2 v[80:81], v[72:73], off
	v_mul_f32_e32 v59, v60, v59
	v_cvt_pk_bf16_f32 v56, v56, v57
	v_cvt_pk_bf16_f32 v57, v58, v59
	global_store_dwordx2 v[64:65], v[56:57], off
	v_mul_f32_e32 v43, v44, v43
	v_cvt_pk_bf16_f32 v40, v40, v41
	v_cvt_pk_bf16_f32 v41, v42, v43
	global_store_dwordx2 v[48:49], v[40:41], off
	v_mul_f32_e32 v27, v28, v27
	v_cvt_pk_bf16_f32 v24, v24, v25
	v_cvt_pk_bf16_f32 v25, v26, v27
	global_store_dwordx2 v[32:33], v[24:25], off
	v_mul_f32_e32 v11, v12, v11
	v_cvt_pk_bf16_f32 v8, v8, v9
	v_cvt_pk_bf16_f32 v9, v10, v11
	global_store_dwordx2 v[16:17], v[8:9], off
	v_mul_f32_e32 v3, v4, v3
	v_cvt_pk_bf16_f32 v0, v0, v1
	v_cvt_pk_bf16_f32 v1, v2, v3
	global_store_dwordx2 v[16:17], v[0:1], off offset:128
	s_cbranch_vccz .LBB0_2212
	s_waitcnt vmcnt(0)
	s_cmpk_gt_u32 s4, 0xff
	s_cbranch_scc1 .LBB0_2223
	s_barrier

; #define PG8_STAGE(bufoff, gbase, voff) do { _Pragma("unroll") for (int _i = 0; _i < 2; ++_i) \
;         __builtin_amdgcn_global_load_lds((const unsigned*)((const char*)(gbase) + (voff)[_i]), (LAS unsigned*)(lds + (bufoff) + ldsw + _i * 8192), 16, 0, 0); } while (0)
; #define PG8_LDA(dst, b, h) do { _Pragma("unroll") for (int m = 0; m < 4; ++m) _Pragma("unroll") for (int k = 0; k < 2; ++k) dst[m][k] = *(const LAS bf16x8*)(lds + PG8_SA(b, h) + aoff + m * 2048 + k * 1024); } while (0)
; #define PG8_LDB(dst, b, h) do { _Pragma("unroll") for (int n = 0; n < 2; ++n) _Pragma("unroll") for (int k = 0; k < 2; ++k) dst[n][k] = *(const LAS bf16x8*)(lds + PG8_SB(b, h) + boff + n * 2048 + k * 1024); } while (0)
; #define PG8_MMA(ai, bj, At, Bt) do { __builtin_amdgcn_s_setprio(1); _Pragma("unroll") for (int m = 0; m < 4; ++m) _Pragma("unroll") for (int n = 0; n < 2; ++n) _Pragma("unroll") for (int k = 0; k < 2; ++k) \
;         acc[ai][bj][m][n] = __builtin_amdgcn_mfma_f32_16x16x32_bf16(Bt[n][k], At[m][k], acc[ai][bj][m][n], 0, 0, 0); __builtin_amdgcn_s_setprio(0); } while (0)
; #define PG8_WAIT_L(n) asm volatile("s_waitcnt lgkmcnt(" #n ")" ::: "memory")
; #define PG8_BAR __builtin_amdgcn_s_barrier()
; #define PG8_SCHED __builtin_amdgcn_sched_barrier(0)
; template <class Epi>
; __device__ __forceinline__ void gemm_phase(LAS unsigned char* lds, const Gemm g, const StaticOrder S, const Epi E) {
;     ...
;         for (int t = 0; t < nt; t += 2) {
;             const bool last = (t == nt - 2);
;             const char* a1 = cA + (size_t)(t + 1) * kstep;
;             const char* a2 = last ? nA : cA + (size_t)(t + 2) * kstep; const char* b2 = last ? nB : cB + (size_t)(t + 2) * kstep;
;             const char* a3 = a2 + kstep; const char* b3 = b2 + kstep;
;             PG8_LDB(B0, 0, 0); PG8_SCHED; PG8_LDA(At, 0, 0); PG8_STAGE(PG8_SA(1, 1), a1 + hstep, voffA);
;             PG8_WAIT_L(8); PG8_BAR; PG8_WAIT_L(0); PG8_MMA(0, 0, At, B0); PG8_BAR; PG8_SCHED;
;             PG8_LDB(B1, 0, 1); PG8_STAGE(PG8_SB(0, 0), b2, voffA);
;             PG8_BAR; PG8_WAIT_L(0); PG8_MMA(0, 1, At, B1); PG8_BAR;
;             PG8_LDA(At, 0, 1); PG8_STAGE(PG8_SA(0, 0), a2, voffA);
;             PG8_BAR; PG8_WAIT_L(0); PG8_MMA(1, 0, At, B0); PG8_BAR; PG8_SCHED;
.LBB0_2572:
	s_add_i32 s11, s63, -2
	s_add_u32 s64, s64, 0x100
	s_addc_u32 s65, s65, 0
	s_mov_b32 s50, 0
	s_add_i32 s66, s50, 2
	s_add_u32 s48, s38, 0x100
	s_addc_u32 s49, s39, 0
	s_add_i32 s30, 0, 0x10000
	v_add_u32_e32 v140, s30, v228
	ds_read_b128 v[128:131], v140
	ds_read_b128 v[132:135], v140 offset:1024
	ds_read_b128 v[136:139], v140 offset:2048
	ds_read_b128 v[140:143], v140 offset:3072
	s_cmp_eq_u32 s11, s50
	s_cselect_b32 s50, s46, s64
	s_cselect_b32 s53, s43, s49
	s_cselect_b32 s52, s42, s48
	s_cselect_b32 s51, s47, s65
	v_lshl_add_u64 v[200:201], s[38:39], 0, v[196:197]
	s_add_i32 m0, s23, 0xc000
	ds_read_b128 v[144:147], v230
	ds_read_b128 v[148:151], v230 offset:1024
	ds_read_b128 v[152:155], v230 offset:2048
	ds_read_b128 v[156:159], v230 offset:3072
	ds_read_b128 v[160:163], v230 offset:4096
	ds_read_b128 v[164:167], v230 offset:5120
	ds_read_b128 v[168:171], v230 offset:6144
	ds_read_b128 v[172:175], v230 offset:7168
	global_load_lds_dwordx4 v[200:201], off
	v_lshl_add_u64 v[200:201], s[38:39], 0, v[198:199]
	s_add_i32 m0, s23, 0xe000
	s_nop 0
	global_load_lds_dwordx4 v[200:201], off
	s_waitcnt lgkmcnt(8)
	s_barrier
	s_waitcnt lgkmcnt(0)
	s_setprio 1
	v_mfma_f32_16x16x32_bf16 v[124:127], v[128:131], v[144:147], 0
	v_mfma_f32_16x16x32_bf16 v[120:123], v[136:139], v[144:147], 0
	v_mfma_f32_16x16x32_bf16 v[112:115], v[128:131], v[152:155], 0
	v_mfma_f32_16x16x32_bf16 v[104:107], v[136:139], v[152:155], 0
	v_mfma_f32_16x16x32_bf16 v[92:95], v[128:131], v[160:163], 0
	v_mfma_f32_16x16x32_bf16 v[88:91], v[136:139], v[160:163], 0
	v_mfma_f32_16x16x32_bf16 v[80:83], v[128:131], v[168:171], 0
	v_mfma_f32_16x16x32_bf16 v[72:75], v[136:139], v[168:171], 0
	v_mfma_f32_16x16x32_bf16 v[124:127], v[132:135], v[148:151], v[124:127]
	v_mfma_f32_16x16x32_bf16 v[120:123], v[140:143], v[148:151], v[120:123]
	v_mfma_f32_16x16x32_bf16 v[112:115], v[132:135], v[156:159], v[112:115]
	v_mfma_f32_16x16x32_bf16 v[104:107], v[140:143], v[156:159], v[104:107]
	v_mfma_f32_16x16x32_bf16 v[92:95], v[132:135], v[164:167], v[92:95]
	v_mfma_f32_16x16x32_bf16 v[88:91], v[140:143], v[164:167], v[88:91]
	v_mfma_f32_16x16x32_bf16 v[80:83], v[132:135], v[172:175], v[80:83]
	v_mfma_f32_16x16x32_bf16 v[72:75], v[140:143], v[172:175], v[72:75]
	s_setprio 0
	s_barrier
	s_add_i32 s38, 0, 0x14000
	v_add_u32_e32 v220, s38, v228
	s_add_i32 s30, s30, s22
	ds_read_b128 v[200:203], v220
	ds_read_b128 v[204:207], v220 offset:1024
	ds_read_b128 v[208:211], v220 offset:2048
	ds_read_b128 v[232:235], v220 offset:3072
	v_lshl_add_u64 v[220:221], s[50:51], 0, v[178:179]
	s_mov_b32 m0, s30
	v_lshl_add_u64 v[222:223], s[50:51], 0, v[194:195]
	global_load_lds_dwordx4 v[220:221], off
	s_add_i32 m0, s30, 0x2000
	s_nop 0
	global_load_lds_dwordx4 v[222:223], off
	s_barrier
	s_waitcnt lgkmcnt(0)
	s_setprio 1
	v_mfma_f32_16x16x32_bf16 v[116:119], v[200:203], v[144:147], 0
	v_mfma_f32_16x16x32_bf16 v[108:111], v[208:211], v[144:147], 0
	v_mfma_f32_16x16x32_bf16 v[100:103], v[200:203], v[152:155], 0
	v_mfma_f32_16x16x32_bf16 v[96:99], v[208:211], v[152:155], 0
	v_mfma_f32_16x16x32_bf16 v[84:87], v[200:203], v[160:163], 0
	v_mfma_f32_16x16x32_bf16 v[76:79], v[208:211], v[160:163], 0
	v_mfma_f32_16x16x32_bf16 v[68:71], v[200:203], v[168:171], 0
	v_mfma_f32_16x16x32_bf16 v[64:67], v[208:211], v[168:171], 0
	v_mfma_f32_16x16x32_bf16 v[116:119], v[204:207], v[148:151], v[116:119]
	v_mfma_f32_16x16x32_bf16 v[108:111], v[232:235], v[148:151], v[108:111]
	v_mfma_f32_16x16x32_bf16 v[100:103], v[204:207], v[156:159], v[100:103]
	v_mfma_f32_16x16x32_bf16 v[96:99], v[232:235], v[156:159], v[96:99]
	v_mfma_f32_16x16x32_bf16 v[84:87], v[204:207], v[164:167], v[84:87]
	v_mfma_f32_16x16x32_bf16 v[76:79], v[232:235], v[164:167], v[76:79]
	v_mfma_f32_16x16x32_bf16 v[68:71], v[204:207], v[172:175], v[68:71]
	v_mfma_f32_16x16x32_bf16 v[64:67], v[232:235], v[172:175], v[64:67]
	s_setprio 0
	s_barrier
	s_mov_b32 m0, s23
	v_lshl_add_u64 v[236:237], s[52:53], 0, v[178:179]
	ds_read_b128 v[144:147], v230 offset:16384
	ds_read_b128 v[148:151], v230 offset:17408
	ds_read_b128 v[152:155], v230 offset:18432
	ds_read_b128 v[156:159], v230 offset:19456
	ds_read_b128 v[160:163], v230 offset:20480
	ds_read_b128 v[164:167], v230 offset:21504
	ds_read_b128 v[168:171], v230 offset:22528
	ds_read_b128 v[172:175], v230 offset:23552
	global_load_lds_dwordx4 v[236:237], off
	v_lshl_add_u64 v[238:239], s[52:53], 0, v[194:195]
	s_mov_b32 m0, s24
	s_nop 0
	global_load_lds_dwordx4 v[238:239], off
	s_barrier
	s_waitcnt lgkmcnt(0)
	s_setprio 1
	v_mfma_f32_16x16x32_bf16 v[60:63], v[128:131], v[144:147], 0
	v_mfma_f32_16x16x32_bf16 v[56:59], v[136:139], v[144:147], 0
	v_mfma_f32_16x16x32_bf16 v[48:51], v[128:131], v[152:155], 0
	v_mfma_f32_16x16x32_bf16 v[40:43], v[136:139], v[152:155], 0
	v_mfma_f32_16x16x32_bf16 v[28:31], v[128:131], v[160:163], 0
	v_mfma_f32_16x16x32_bf16 v[24:27], v[136:139], v[160:163], 0
	v_mfma_f32_16x16x32_bf16 v[16:19], v[128:131], v[168:171], 0
	v_mfma_f32_16x16x32_bf16 v[8:11], v[136:139], v[168:171], 0
	v_mfma_f32_16x16x32_bf16 v[60:63], v[132:135], v[148:151], v[60:63]
	v_mfma_f32_16x16x32_bf16 v[56:59], v[140:143], v[148:151], v[56:59]
	v_mfma_f32_16x16x32_bf16 v[48:51], v[132:135], v[156:159], v[48:51]
	v_mfma_f32_16x16x32_bf16 v[40:43], v[140:143], v[156:159], v[40:43]
	v_mfma_f32_16x16x32_bf16 v[28:31], v[132:135], v[164:167], v[28:31]
	v_mfma_f32_16x16x32_bf16 v[24:27], v[140:143], v[164:167], v[24:27]
	v_mfma_f32_16x16x32_bf16 v[16:19], v[132:135], v[172:175], v[16:19]
	v_mfma_f32_16x16x32_bf16 v[8:11], v[140:143], v[172:175], v[8:11]
	s_setprio 0
	s_barrier
; #define PG8_STAGE(bufoff, gbase, voff) do { _Pragma("unroll") for (int _i = 0; _i < 2; ++_i) \
;         __builtin_amdgcn_global_load_lds((const unsigned*)((const char*)(gbase) + (voff)[_i]), (LAS unsigned*)(lds + (bufoff) + ldsw + _i * 8192), 16, 0, 0); } while (0)
; #define PG8_LDA(dst, b, h) do { _Pragma("unroll") for (int m = 0; m < 4; ++m) _Pragma("unroll") for (int k = 0; k < 2; ++k) dst[m][k] = *(const LAS bf16x8*)(lds + PG8_SA(b, h) + aoff + m * 2048 + k * 1024); } while (0)
; #define PG8_LDB(dst, b, h) do { _Pragma("unroll") for (int n = 0; n < 2; ++n) _Pragma("unroll") for (int k = 0; k < 2; ++k) dst[n][k] = *(const LAS bf16x8*)(lds + PG8_SB(b, h) + boff + n * 2048 + k * 1024); } while (0)
; #define PG8_MMA(ai, bj, At, Bt) do { __builtin_amdgcn_s_setprio(1); _Pragma("unroll") for (int m = 0; m < 4; ++m) _Pragma("unroll") for (int n = 0; n < 2; ++n) _Pragma("unroll") for (int k = 0; k < 2; ++k) \
;         acc[ai][bj][m][n] = __builtin_amdgcn_mfma_f32_16x16x32_bf16(Bt[n][k], At[m][k], acc[ai][bj][m][n], 0, 0, 0); __builtin_amdgcn_s_setprio(0); } while (0)
; #define PG8_WAIT_V(n) asm volatile("s_waitcnt vmcnt(" #n ")" ::: "memory")
; #define PG8_WAIT_L(n) asm volatile("s_waitcnt lgkmcnt(" #n ")" ::: "memory")
; #define PG8_BAR __builtin_amdgcn_s_barrier()
; #define PG8_SCHED __builtin_amdgcn_sched_barrier(0)
; template <class Epi>
; __device__ __forceinline__ void gemm_phase(LAS unsigned char* lds, const Gemm g, const StaticOrder S, const Epi E) {
;     ...
;             PG8_STAGE(PG8_SB(0, 1), b2 + hstep, voffA);
;             PG8_WAIT_V(6); PG8_BAR; PG8_MMA(1, 1, At, B1); PG8_BAR;
;             PG8_LDB(B0, 1, 0); PG8_SCHED; PG8_LDA(At, 1, 0); PG8_STAGE(PG8_SA(0, 1), a2 + hstep, voffA);
;             PG8_WAIT_L(8); PG8_BAR; PG8_WAIT_L(0); PG8_MMA(0, 0, At, B0); PG8_BAR; PG8_SCHED;
;             PG8_LDB(B1, 1, 1); PG8_STAGE(PG8_SB(1, 0), b3, voffA);
;             PG8_BAR; PG8_WAIT_L(0); PG8_MMA(0, 1, At, B1); PG8_BAR;
;             PG8_LDA(At, 1, 1); PG8_STAGE(PG8_SA(1, 0), a3, voffA);
	s_add_u32 s30, s50, 0x158000
	s_addc_u32 s31, s51, 0
	s_add_i32 s38, s38, s22
	v_lshl_add_u64 v[128:129], s[30:31], 0, v[178:179]
	s_mov_b32 m0, s38
	s_nop 0
	global_load_lds_dwordx4 v[128:129], off
	v_lshl_add_u64 v[128:129], s[30:31], 0, v[194:195]
	s_add_i32 m0, s38, 0x2000
	s_nop 0
	global_load_lds_dwordx4 v[128:129], off
	s_waitcnt vmcnt(6)
	s_barrier
	s_setprio 1
	v_mfma_f32_16x16x32_bf16 v[52:55], v[200:203], v[144:147], 0
	v_mfma_f32_16x16x32_bf16 v[44:47], v[208:211], v[144:147], 0
	v_mfma_f32_16x16x32_bf16 v[36:39], v[200:203], v[152:155], 0
	v_mfma_f32_16x16x32_bf16 v[32:35], v[208:211], v[152:155], 0
	v_mfma_f32_16x16x32_bf16 v[20:23], v[200:203], v[160:163], 0
	v_mfma_f32_16x16x32_bf16 v[12:15], v[208:211], v[160:163], 0
	v_mfma_f32_16x16x32_bf16 v[4:7], v[200:203], v[168:171], 0
	v_mfma_f32_16x16x32_bf16 v[0:3], v[208:211], v[168:171], 0
	v_mfma_f32_16x16x32_bf16 v[52:55], v[204:207], v[148:151], v[52:55]
	v_mfma_f32_16x16x32_bf16 v[44:47], v[232:235], v[148:151], v[44:47]
	v_mfma_f32_16x16x32_bf16 v[36:39], v[204:207], v[156:159], v[36:39]
	v_mfma_f32_16x16x32_bf16 v[32:35], v[232:235], v[156:159], v[32:35]
	v_mfma_f32_16x16x32_bf16 v[20:23], v[204:207], v[164:167], v[20:23]
	v_mfma_f32_16x16x32_bf16 v[12:15], v[232:235], v[164:167], v[12:15]
	v_mfma_f32_16x16x32_bf16 v[4:7], v[204:207], v[172:175], v[4:7]
	v_mfma_f32_16x16x32_bf16 v[0:3], v[232:235], v[172:175], v[0:3]
	s_setprio 0
	s_barrier
	s_add_i32 s38, 0, 0x18000
	v_add_u32_e32 v140, s38, v228
	ds_read_b128 v[128:131], v140
	ds_read_b128 v[132:135], v140 offset:1024
	ds_read_b128 v[136:139], v140 offset:2048
	ds_read_b128 v[140:143], v140 offset:3072
	s_add_u32 s30, s52, 0x158000
	s_addc_u32 s31, s53, 0
	s_mov_b32 m0, s25
	v_lshl_add_u64 v[200:201], s[30:31], 0, v[178:179]
	ds_read_b128 v[144:147], v230 offset:32768
	ds_read_b128 v[148:151], v230 offset:33792
	ds_read_b128 v[152:155], v230 offset:34816
	ds_read_b128 v[156:159], v230 offset:35840
	ds_read_b128 v[160:163], v230 offset:36864
	ds_read_b128 v[164:167], v230 offset:37888
	ds_read_b128 v[168:171], v230 offset:38912
	ds_read_b128 v[172:175], v230 offset:39936
	global_load_lds_dwordx4 v[200:201], off
	v_lshl_add_u64 v[200:201], s[30:31], 0, v[194:195]
	s_mov_b32 m0, s14
	s_nop 0
	global_load_lds_dwordx4 v[200:201], off
	s_waitcnt lgkmcnt(8)
	s_barrier
	s_waitcnt lgkmcnt(0)
	s_setprio 1
	v_mfma_f32_16x16x32_bf16 v[124:127], v[128:131], v[144:147], v[124:127]
	v_mfma_f32_16x16x32_bf16 v[120:123], v[136:139], v[144:147], v[120:123]
	v_mfma_f32_16x16x32_bf16 v[112:115], v[128:131], v[152:155], v[112:115]
	v_mfma_f32_16x16x32_bf16 v[104:107], v[136:139], v[152:155], v[104:107]
	v_mfma_f32_16x16x32_bf16 v[92:95], v[128:131], v[160:163], v[92:95]
	v_mfma_f32_16x16x32_bf16 v[88:91], v[136:139], v[160:163], v[88:91]
	v_mfma_f32_16x16x32_bf16 v[80:83], v[128:131], v[168:171], v[80:83]
	v_mfma_f32_16x16x32_bf16 v[72:75], v[136:139], v[168:171], v[72:75]
	v_mfma_f32_16x16x32_bf16 v[124:127], v[132:135], v[148:151], v[124:127]
	v_mfma_f32_16x16x32_bf16 v[120:123], v[140:143], v[148:151], v[120:123]
	v_mfma_f32_16x16x32_bf16 v[112:115], v[132:135], v[156:159], v[112:115]
	v_mfma_f32_16x16x32_bf16 v[104:107], v[140:143], v[156:159], v[104:107]
	v_mfma_f32_16x16x32_bf16 v[92:95], v[132:135], v[164:167], v[92:95]
	v_mfma_f32_16x16x32_bf16 v[88:91], v[140:143], v[164:167], v[88:91]
	v_mfma_f32_16x16x32_bf16 v[80:83], v[132:135], v[172:175], v[80:83]
	v_mfma_f32_16x16x32_bf16 v[72:75], v[140:143], v[172:175], v[72:75]
	s_setprio 0
	s_barrier
	s_add_i32 s39, 0, 0x1c000
	s_add_i32 s30, s38, s22
	v_add_u32_e32 v231, s39, v228
	v_lshl_add_u64 v[220:221], v[220:221], 0, s[34:35]
	s_mov_b32 m0, s30
	ds_read_b128 v[200:203], v231
	ds_read_b128 v[204:207], v231 offset:1024
	ds_read_b128 v[208:211], v231 offset:2048
	ds_read_b128 v[232:235], v231 offset:3072
	global_load_lds_dwordx4 v[220:221], off
	v_lshl_add_u64 v[220:221], v[222:223], 0, s[34:35]
	s_add_i32 m0, s30, 0x2000
	s_nop 0
	global_load_lds_dwordx4 v[220:221], off
	s_barrier
; #define PG8_STAGE(bufoff, gbase, voff) do { _Pragma("unroll") for (int _i = 0; _i < 2; ++_i) \
;         __builtin_amdgcn_global_load_lds((const unsigned*)((const char*)(gbase) + (voff)[_i]), (LAS unsigned*)(lds + (bufoff) + ldsw + _i * 8192), 16, 0, 0); } while (0)
; #define PG8_LDA(dst, b, h) do { _Pragma("unroll") for (int m = 0; m < 4; ++m) _Pragma("unroll") for (int k = 0; k < 2; ++k) dst[m][k] = *(const LAS bf16x8*)(lds + PG8_SA(b, h) + aoff + m * 2048 + k * 1024); } while (0)
; #define PG8_MMA(ai, bj, At, Bt) do { __builtin_amdgcn_s_setprio(1); _Pragma("unroll") for (int m = 0; m < 4; ++m) _Pragma("unroll") for (int n = 0; n < 2; ++n) _Pragma("unroll") for (int k = 0; k < 2; ++k) \
;         acc[ai][bj][m][n] = __builtin_amdgcn_mfma_f32_16x16x32_bf16(Bt[n][k], At[m][k], acc[ai][bj][m][n], 0, 0, 0); __builtin_amdgcn_s_setprio(0); } while (0)
; #define PG8_WAIT_V(n) asm volatile("s_waitcnt vmcnt(" #n ")" ::: "memory")
; #define PG8_WAIT_L(n) asm volatile("s_waitcnt lgkmcnt(" #n ")" ::: "memory")
; #define PG8_BAR __builtin_amdgcn_s_barrier()
; #define PG8_SCHED __builtin_amdgcn_sched_barrier(0)
; template <class Epi>
; __device__ __forceinline__ void gemm_phase(LAS unsigned char* lds, const Gemm g, const StaticOrder S, const Epi E) {
;     ...
;         for (int t = 0; t < nt; t += 2) {
;     ...
;             PG8_LDA(At, 1, 1); PG8_STAGE(PG8_SA(1, 0), a3, voffA);
;             PG8_BAR; PG8_WAIT_L(0); PG8_MMA(1, 0, At, B0); PG8_BAR; PG8_SCHED;
;             PG8_STAGE(PG8_SB(1, 1), b3 + hstep, voffA);
;             PG8_WAIT_V(6); PG8_BAR; PG8_MMA(1, 1, At, B1); PG8_BAR;
;         }
	s_waitcnt lgkmcnt(0)
	s_setprio 1
	v_mfma_f32_16x16x32_bf16 v[116:119], v[200:203], v[144:147], v[116:119]
	v_mfma_f32_16x16x32_bf16 v[108:111], v[208:211], v[144:147], v[108:111]
	v_mfma_f32_16x16x32_bf16 v[100:103], v[200:203], v[152:155], v[100:103]
	v_mfma_f32_16x16x32_bf16 v[96:99], v[208:211], v[152:155], v[96:99]
	v_mfma_f32_16x16x32_bf16 v[84:87], v[200:203], v[160:163], v[84:87]
	v_mfma_f32_16x16x32_bf16 v[76:79], v[208:211], v[160:163], v[76:79]
	v_mfma_f32_16x16x32_bf16 v[68:71], v[200:203], v[168:171], v[68:71]
	v_mfma_f32_16x16x32_bf16 v[64:67], v[208:211], v[168:171], v[64:67]
	v_mfma_f32_16x16x32_bf16 v[116:119], v[204:207], v[148:151], v[116:119]
	v_mfma_f32_16x16x32_bf16 v[108:111], v[232:235], v[148:151], v[108:111]
	v_mfma_f32_16x16x32_bf16 v[100:103], v[204:207], v[156:159], v[100:103]
	v_mfma_f32_16x16x32_bf16 v[96:99], v[232:235], v[156:159], v[96:99]
	v_mfma_f32_16x16x32_bf16 v[84:87], v[204:207], v[164:167], v[84:87]
	v_mfma_f32_16x16x32_bf16 v[76:79], v[232:235], v[164:167], v[76:79]
	v_mfma_f32_16x16x32_bf16 v[68:71], v[204:207], v[172:175], v[68:71]
	v_mfma_f32_16x16x32_bf16 v[64:67], v[232:235], v[172:175], v[64:67]
	s_setprio 0
	s_barrier
	s_mov_b32 m0, s57
	v_lshl_add_u64 v[220:221], v[236:237], 0, s[34:35]
	ds_read_b128 v[144:147], v230 offset:49152
	ds_read_b128 v[148:151], v230 offset:50176
	ds_read_b128 v[152:155], v230 offset:51200
	ds_read_b128 v[156:159], v230 offset:52224
	ds_read_b128 v[160:163], v230 offset:53248
	ds_read_b128 v[164:167], v230 offset:54272
	ds_read_b128 v[168:171], v230 offset:55296
	ds_read_b128 v[172:175], v230 offset:56320
	global_load_lds_dwordx4 v[220:221], off
	v_lshl_add_u64 v[220:221], v[238:239], 0, s[34:35]
	s_mov_b32 m0, s58
	s_nop 0
	global_load_lds_dwordx4 v[220:221], off
	s_barrier
	s_waitcnt lgkmcnt(0)
	s_setprio 1
	v_mfma_f32_16x16x32_bf16 v[60:63], v[128:131], v[144:147], v[60:63]
	v_mfma_f32_16x16x32_bf16 v[56:59], v[136:139], v[144:147], v[56:59]
	v_mfma_f32_16x16x32_bf16 v[48:51], v[128:131], v[152:155], v[48:51]
	v_mfma_f32_16x16x32_bf16 v[40:43], v[136:139], v[152:155], v[40:43]
	v_mfma_f32_16x16x32_bf16 v[28:31], v[128:131], v[160:163], v[28:31]
	v_mfma_f32_16x16x32_bf16 v[24:27], v[136:139], v[160:163], v[24:27]
	v_mfma_f32_16x16x32_bf16 v[16:19], v[128:131], v[168:171], v[16:19]
	v_mfma_f32_16x16x32_bf16 v[8:11], v[136:139], v[168:171], v[8:11]
	v_mfma_f32_16x16x32_bf16 v[60:63], v[132:135], v[148:151], v[60:63]
	v_mfma_f32_16x16x32_bf16 v[56:59], v[140:143], v[148:151], v[56:59]
	v_mfma_f32_16x16x32_bf16 v[48:51], v[132:135], v[156:159], v[48:51]
	v_mfma_f32_16x16x32_bf16 v[40:43], v[140:143], v[156:159], v[40:43]
	v_mfma_f32_16x16x32_bf16 v[28:31], v[132:135], v[164:167], v[28:31]
	v_mfma_f32_16x16x32_bf16 v[24:27], v[140:143], v[164:167], v[24:27]
	v_mfma_f32_16x16x32_bf16 v[16:19], v[132:135], v[172:175], v[16:19]
	v_mfma_f32_16x16x32_bf16 v[8:11], v[140:143], v[172:175], v[8:11]
	s_setprio 0
	s_barrier
	s_add_u32 s30, s50, 0x158080
	s_addc_u32 s31, s51, 0
	s_add_i32 s38, s39, s22
	v_lshl_add_u64 v[128:129], s[30:31], 0, v[178:179]
	s_mov_b32 m0, s38
	s_nop 0
	global_load_lds_dwordx4 v[128:129], off
	v_lshl_add_u64 v[128:129], s[30:31], 0, v[194:195]
	s_add_i32 m0, s38, 0x2000
	s_nop 0
	global_load_lds_dwordx4 v[128:129], off
	s_waitcnt vmcnt(6)
	s_barrier
	s_setprio 1
	v_mfma_f32_16x16x32_bf16 v[52:55], v[200:203], v[144:147], v[52:55]
	v_mfma_f32_16x16x32_bf16 v[44:47], v[208:211], v[144:147], v[44:47]
	v_mfma_f32_16x16x32_bf16 v[36:39], v[200:203], v[152:155], v[36:39]
	v_mfma_f32_16x16x32_bf16 v[32:35], v[208:211], v[152:155], v[32:35]
	v_mfma_f32_16x16x32_bf16 v[20:23], v[200:203], v[160:163], v[20:23]
	v_mfma_f32_16x16x32_bf16 v[12:15], v[208:211], v[160:163], v[12:15]
	v_mfma_f32_16x16x32_bf16 v[4:7], v[200:203], v[168:171], v[4:7]
	v_mfma_f32_16x16x32_bf16 v[0:3], v[208:211], v[168:171], v[0:3]
	v_mfma_f32_16x16x32_bf16 v[52:55], v[204:207], v[148:151], v[52:55]
	v_mfma_f32_16x16x32_bf16 v[44:47], v[232:235], v[148:151], v[44:47]
	v_mfma_f32_16x16x32_bf16 v[36:39], v[204:207], v[156:159], v[36:39]
	v_mfma_f32_16x16x32_bf16 v[32:35], v[232:235], v[156:159], v[32:35]
	v_mfma_f32_16x16x32_bf16 v[20:23], v[204:207], v[164:167], v[20:23]
	v_mfma_f32_16x16x32_bf16 v[12:15], v[232:235], v[164:167], v[12:15]
	v_mfma_f32_16x16x32_bf16 v[4:7], v[204:207], v[172:175], v[4:7]
	v_mfma_f32_16x16x32_bf16 v[0:3], v[232:235], v[172:175], v[0:3]
	s_setprio 0
	s_barrier
	s_add_u32 s64, s64, 0x100
	s_addc_u32 s65, s65, 0
	s_cmp_ge_i32 s66, s63
	s_mov_b64 s[38:39], s[48:49]
	s_mov_b32 s50, s66
	s_cbranch_scc0 .LBB0_2573
	s_branch .Lpeel_exit_1

;     __device__ __forceinline__ void operator()(AccRef acc, const pg8::Unit& u, int wr, int wc, int fr, int fq) const {
;         const int row0 = u.pm * 256 + wr * 64 + fr, col0 = u.pn * 256 + wc * 32 + 4 * fq;
;         const int v = u.pm < 32 ? (u.pm >> 3) : 4;
;         f32x4 gv[2][2];
; #pragma unroll
;         for (int bj = 0; bj < 2; ++bj)
; #pragma unroll
;             for (int n = 0; n < 2; ++n) gv[bj][n] = *(const f32x4*)(gate + (size_t)v * MODW + col0 + bj * 128 + n * 16) * coef;
;         const bool part = u.part != 0;
;         float* base = part ? PART + ((size_t)u.ks * NCTX - NLAT) * DM : X;
.Lpeel_exit_1:
	s_cmp_gt_i32 s28, 31
	s_mov_b64 s[38:39], 0x12000
	s_cbranch_scc1 .LBB0_2576
	s_ashr_i32 s11, s28, 3
	s_mul_hi_i32 s39, s11, 0x4800
	s_mul_i32 s38, s11, 0x4800

; #define PG8_STAGE(bufoff, gbase, voff) do { _Pragma("unroll") for (int _i = 0; _i < 2; ++_i) \
;         __builtin_amdgcn_global_load_lds((const unsigned*)((const char*)(gbase) + (voff)[_i]), (LAS unsigned*)(lds + (bufoff) + ldsw + _i * 8192), 16, 0, 0); } while (0)
; #define PG8_LDA(dst, b, h) do { _Pragma("unroll") for (int m = 0; m < 4; ++m) _Pragma("unroll") for (int k = 0; k < 2; ++k) dst[m][k] = *(const LAS bf16x8*)(lds + PG8_SA(b, h) + aoff + m * 2048 + k * 1024); } while (0)
; #define PG8_LDB(dst, b, h) do { _Pragma("unroll") for (int n = 0; n < 2; ++n) _Pragma("unroll") for (int k = 0; k < 2; ++k) dst[n][k] = *(const LAS bf16x8*)(lds + PG8_SB(b, h) + boff + n * 2048 + k * 1024); } while (0)
; #define PG8_MMA(ai, bj, At, Bt) do { __builtin_amdgcn_s_setprio(1); _Pragma("unroll") for (int m = 0; m < 4; ++m) _Pragma("unroll") for (int n = 0; n < 2; ++n) _Pragma("unroll") for (int k = 0; k < 2; ++k) \
;         acc[ai][bj][m][n] = __builtin_amdgcn_mfma_f32_16x16x32_bf16(Bt[n][k], At[m][k], acc[ai][bj][m][n], 0, 0, 0); __builtin_amdgcn_s_setprio(0); } while (0)
; template <class Epi>
; __device__ __forceinline__ void gemm_phase(LAS unsigned char* lds, const Gemm g, const StaticOrder S, const Epi E) {
;     ...
;         const bool has_next = S.next(ui + 1, nxt);
;         const char* nA = has_next ? (const char*)g.A + (size_t)nxt.pm * tstep + (size_t)nxt.k0 * kstep : cA; const char* nB = has_next ? (const char*)g.Bt + (size_t)nxt.pn * tstep + (size_t)nxt.k0 * kstep : cB;
;         const int nt = cur.nk;
;         for (int t = 0; t < nt; t += 2) {
;             const bool last = (t == nt - 2);
;             const char* a1 = cA + (size_t)(t + 1) * kstep;
;             const char* a2 = last ? nA : cA + (size_t)(t + 2) * kstep; const char* b2 = last ? nB : cB + (size_t)(t + 2) * kstep;
;             const char* a3 = a2 + kstep; const char* b3 = b2 + kstep;
;             PG8_LDB(B0, 0, 0); PG8_SCHED; PG8_LDA(At, 0, 0); PG8_STAGE(PG8_SA(1, 1), a1 + hstep, voffA);
;             PG8_WAIT_L(8); PG8_BAR; PG8_WAIT_L(0); PG8_MMA(0, 0, At, B0); PG8_BAR; PG8_SCHED;
;             PG8_LDB(B1, 0, 1); PG8_STAGE(PG8_SB(0, 0), b2, voffA);
;             PG8_BAR; PG8_WAIT_L(0); PG8_MMA(0, 1, At, B1); PG8_BAR;
;             PG8_LDA(At, 0, 1); PG8_STAGE(PG8_SA(0, 0), a2, voffA);
;             PG8_BAR; PG8_WAIT_L(0); PG8_MMA(1, 0, At, B0); PG8_BAR; PG8_SCHED;
.LBB0_2720:
	s_ashr_i32 s11, s10, 31
	s_lshl_b64 s[30:31], s[10:11], 20
	v_readlane_b32 s3, v255, 1
	s_add_u32 s3, s3, s30
	v_readlane_b32 s11, v255, 2
	v_cmp_lt_i64_e32 vcc, s[44:45], v[184:185]
	s_addc_u32 s11, s11, s31
	s_and_b64 s[30:31], vcc, exec
	s_cselect_b32 s45, s11, s43
	s_cselect_b32 s44, s3, s42
	s_ashr_i32 s3, s2, 31
	s_lshl_b64 s[30:31], s[2:3], 20
	s_add_u32 s3, s6, s30
	s_addc_u32 s11, s7, s31
	s_and_b64 s[30:31], vcc, exec
	s_cselect_b32 s47, s11, s49
	s_cselect_b32 s46, s3, s48
	s_add_u32 s3, s48, 0x100
	s_addc_u32 s11, s49, 0
	s_mov_b32 s57, -2
	s_add_u32 s48, s42, 0x100
	s_addc_u32 s49, s43, 0
	s_add_i32 s30, 0, 0x10000
	v_add_u32_e32 v132, s30, v151
	ds_read_b128 v[128:131], v132
	ds_read_b128 v[142:145], v132 offset:1024
	ds_read_b128 v[146:149], v132 offset:2048
	ds_read_b128 v[158:161], v132 offset:3072
	s_cmp_eq_u32 s57, 28
	s_cselect_b32 s53, s45, s49
	s_cselect_b32 s52, s44, s48
	s_cselect_b32 s51, s47, s11
	s_cselect_b32 s50, s46, s3
	v_lshl_add_u64 v[132:133], s[42:43], 0, v[138:139]
	s_add_i32 m0, s23, 0xc000
	ds_read_b128 v[162:165], v156
	ds_read_b128 v[166:169], v156 offset:1024
	ds_read_b128 v[170:173], v156 offset:2048
	ds_read_b128 v[194:197], v156 offset:3072
	ds_read_b128 v[198:201], v156 offset:4096
	ds_read_b128 v[202:205], v156 offset:5120
	ds_read_b128 v[206:209], v156 offset:6144
	ds_read_b128 v[228:231], v156 offset:7168
	global_load_lds_dwordx4 v[132:133], off
	v_lshl_add_u64 v[132:133], s[42:43], 0, v[140:141]
	s_add_i32 m0, s23, 0xe000
	s_nop 0
	global_load_lds_dwordx4 v[132:133], off
	s_waitcnt lgkmcnt(8)
	s_barrier
	s_waitcnt lgkmcnt(0)
	s_setprio 1
	v_mfma_f32_16x16x32_bf16 v[124:127], v[128:131], v[162:165], 0
	v_mfma_f32_16x16x32_bf16 v[120:123], v[146:149], v[162:165], 0
	v_mfma_f32_16x16x32_bf16 v[108:111], v[128:131], v[170:173], 0
	v_mfma_f32_16x16x32_bf16 v[104:107], v[146:149], v[170:173], 0
	v_mfma_f32_16x16x32_bf16 v[92:95], v[128:131], v[198:201], 0
	v_mfma_f32_16x16x32_bf16 v[88:91], v[146:149], v[198:201], 0
	v_mfma_f32_16x16x32_bf16 v[76:79], v[128:131], v[206:209], 0
	v_mfma_f32_16x16x32_bf16 v[72:75], v[146:149], v[206:209], 0
	v_mfma_f32_16x16x32_bf16 v[124:127], v[142:145], v[166:169], v[124:127]
	v_mfma_f32_16x16x32_bf16 v[120:123], v[158:161], v[166:169], v[120:123]
	v_mfma_f32_16x16x32_bf16 v[108:111], v[142:145], v[194:197], v[108:111]
	v_mfma_f32_16x16x32_bf16 v[104:107], v[158:161], v[194:197], v[104:107]
	v_mfma_f32_16x16x32_bf16 v[92:95], v[142:145], v[202:205], v[92:95]
	v_mfma_f32_16x16x32_bf16 v[88:91], v[158:161], v[202:205], v[88:91]
	v_mfma_f32_16x16x32_bf16 v[76:79], v[142:145], v[228:231], v[76:79]
	v_mfma_f32_16x16x32_bf16 v[72:75], v[158:161], v[228:231], v[72:75]
	s_setprio 0
	s_barrier
	s_add_i32 s42, 0, 0x14000
	v_add_u32_e32 v132, s42, v151
	s_add_i32 s30, s30, s22
	ds_read_b128 v[232:235], v132
	ds_read_b128 v[236:239], v132 offset:1024
	ds_read_b128 v[240:243], v132 offset:2048
	ds_read_b128 v[244:247], v132 offset:3072
	v_lshl_add_u64 v[132:133], s[50:51], 0, v[178:179]
	s_mov_b32 m0, s30
	v_lshl_add_u64 v[174:175], s[50:51], 0, v[134:135]
	global_load_lds_dwordx4 v[132:133], off
	s_add_i32 m0, s30, 0x2000
	s_nop 0
	global_load_lds_dwordx4 v[174:175], off
	s_barrier
	s_waitcnt lgkmcnt(0)
	s_setprio 1
	v_mfma_f32_16x16x32_bf16 v[116:119], v[232:235], v[162:165], 0
	v_mfma_f32_16x16x32_bf16 v[112:115], v[240:243], v[162:165], 0
	v_mfma_f32_16x16x32_bf16 v[100:103], v[232:235], v[170:173], 0
	v_mfma_f32_16x16x32_bf16 v[96:99], v[240:243], v[170:173], 0
	v_mfma_f32_16x16x32_bf16 v[84:87], v[232:235], v[198:201], 0
	v_mfma_f32_16x16x32_bf16 v[80:83], v[240:243], v[198:201], 0
	v_mfma_f32_16x16x32_bf16 v[68:71], v[232:235], v[206:209], 0
	v_mfma_f32_16x16x32_bf16 v[64:67], v[240:243], v[206:209], 0
	v_mfma_f32_16x16x32_bf16 v[116:119], v[236:239], v[166:169], v[116:119]
	v_mfma_f32_16x16x32_bf16 v[112:115], v[244:247], v[166:169], v[112:115]
	v_mfma_f32_16x16x32_bf16 v[100:103], v[236:239], v[194:197], v[100:103]
	v_mfma_f32_16x16x32_bf16 v[96:99], v[244:247], v[194:197], v[96:99]
	v_mfma_f32_16x16x32_bf16 v[84:87], v[236:239], v[202:205], v[84:87]
	v_mfma_f32_16x16x32_bf16 v[80:83], v[244:247], v[202:205], v[80:83]
	v_mfma_f32_16x16x32_bf16 v[68:71], v[236:239], v[228:231], v[68:71]
	v_mfma_f32_16x16x32_bf16 v[64:67], v[244:247], v[228:231], v[64:67]
	s_setprio 0
	s_barrier
	s_mov_b32 m0, s23
	v_lshl_add_u64 v[210:211], s[52:53], 0, v[178:179]
	ds_read_b128 v[162:165], v156 offset:16384
	ds_read_b128 v[166:169], v156 offset:17408
	ds_read_b128 v[170:173], v156 offset:18432
	ds_read_b128 v[194:197], v156 offset:19456
	ds_read_b128 v[198:201], v156 offset:20480
	ds_read_b128 v[202:205], v156 offset:21504
	ds_read_b128 v[206:209], v156 offset:22528
	ds_read_b128 v[228:231], v156 offset:23552
	global_load_lds_dwordx4 v[210:211], off
	v_lshl_add_u64 v[220:221], s[52:53], 0, v[134:135]
	s_mov_b32 m0, s24
	s_nop 0
	global_load_lds_dwordx4 v[220:221], off
	s_barrier
	s_waitcnt lgkmcnt(0)
	s_setprio 1
	v_mfma_f32_16x16x32_bf16 v[60:63], v[128:131], v[162:165], 0
	v_mfma_f32_16x16x32_bf16 v[56:59], v[146:149], v[162:165], 0
	v_mfma_f32_16x16x32_bf16 v[44:47], v[128:131], v[170:173], 0
	v_mfma_f32_16x16x32_bf16 v[40:43], v[146:149], v[170:173], 0
	v_mfma_f32_16x16x32_bf16 v[28:31], v[128:131], v[198:201], 0
	v_mfma_f32_16x16x32_bf16 v[24:27], v[146:149], v[198:201], 0
	v_mfma_f32_16x16x32_bf16 v[12:15], v[128:131], v[206:209], 0
	v_mfma_f32_16x16x32_bf16 v[8:11], v[146:149], v[206:209], 0
	v_mfma_f32_16x16x32_bf16 v[60:63], v[142:145], v[166:169], v[60:63]
	v_mfma_f32_16x16x32_bf16 v[56:59], v[158:161], v[166:169], v[56:59]
	v_mfma_f32_16x16x32_bf16 v[44:47], v[142:145], v[194:197], v[44:47]
	v_mfma_f32_16x16x32_bf16 v[40:43], v[158:161], v[194:197], v[40:43]
	v_mfma_f32_16x16x32_bf16 v[28:31], v[142:145], v[202:205], v[28:31]
	v_mfma_f32_16x16x32_bf16 v[24:27], v[158:161], v[202:205], v[24:27]
	v_mfma_f32_16x16x32_bf16 v[12:15], v[142:145], v[228:231], v[12:15]
	v_mfma_f32_16x16x32_bf16 v[8:11], v[158:161], v[228:231], v[8:11]
	s_setprio 0
	s_barrier
; #define PG8_STAGE(bufoff, gbase, voff) do { _Pragma("unroll") for (int _i = 0; _i < 2; ++_i) \
;         __builtin_amdgcn_global_load_lds((const unsigned*)((const char*)(gbase) + (voff)[_i]), (LAS unsigned*)(lds + (bufoff) + ldsw + _i * 8192), 16, 0, 0); } while (0)
; #define PG8_LDA(dst, b, h) do { _Pragma("unroll") for (int m = 0; m < 4; ++m) _Pragma("unroll") for (int k = 0; k < 2; ++k) dst[m][k] = *(const LAS bf16x8*)(lds + PG8_SA(b, h) + aoff + m * 2048 + k * 1024); } while (0)
; #define PG8_LDB(dst, b, h) do { _Pragma("unroll") for (int n = 0; n < 2; ++n) _Pragma("unroll") for (int k = 0; k < 2; ++k) dst[n][k] = *(const LAS bf16x8*)(lds + PG8_SB(b, h) + boff + n * 2048 + k * 1024); } while (0)
; #define PG8_MMA(ai, bj, At, Bt) do { __builtin_amdgcn_s_setprio(1); _Pragma("unroll") for (int m = 0; m < 4; ++m) _Pragma("unroll") for (int n = 0; n < 2; ++n) _Pragma("unroll") for (int k = 0; k < 2; ++k) \
;         acc[ai][bj][m][n] = __builtin_amdgcn_mfma_f32_16x16x32_bf16(Bt[n][k], At[m][k], acc[ai][bj][m][n], 0, 0, 0); __builtin_amdgcn_s_setprio(0); } while (0)
; #define PG8_WAIT_V(n) asm volatile("s_waitcnt vmcnt(" #n ")" ::: "memory")
; #define PG8_WAIT_L(n) asm volatile("s_waitcnt lgkmcnt(" #n ")" ::: "memory")
; #define PG8_BAR __builtin_amdgcn_s_barrier()
; #define PG8_SCHED __builtin_amdgcn_sched_barrier(0)
; template <class Epi>
; __device__ __forceinline__ void gemm_phase(LAS unsigned char* lds, const Gemm g, const StaticOrder S, const Epi E) {
;     ...
;             PG8_STAGE(PG8_SB(0, 1), b2 + hstep, voffA);
;             PG8_WAIT_V(6); PG8_BAR; PG8_MMA(1, 1, At, B1); PG8_BAR;
;             PG8_LDB(B0, 1, 0); PG8_SCHED; PG8_LDA(At, 1, 0); PG8_STAGE(PG8_SA(0, 1), a2 + hstep, voffA);
;             PG8_WAIT_L(8); PG8_BAR; PG8_WAIT_L(0); PG8_MMA(0, 0, At, B0); PG8_BAR; PG8_SCHED;
;             PG8_LDB(B1, 1, 1); PG8_STAGE(PG8_SB(1, 0), b3, voffA);
;             PG8_BAR; PG8_WAIT_L(0); PG8_MMA(0, 1, At, B1); PG8_BAR;
;             PG8_LDA(At, 1, 1); PG8_STAGE(PG8_SA(1, 0), a3, voffA);
	s_add_u32 s30, s50, 0x80000
	s_addc_u32 s31, s51, 0
	s_add_i32 s42, s42, s22
	v_lshl_add_u64 v[128:129], s[30:31], 0, v[178:179]
	s_mov_b32 m0, s42
	s_nop 0
	global_load_lds_dwordx4 v[128:129], off
	v_lshl_add_u64 v[128:129], s[30:31], 0, v[134:135]
	s_add_i32 m0, s42, 0x2000
	s_nop 0
	global_load_lds_dwordx4 v[128:129], off
	s_waitcnt vmcnt(6)
	s_barrier
	s_setprio 1
	v_mfma_f32_16x16x32_bf16 v[52:55], v[232:235], v[162:165], 0
	v_mfma_f32_16x16x32_bf16 v[48:51], v[240:243], v[162:165], 0
	v_mfma_f32_16x16x32_bf16 v[36:39], v[232:235], v[170:173], 0
	v_mfma_f32_16x16x32_bf16 v[32:35], v[240:243], v[170:173], 0
	v_mfma_f32_16x16x32_bf16 v[20:23], v[232:235], v[198:201], 0
	v_mfma_f32_16x16x32_bf16 v[16:19], v[240:243], v[198:201], 0
	v_mfma_f32_16x16x32_bf16 v[4:7], v[232:235], v[206:209], 0
	v_mfma_f32_16x16x32_bf16 v[0:3], v[240:243], v[206:209], 0
	v_mfma_f32_16x16x32_bf16 v[52:55], v[236:239], v[166:169], v[52:55]
	v_mfma_f32_16x16x32_bf16 v[48:51], v[244:247], v[166:169], v[48:51]
	v_mfma_f32_16x16x32_bf16 v[36:39], v[236:239], v[194:197], v[36:39]
	v_mfma_f32_16x16x32_bf16 v[32:35], v[244:247], v[194:197], v[32:35]
	v_mfma_f32_16x16x32_bf16 v[20:23], v[236:239], v[202:205], v[20:23]
	v_mfma_f32_16x16x32_bf16 v[16:19], v[244:247], v[202:205], v[16:19]
	v_mfma_f32_16x16x32_bf16 v[4:7], v[236:239], v[228:231], v[4:7]
	v_mfma_f32_16x16x32_bf16 v[0:3], v[244:247], v[228:231], v[0:3]
	s_setprio 0
	s_barrier
	s_add_i32 s42, 0, 0x18000
	v_add_u32_e32 v157, s42, v151
	ds_read_b128 v[128:131], v157
	ds_read_b128 v[142:145], v157 offset:1024
	ds_read_b128 v[146:149], v157 offset:2048
	ds_read_b128 v[158:161], v157 offset:3072
	s_add_u32 s30, s52, 0x80000
	s_addc_u32 s31, s53, 0
	s_mov_b32 m0, s25
	v_lshl_add_u64 v[222:223], s[30:31], 0, v[178:179]
	ds_read_b128 v[162:165], v156 offset:32768
	ds_read_b128 v[166:169], v156 offset:33792
	ds_read_b128 v[170:173], v156 offset:34816
	ds_read_b128 v[194:197], v156 offset:35840
	ds_read_b128 v[198:201], v156 offset:36864
	ds_read_b128 v[202:205], v156 offset:37888
	ds_read_b128 v[206:209], v156 offset:38912
	ds_read_b128 v[228:231], v156 offset:39936
	global_load_lds_dwordx4 v[222:223], off
	v_lshl_add_u64 v[222:223], s[30:31], 0, v[134:135]
	s_mov_b32 m0, s26
	s_nop 0
	global_load_lds_dwordx4 v[222:223], off
	s_waitcnt lgkmcnt(8)
	s_barrier
	s_waitcnt lgkmcnt(0)
	s_setprio 1
	v_mfma_f32_16x16x32_bf16 v[124:127], v[128:131], v[162:165], v[124:127]
	v_mfma_f32_16x16x32_bf16 v[120:123], v[146:149], v[162:165], v[120:123]
	v_mfma_f32_16x16x32_bf16 v[108:111], v[128:131], v[170:173], v[108:111]
	v_mfma_f32_16x16x32_bf16 v[104:107], v[146:149], v[170:173], v[104:107]
	v_mfma_f32_16x16x32_bf16 v[92:95], v[128:131], v[198:201], v[92:95]
	v_mfma_f32_16x16x32_bf16 v[88:91], v[146:149], v[198:201], v[88:91]
	v_mfma_f32_16x16x32_bf16 v[76:79], v[128:131], v[206:209], v[76:79]
	v_mfma_f32_16x16x32_bf16 v[72:75], v[146:149], v[206:209], v[72:75]
	v_mfma_f32_16x16x32_bf16 v[124:127], v[142:145], v[166:169], v[124:127]
	v_mfma_f32_16x16x32_bf16 v[120:123], v[158:161], v[166:169], v[120:123]
	v_mfma_f32_16x16x32_bf16 v[108:111], v[142:145], v[194:197], v[108:111]
	v_mfma_f32_16x16x32_bf16 v[104:107], v[158:161], v[194:197], v[104:107]
	v_mfma_f32_16x16x32_bf16 v[92:95], v[142:145], v[202:205], v[92:95]
	v_mfma_f32_16x16x32_bf16 v[88:91], v[158:161], v[202:205], v[88:91]
	v_mfma_f32_16x16x32_bf16 v[76:79], v[142:145], v[228:231], v[76:79]
	v_mfma_f32_16x16x32_bf16 v[72:75], v[158:161], v[228:231], v[72:75]
	s_setprio 0
	s_barrier
	s_add_i32 s43, 0, 0x1c000
	s_add_i32 s30, s42, s22
	v_add_u32_e32 v157, s43, v151
	v_lshl_add_u64 v[132:133], v[132:133], 0, s[34:35]
	s_mov_b32 m0, s30
	ds_read_b128 v[232:235], v157
	ds_read_b128 v[236:239], v157 offset:1024
	ds_read_b128 v[240:243], v157 offset:2048
	ds_read_b128 v[244:247], v157 offset:3072
	global_load_lds_dwordx4 v[132:133], off
	v_lshl_add_u64 v[132:133], v[174:175], 0, s[34:35]
	s_add_i32 m0, s30, 0x2000
	s_nop 0
	global_load_lds_dwordx4 v[132:133], off
	s_barrier
; #define PG8_STAGE(bufoff, gbase, voff) do { _Pragma("unroll") for (int _i = 0; _i < 2; ++_i) \
;         __builtin_amdgcn_global_load_lds((const unsigned*)((const char*)(gbase) + (voff)[_i]), (LAS unsigned*)(lds + (bufoff) + ldsw + _i * 8192), 16, 0, 0); } while (0)
; #define PG8_LDA(dst, b, h) do { _Pragma("unroll") for (int m = 0; m < 4; ++m) _Pragma("unroll") for (int k = 0; k < 2; ++k) dst[m][k] = *(const LAS bf16x8*)(lds + PG8_SA(b, h) + aoff + m * 2048 + k * 1024); } while (0)
; #define PG8_MMA(ai, bj, At, Bt) do { __builtin_amdgcn_s_setprio(1); _Pragma("unroll") for (int m = 0; m < 4; ++m) _Pragma("unroll") for (int n = 0; n < 2; ++n) _Pragma("unroll") for (int k = 0; k < 2; ++k) \
;         acc[ai][bj][m][n] = __builtin_amdgcn_mfma_f32_16x16x32_bf16(Bt[n][k], At[m][k], acc[ai][bj][m][n], 0, 0, 0); __builtin_amdgcn_s_setprio(0); } while (0)
; #define PG8_WAIT_V(n) asm volatile("s_waitcnt vmcnt(" #n ")" ::: "memory")
; #define PG8_WAIT_L(n) asm volatile("s_waitcnt lgkmcnt(" #n ")" ::: "memory")
; #define PG8_BAR __builtin_amdgcn_s_barrier()
; #define PG8_SCHED __builtin_amdgcn_sched_barrier(0)
; template <class Epi>
; __device__ __forceinline__ void gemm_phase(LAS unsigned char* lds, const Gemm g, const StaticOrder S, const Epi E) {
;     ...
;         for (int t = 0; t < nt; t += 2) {
;     ...
;             PG8_LDA(At, 1, 1); PG8_STAGE(PG8_SA(1, 0), a3, voffA);
;             PG8_BAR; PG8_WAIT_L(0); PG8_MMA(1, 0, At, B0); PG8_BAR; PG8_SCHED;
;             PG8_STAGE(PG8_SB(1, 1), b3 + hstep, voffA);
;             PG8_WAIT_V(6); PG8_BAR; PG8_MMA(1, 1, At, B1); PG8_BAR;
;         }
	s_waitcnt lgkmcnt(0)
	s_setprio 1
	v_mfma_f32_16x16x32_bf16 v[116:119], v[232:235], v[162:165], v[116:119]
	v_mfma_f32_16x16x32_bf16 v[112:115], v[240:243], v[162:165], v[112:115]
	v_mfma_f32_16x16x32_bf16 v[100:103], v[232:235], v[170:173], v[100:103]
	v_mfma_f32_16x16x32_bf16 v[96:99], v[240:243], v[170:173], v[96:99]
	v_mfma_f32_16x16x32_bf16 v[84:87], v[232:235], v[198:201], v[84:87]
	v_mfma_f32_16x16x32_bf16 v[80:83], v[240:243], v[198:201], v[80:83]
	v_mfma_f32_16x16x32_bf16 v[68:71], v[232:235], v[206:209], v[68:71]
	v_mfma_f32_16x16x32_bf16 v[64:67], v[240:243], v[206:209], v[64:67]
	v_mfma_f32_16x16x32_bf16 v[116:119], v[236:239], v[166:169], v[116:119]
	v_mfma_f32_16x16x32_bf16 v[112:115], v[244:247], v[166:169], v[112:115]
	v_mfma_f32_16x16x32_bf16 v[100:103], v[236:239], v[194:197], v[100:103]
	v_mfma_f32_16x16x32_bf16 v[96:99], v[244:247], v[194:197], v[96:99]
	v_mfma_f32_16x16x32_bf16 v[84:87], v[236:239], v[202:205], v[84:87]
	v_mfma_f32_16x16x32_bf16 v[80:83], v[244:247], v[202:205], v[80:83]
	v_mfma_f32_16x16x32_bf16 v[68:71], v[236:239], v[228:231], v[68:71]
	v_mfma_f32_16x16x32_bf16 v[64:67], v[244:247], v[228:231], v[64:67]
	s_setprio 0
	s_barrier
	s_mov_b32 m0, s28
	v_lshl_add_u64 v[132:133], v[210:211], 0, s[34:35]
	ds_read_b128 v[162:165], v156 offset:49152
	ds_read_b128 v[166:169], v156 offset:50176
	ds_read_b128 v[170:173], v156 offset:51200
	ds_read_b128 v[194:197], v156 offset:52224
	ds_read_b128 v[198:201], v156 offset:53248
	ds_read_b128 v[202:205], v156 offset:54272
	ds_read_b128 v[206:209], v156 offset:55296
	ds_read_b128 v[228:231], v156 offset:56320
	global_load_lds_dwordx4 v[132:133], off
	v_lshl_add_u64 v[132:133], v[220:221], 0, s[34:35]
	s_mov_b32 m0, s29
	s_nop 0
	global_load_lds_dwordx4 v[132:133], off
	s_barrier
	s_waitcnt lgkmcnt(0)
	s_setprio 1
	v_mfma_f32_16x16x32_bf16 v[60:63], v[128:131], v[162:165], v[60:63]
	v_mfma_f32_16x16x32_bf16 v[56:59], v[146:149], v[162:165], v[56:59]
	v_mfma_f32_16x16x32_bf16 v[44:47], v[128:131], v[170:173], v[44:47]
	v_mfma_f32_16x16x32_bf16 v[40:43], v[146:149], v[170:173], v[40:43]
	v_mfma_f32_16x16x32_bf16 v[28:31], v[128:131], v[198:201], v[28:31]
	v_mfma_f32_16x16x32_bf16 v[24:27], v[146:149], v[198:201], v[24:27]
	v_mfma_f32_16x16x32_bf16 v[12:15], v[128:131], v[206:209], v[12:15]
	v_mfma_f32_16x16x32_bf16 v[8:11], v[146:149], v[206:209], v[8:11]
	v_mfma_f32_16x16x32_bf16 v[60:63], v[142:145], v[166:169], v[60:63]
	v_mfma_f32_16x16x32_bf16 v[56:59], v[158:161], v[166:169], v[56:59]
	v_mfma_f32_16x16x32_bf16 v[44:47], v[142:145], v[194:197], v[44:47]
	v_mfma_f32_16x16x32_bf16 v[40:43], v[158:161], v[194:197], v[40:43]
	v_mfma_f32_16x16x32_bf16 v[28:31], v[142:145], v[202:205], v[28:31]
	v_mfma_f32_16x16x32_bf16 v[24:27], v[158:161], v[202:205], v[24:27]
	v_mfma_f32_16x16x32_bf16 v[12:15], v[142:145], v[228:231], v[12:15]
	v_mfma_f32_16x16x32_bf16 v[8:11], v[158:161], v[228:231], v[8:11]
	s_setprio 0
	s_barrier
	s_add_u32 s30, s50, 0x80080
	s_addc_u32 s31, s51, 0
	s_add_i32 s42, s43, s22
	v_lshl_add_u64 v[128:129], s[30:31], 0, v[178:179]
	s_mov_b32 m0, s42
	s_nop 0
	global_load_lds_dwordx4 v[128:129], off
	v_lshl_add_u64 v[128:129], s[30:31], 0, v[134:135]
	s_add_i32 m0, s42, 0x2000
	s_nop 0
	global_load_lds_dwordx4 v[128:129], off
	s_waitcnt vmcnt(6)
	s_barrier
	s_setprio 1
	v_mfma_f32_16x16x32_bf16 v[52:55], v[232:235], v[162:165], v[52:55]
	v_mfma_f32_16x16x32_bf16 v[48:51], v[240:243], v[162:165], v[48:51]
	v_mfma_f32_16x16x32_bf16 v[36:39], v[232:235], v[170:173], v[36:39]
	v_mfma_f32_16x16x32_bf16 v[32:35], v[240:243], v[170:173], v[32:35]
	v_mfma_f32_16x16x32_bf16 v[20:23], v[232:235], v[198:201], v[20:23]
	v_mfma_f32_16x16x32_bf16 v[16:19], v[240:243], v[198:201], v[16:19]
	v_mfma_f32_16x16x32_bf16 v[4:7], v[232:235], v[206:209], v[4:7]
	v_mfma_f32_16x16x32_bf16 v[0:3], v[240:243], v[206:209], v[0:3]
	v_mfma_f32_16x16x32_bf16 v[52:55], v[236:239], v[166:169], v[52:55]
	v_mfma_f32_16x16x32_bf16 v[48:51], v[244:247], v[166:169], v[48:51]
	v_mfma_f32_16x16x32_bf16 v[36:39], v[236:239], v[194:197], v[36:39]
	v_mfma_f32_16x16x32_bf16 v[32:35], v[244:247], v[194:197], v[32:35]
	v_mfma_f32_16x16x32_bf16 v[20:23], v[236:239], v[202:205], v[20:23]
	v_mfma_f32_16x16x32_bf16 v[16:19], v[244:247], v[202:205], v[16:19]
	v_mfma_f32_16x16x32_bf16 v[4:7], v[236:239], v[228:231], v[4:7]
	v_mfma_f32_16x16x32_bf16 v[0:3], v[244:247], v[228:231], v[0:3]
	s_setprio 0
	s_barrier
	s_add_i32 s57, s57, 2
	s_add_u32 s3, s3, 0x100
	s_addc_u32 s11, s11, 0
	s_cmp_gt_u32 s57, 29
	s_mov_b64 s[42:43], s[48:49]
	s_cbranch_scc0 .LBB0_2721
	s_branch .Lpeel_exit_2

;     __device__ __forceinline__ void operator()(AccRef acc, const pg8::Unit& u, int wr, int wc, int fr, int fq) const {
;         const int row0 = u.pm * 256 + wr * 64 + fr, col0 = u.pn * 256 + wc * 32 + 4 * fq;
;         const bool rope = (u.pn == rope_pn) && (u.pm < 32);
; #pragma unroll
;         for (int ai = 0; ai < 2; ++ai)
; #pragma unroll
;             for (int m = 0; m < 4; ++m) { const int row = row0 + ai * 128 + m * 16; bf16_t* rowp = O + (size_t)row * ldc + col0;
;                 f32x4 cs = {1.f, 1.f, 1.f, 1.f}, sn = {0.f, 0.f, 0.f, 0.f};
;                 if (rope) { const int t = row & 2047; const int pos = (wc & 1) ? (t & 63) : (t >> 6); cs = *(const f32x4*)(cos64 + pos * 16 + 4 * fq); sn = *(const f32x4*)(sin64 + pos * 16 + 4 * fq); }
.Lpeel_exit_2:
	s_lshl_b32 s11, s56, 8
	s_add_i32 s11, s11, s27
	s_cmp_eq_u32 s55, -1
	s_cselect_b64 s[30:31], -1, 0
	s_cmp_lt_i32 s56, 32
	s_cselect_b64 s[42:43], -1, 0
	s_and_b64 s[30:31], s[30:31], s[42:43]
	v_cndmask_b32_e64 v129, 0, 1, s[30:31]
	s_bfe_u32 s3, s11, 0x50006
	v_mov_b32_e32 v144, 1.0
	v_mov_b32_e32 v128, 0
	v_cmp_ne_u32_e64 s[42:43], 1, v129
	s_andn2_b64 vcc, exec, s[30:31]
	v_mov_b32_e32 v130, 0
	v_mov_b32_e32 v131, 0
	v_mov_b32_e32 v132, 0
	v_mov_b32_e32 v133, 0
	v_mov_b32_e32 v146, 1.0
	v_mov_b32_e32 v147, 1.0
	v_mov_b32_e32 v148, 1.0
	v_mov_b32_e32 v149, 1.0
	s_cbranch_vccnz .LBB0_2724
	v_mov_b32_e32 v129, s3
	v_cndmask_b32_e64 v129, v150, v129, s[38:39]
	v_lshl_or_b32 v130, v129, 6, v136
	v_mov_b32_e32 v131, v137
	flat_load_dwordx4 v[130:133], v[130:131]
	s_waitcnt vmcnt(0) lgkmcnt(0)
	v_mov_b32_e32 v146, v130
	v_mov_b32_e32 v147, v131
	v_mov_b32_e32 v148, v132
	v_mov_b32_e32 v149, v133

; #define PG8_STAGE(bufoff, gbase, voff) do { _Pragma("unroll") for (int _i = 0; _i < 2; ++_i) \
;         __builtin_amdgcn_global_load_lds((const unsigned*)((const char*)(gbase) + (voff)[_i]), (LAS unsigned*)(lds + (bufoff) + ldsw + _i * 8192), 16, 0, 0); } while (0)
; #define PG8_LDA(dst, b, h) do { _Pragma("unroll") for (int m = 0; m < 4; ++m) _Pragma("unroll") for (int k = 0; k < 2; ++k) dst[m][k] = *(const LAS bf16x8*)(lds + PG8_SA(b, h) + aoff + m * 2048 + k * 1024); } while (0)
; #define PG8_LDB(dst, b, h) do { _Pragma("unroll") for (int n = 0; n < 2; ++n) _Pragma("unroll") for (int k = 0; k < 2; ++k) dst[n][k] = *(const LAS bf16x8*)(lds + PG8_SB(b, h) + boff + n * 2048 + k * 1024); } while (0)
; #define PG8_MMA(ai, bj, At, Bt) do { __builtin_amdgcn_s_setprio(1); _Pragma("unroll") for (int m = 0; m < 4; ++m) _Pragma("unroll") for (int n = 0; n < 2; ++n) _Pragma("unroll") for (int k = 0; k < 2; ++k) \
;         acc[ai][bj][m][n] = __builtin_amdgcn_mfma_f32_16x16x32_bf16(Bt[n][k], At[m][k], acc[ai][bj][m][n], 0, 0, 0); __builtin_amdgcn_s_setprio(0); } while (0)
; template <class Epi>
; __device__ __forceinline__ void gemm_phase(LAS unsigned char* lds, const Gemm g, const StaticOrder S, const Epi E) {
;     ...
;         const bool has_next = S.next(ui + 1, nxt);
;         const char* nA = has_next ? (const char*)g.A + (size_t)nxt.pm * tstep + (size_t)nxt.k0 * kstep : cA; const char* nB = has_next ? (const char*)g.Bt + (size_t)nxt.pn * tstep + (size_t)nxt.k0 * kstep : cB;
;         const int nt = cur.nk;
;         for (int t = 0; t < nt; t += 2) {
;             const bool last = (t == nt - 2);
;             const char* a1 = cA + (size_t)(t + 1) * kstep;
;             const char* a2 = last ? nA : cA + (size_t)(t + 2) * kstep; const char* b2 = last ? nB : cB + (size_t)(t + 2) * kstep;
;             const char* a3 = a2 + kstep; const char* b3 = b2 + kstep;
;             PG8_LDB(B0, 0, 0); PG8_SCHED; PG8_LDA(At, 0, 0); PG8_STAGE(PG8_SA(1, 1), a1 + hstep, voffA);
;             PG8_WAIT_L(8); PG8_BAR; PG8_WAIT_L(0); PG8_MMA(0, 0, At, B0); PG8_BAR; PG8_SCHED;
;             PG8_LDB(B1, 0, 1); PG8_STAGE(PG8_SB(0, 0), b2, voffA);
;             PG8_BAR; PG8_WAIT_L(0); PG8_MMA(0, 1, At, B1); PG8_BAR;
;             PG8_LDA(At, 0, 1); PG8_STAGE(PG8_SA(0, 0), a2, voffA);
;             PG8_BAR; PG8_WAIT_L(0); PG8_MMA(1, 0, At, B0); PG8_BAR; PG8_SCHED;
.LBB0_3277:
	s_ashr_i32 s3, s2, 31
	s_lshl_b64 s[28:29], s[2:3], 18
	v_readlane_b32 s1, v253, 48
	s_add_u32 s1, s1, s28
	v_cmp_lt_i64_e32 vcc, s[46:47], v[188:189]
	s_addc_u32 s3, s14, s29
	s_and_b64 s[28:29], vcc, exec
	s_cselect_b32 s47, s3, s53
	s_cselect_b32 s46, s1, s52
	s_ashr_i32 s1, s0, 31
	s_lshl_b64 s[28:29], s[0:1], 18
	s_add_u32 s1, s6, s28
	s_addc_u32 s3, s7, s29
	s_and_b64 s[28:29], vcc, exec
	s_cselect_b32 s49, s3, s55
	s_cselect_b32 s48, s1, s54
	s_add_u32 s1, s54, 0x100
	s_addc_u32 s3, s55, 0
	s_mov_b32 s27, -2
	s_add_u32 s54, s52, 0x100
	s_addc_u32 s55, s53, 0
	s_add_i32 s28, 0, 0x10000
	v_add_u32_e32 v140, s28, v157
	ds_read_b128 v[128:131], v140
	ds_read_b128 v[132:135], v140 offset:1024
	ds_read_b128 v[136:139], v140 offset:2048
	ds_read_b128 v[164:167], v140 offset:3072
	s_cmp_eq_u32 s27, 4
	s_cselect_b32 s59, s47, s55
	s_cselect_b32 s58, s46, s54
	s_cselect_b32 s57, s49, s3
	s_cselect_b32 s56, s48, s1
	v_lshl_add_u64 v[140:141], s[52:53], 0, v[150:151]
	s_add_i32 m0, s23, 0xc000
	ds_read_b128 v[168:171], v162
	ds_read_b128 v[172:175], v162 offset:1024
	ds_read_b128 v[194:197], v162 offset:2048
	ds_read_b128 v[198:201], v162 offset:3072
	ds_read_b128 v[202:205], v162 offset:4096
	ds_read_b128 v[206:209], v162 offset:5120
	ds_read_b128 v[228:231], v162 offset:6144
	ds_read_b128 v[232:235], v162 offset:7168
	global_load_lds_dwordx4 v[140:141], off
	v_lshl_add_u64 v[140:141], s[52:53], 0, v[152:153]
	s_add_i32 m0, s23, 0xe000
	s_nop 0
	global_load_lds_dwordx4 v[140:141], off
	s_waitcnt lgkmcnt(8)
	s_barrier
	s_waitcnt lgkmcnt(0)
	s_setprio 1
	v_mfma_f32_16x16x32_bf16 v[124:127], v[128:131], v[168:171], 0
	v_mfma_f32_16x16x32_bf16 v[120:123], v[136:139], v[168:171], 0
	v_mfma_f32_16x16x32_bf16 v[108:111], v[128:131], v[194:197], 0
	v_mfma_f32_16x16x32_bf16 v[104:107], v[136:139], v[194:197], 0
	v_mfma_f32_16x16x32_bf16 v[92:95], v[128:131], v[202:205], 0
	v_mfma_f32_16x16x32_bf16 v[88:91], v[136:139], v[202:205], 0
	v_mfma_f32_16x16x32_bf16 v[76:79], v[128:131], v[228:231], 0
	v_mfma_f32_16x16x32_bf16 v[72:75], v[136:139], v[228:231], 0
	v_mfma_f32_16x16x32_bf16 v[124:127], v[132:135], v[172:175], v[124:127]
	v_mfma_f32_16x16x32_bf16 v[120:123], v[164:167], v[172:175], v[120:123]
	v_mfma_f32_16x16x32_bf16 v[108:111], v[132:135], v[198:201], v[108:111]
	v_mfma_f32_16x16x32_bf16 v[104:107], v[164:167], v[198:201], v[104:107]
	v_mfma_f32_16x16x32_bf16 v[92:95], v[132:135], v[206:209], v[92:95]
	v_mfma_f32_16x16x32_bf16 v[88:91], v[164:167], v[206:209], v[88:91]
	v_mfma_f32_16x16x32_bf16 v[76:79], v[132:135], v[232:235], v[76:79]
	v_mfma_f32_16x16x32_bf16 v[72:75], v[164:167], v[232:235], v[72:75]
	s_setprio 0
	s_barrier
	s_add_i32 s30, 0, 0x14000
	v_add_u32_e32 v140, s30, v157
	s_add_i32 s28, s28, s22
	ds_read_b128 v[236:239], v140
	ds_read_b128 v[240:243], v140 offset:1024
	ds_read_b128 v[244:247], v140 offset:2048
	ds_read_b128 v[220:223], v140 offset:3072
	v_lshl_add_u64 v[140:141], s[56:57], 0, v[142:143]
	s_mov_b32 m0, s28
	v_lshl_add_u64 v[154:155], s[56:57], 0, v[144:145]
	global_load_lds_dwordx4 v[140:141], off
	s_add_i32 m0, s28, 0x2000
	s_nop 0
	global_load_lds_dwordx4 v[154:155], off
	s_barrier
	s_waitcnt lgkmcnt(0)
	s_setprio 1
	v_mfma_f32_16x16x32_bf16 v[116:119], v[236:239], v[168:171], 0
	v_mfma_f32_16x16x32_bf16 v[112:115], v[244:247], v[168:171], 0
	v_mfma_f32_16x16x32_bf16 v[100:103], v[236:239], v[194:197], 0
	v_mfma_f32_16x16x32_bf16 v[96:99], v[244:247], v[194:197], 0
	v_mfma_f32_16x16x32_bf16 v[84:87], v[236:239], v[202:205], 0
	v_mfma_f32_16x16x32_bf16 v[80:83], v[244:247], v[202:205], 0
	v_mfma_f32_16x16x32_bf16 v[68:71], v[236:239], v[228:231], 0
	v_mfma_f32_16x16x32_bf16 v[64:67], v[244:247], v[228:231], 0
	v_mfma_f32_16x16x32_bf16 v[116:119], v[240:243], v[172:175], v[116:119]
	v_mfma_f32_16x16x32_bf16 v[112:115], v[220:223], v[172:175], v[112:115]
	v_mfma_f32_16x16x32_bf16 v[100:103], v[240:243], v[198:201], v[100:103]
	v_mfma_f32_16x16x32_bf16 v[96:99], v[220:223], v[198:201], v[96:99]
	v_mfma_f32_16x16x32_bf16 v[84:87], v[240:243], v[206:209], v[84:87]
	v_mfma_f32_16x16x32_bf16 v[80:83], v[220:223], v[206:209], v[80:83]
	v_mfma_f32_16x16x32_bf16 v[68:71], v[240:243], v[232:235], v[68:71]
	v_mfma_f32_16x16x32_bf16 v[64:67], v[220:223], v[232:235], v[64:67]
	s_setprio 0
	s_barrier
	s_mov_b32 m0, s23
	v_lshl_add_u64 v[210:211], s[58:59], 0, v[142:143]
	ds_read_b128 v[168:171], v162 offset:16384
	ds_read_b128 v[172:175], v162 offset:17408
	ds_read_b128 v[194:197], v162 offset:18432
	ds_read_b128 v[198:201], v162 offset:19456
	ds_read_b128 v[202:205], v162 offset:20480
	ds_read_b128 v[206:209], v162 offset:21504
	ds_read_b128 v[228:231], v162 offset:22528
	ds_read_b128 v[232:235], v162 offset:23552
	global_load_lds_dwordx4 v[210:211], off
	v_lshl_add_u64 v[248:249], s[58:59], 0, v[144:145]
	s_mov_b32 m0, s24
	s_nop 0
	global_load_lds_dwordx4 v[248:249], off
	s_barrier
	s_waitcnt lgkmcnt(0)
	s_setprio 1
	v_mfma_f32_16x16x32_bf16 v[60:63], v[128:131], v[168:171], 0
	v_mfma_f32_16x16x32_bf16 v[56:59], v[136:139], v[168:171], 0
	v_mfma_f32_16x16x32_bf16 v[44:47], v[128:131], v[194:197], 0
	v_mfma_f32_16x16x32_bf16 v[40:43], v[136:139], v[194:197], 0
	v_mfma_f32_16x16x32_bf16 v[28:31], v[128:131], v[202:205], 0
	v_mfma_f32_16x16x32_bf16 v[24:27], v[136:139], v[202:205], 0
	v_mfma_f32_16x16x32_bf16 v[12:15], v[128:131], v[228:231], 0
	v_mfma_f32_16x16x32_bf16 v[8:11], v[136:139], v[228:231], 0
	v_mfma_f32_16x16x32_bf16 v[60:63], v[132:135], v[172:175], v[60:63]
	v_mfma_f32_16x16x32_bf16 v[56:59], v[164:167], v[172:175], v[56:59]
	v_mfma_f32_16x16x32_bf16 v[44:47], v[132:135], v[198:201], v[44:47]
	v_mfma_f32_16x16x32_bf16 v[40:43], v[164:167], v[198:201], v[40:43]
	v_mfma_f32_16x16x32_bf16 v[28:31], v[132:135], v[206:209], v[28:31]
	v_mfma_f32_16x16x32_bf16 v[24:27], v[164:167], v[206:209], v[24:27]
	v_mfma_f32_16x16x32_bf16 v[12:15], v[132:135], v[232:235], v[12:15]
	v_mfma_f32_16x16x32_bf16 v[8:11], v[164:167], v[232:235], v[8:11]
	s_setprio 0
	s_barrier
; #define PG8_STAGE(bufoff, gbase, voff) do { _Pragma("unroll") for (int _i = 0; _i < 2; ++_i) \
;         __builtin_amdgcn_global_load_lds((const unsigned*)((const char*)(gbase) + (voff)[_i]), (LAS unsigned*)(lds + (bufoff) + ldsw + _i * 8192), 16, 0, 0); } while (0)
; #define PG8_LDA(dst, b, h) do { _Pragma("unroll") for (int m = 0; m < 4; ++m) _Pragma("unroll") for (int k = 0; k < 2; ++k) dst[m][k] = *(const LAS bf16x8*)(lds + PG8_SA(b, h) + aoff + m * 2048 + k * 1024); } while (0)
; #define PG8_LDB(dst, b, h) do { _Pragma("unroll") for (int n = 0; n < 2; ++n) _Pragma("unroll") for (int k = 0; k < 2; ++k) dst[n][k] = *(const LAS bf16x8*)(lds + PG8_SB(b, h) + boff + n * 2048 + k * 1024); } while (0)
; #define PG8_MMA(ai, bj, At, Bt) do { __builtin_amdgcn_s_setprio(1); _Pragma("unroll") for (int m = 0; m < 4; ++m) _Pragma("unroll") for (int n = 0; n < 2; ++n) _Pragma("unroll") for (int k = 0; k < 2; ++k) \
;         acc[ai][bj][m][n] = __builtin_amdgcn_mfma_f32_16x16x32_bf16(Bt[n][k], At[m][k], acc[ai][bj][m][n], 0, 0, 0); __builtin_amdgcn_s_setprio(0); } while (0)
; #define PG8_WAIT_V(n) asm volatile("s_waitcnt vmcnt(" #n ")" ::: "memory")
; #define PG8_WAIT_L(n) asm volatile("s_waitcnt lgkmcnt(" #n ")" ::: "memory")
; #define PG8_BAR __builtin_amdgcn_s_barrier()
; #define PG8_SCHED __builtin_amdgcn_sched_barrier(0)
; template <class Epi>
; __device__ __forceinline__ void gemm_phase(LAS unsigned char* lds, const Gemm g, const StaticOrder S, const Epi E) {
;     ...
;             PG8_STAGE(PG8_SB(0, 1), b2 + hstep, voffA);
;             PG8_WAIT_V(6); PG8_BAR; PG8_MMA(1, 1, At, B1); PG8_BAR;
;             PG8_LDB(B0, 1, 0); PG8_SCHED; PG8_LDA(At, 1, 0); PG8_STAGE(PG8_SA(0, 1), a2 + hstep, voffA);
;             PG8_WAIT_L(8); PG8_BAR; PG8_WAIT_L(0); PG8_MMA(0, 0, At, B0); PG8_BAR; PG8_SCHED;
;             PG8_LDB(B1, 1, 1); PG8_STAGE(PG8_SB(1, 0), b3, voffA);
;             PG8_BAR; PG8_WAIT_L(0); PG8_MMA(0, 1, At, B1); PG8_BAR;
;             PG8_LDA(At, 1, 1); PG8_STAGE(PG8_SA(1, 0), a3, voffA);
	s_add_u32 s28, s56, 0x20000
	s_addc_u32 s29, s57, 0
	s_add_i32 s30, s30, s22
	v_lshl_add_u64 v[128:129], s[28:29], 0, v[142:143]
	s_mov_b32 m0, s30
	s_nop 0
	global_load_lds_dwordx4 v[128:129], off
	v_lshl_add_u64 v[128:129], s[28:29], 0, v[144:145]
	s_add_i32 m0, s30, 0x2000
	s_nop 0
	global_load_lds_dwordx4 v[128:129], off
	s_waitcnt vmcnt(6)
	s_barrier
	s_setprio 1
	v_mfma_f32_16x16x32_bf16 v[52:55], v[236:239], v[168:171], 0
	v_mfma_f32_16x16x32_bf16 v[48:51], v[244:247], v[168:171], 0
	v_mfma_f32_16x16x32_bf16 v[36:39], v[236:239], v[194:197], 0
	v_mfma_f32_16x16x32_bf16 v[32:35], v[244:247], v[194:197], 0
	v_mfma_f32_16x16x32_bf16 v[20:23], v[236:239], v[202:205], 0
	v_mfma_f32_16x16x32_bf16 v[16:19], v[244:247], v[202:205], 0
	v_mfma_f32_16x16x32_bf16 v[4:7], v[236:239], v[228:231], 0
	v_mfma_f32_16x16x32_bf16 v[0:3], v[244:247], v[228:231], 0
	v_mfma_f32_16x16x32_bf16 v[52:55], v[240:243], v[172:175], v[52:55]
	v_mfma_f32_16x16x32_bf16 v[48:51], v[220:223], v[172:175], v[48:51]
	v_mfma_f32_16x16x32_bf16 v[36:39], v[240:243], v[198:201], v[36:39]
	v_mfma_f32_16x16x32_bf16 v[32:35], v[220:223], v[198:201], v[32:35]
	v_mfma_f32_16x16x32_bf16 v[20:23], v[240:243], v[206:209], v[20:23]
	v_mfma_f32_16x16x32_bf16 v[16:19], v[220:223], v[206:209], v[16:19]
	v_mfma_f32_16x16x32_bf16 v[4:7], v[240:243], v[232:235], v[4:7]
	v_mfma_f32_16x16x32_bf16 v[0:3], v[220:223], v[232:235], v[0:3]
	s_setprio 0
	s_barrier
	s_add_i32 s30, 0, 0x18000
	v_add_u32_e32 v163, s30, v157
	ds_read_b128 v[128:131], v163
	ds_read_b128 v[132:135], v163 offset:1024
	ds_read_b128 v[136:139], v163 offset:2048
	ds_read_b128 v[164:167], v163 offset:3072
	s_add_u32 s28, s58, 0x20000
	s_addc_u32 s29, s59, 0
	s_mov_b32 m0, s25
	v_lshl_add_u64 v[232:233], s[28:29], 0, v[142:143]
	ds_read_b128 v[168:171], v162 offset:32768
	ds_read_b128 v[172:175], v162 offset:33792
	ds_read_b128 v[194:197], v162 offset:34816
	ds_read_b128 v[198:201], v162 offset:35840
	ds_read_b128 v[202:205], v162 offset:36864
	ds_read_b128 v[206:209], v162 offset:37888
	ds_read_b128 v[220:223], v162 offset:38912
	ds_read_b128 v[228:231], v162 offset:39936
	global_load_lds_dwordx4 v[232:233], off
	v_lshl_add_u64 v[232:233], s[28:29], 0, v[144:145]
	s_mov_b32 m0, s51
	s_nop 0
	global_load_lds_dwordx4 v[232:233], off
	s_waitcnt lgkmcnt(8)
	s_barrier
	s_waitcnt lgkmcnt(0)
	s_setprio 1
	v_mfma_f32_16x16x32_bf16 v[124:127], v[128:131], v[168:171], v[124:127]
	v_mfma_f32_16x16x32_bf16 v[120:123], v[136:139], v[168:171], v[120:123]
	v_mfma_f32_16x16x32_bf16 v[108:111], v[128:131], v[194:197], v[108:111]
	v_mfma_f32_16x16x32_bf16 v[104:107], v[136:139], v[194:197], v[104:107]
	v_mfma_f32_16x16x32_bf16 v[92:95], v[128:131], v[202:205], v[92:95]
	v_mfma_f32_16x16x32_bf16 v[88:91], v[136:139], v[202:205], v[88:91]
	v_mfma_f32_16x16x32_bf16 v[76:79], v[128:131], v[220:223], v[76:79]
	v_mfma_f32_16x16x32_bf16 v[72:75], v[136:139], v[220:223], v[72:75]
	v_mfma_f32_16x16x32_bf16 v[124:127], v[132:135], v[172:175], v[124:127]
	v_mfma_f32_16x16x32_bf16 v[120:123], v[164:167], v[172:175], v[120:123]
	v_mfma_f32_16x16x32_bf16 v[108:111], v[132:135], v[198:201], v[108:111]
	v_mfma_f32_16x16x32_bf16 v[104:107], v[164:167], v[198:201], v[104:107]
	v_mfma_f32_16x16x32_bf16 v[92:95], v[132:135], v[206:209], v[92:95]
	v_mfma_f32_16x16x32_bf16 v[88:91], v[164:167], v[206:209], v[88:91]
	v_mfma_f32_16x16x32_bf16 v[76:79], v[132:135], v[228:231], v[76:79]
	v_mfma_f32_16x16x32_bf16 v[72:75], v[164:167], v[228:231], v[72:75]
	s_setprio 0
	s_barrier
	s_add_i32 s31, 0, 0x1c000
	s_add_i32 s28, s30, s22
	v_add_u32_e32 v163, s31, v157
	v_lshl_add_u64 v[140:141], v[140:141], 0, s[34:35]
	s_mov_b32 m0, s28
	ds_read_b128 v[232:235], v163
	ds_read_b128 v[236:239], v163 offset:1024
	ds_read_b128 v[240:243], v163 offset:2048
	ds_read_b128 v[244:247], v163 offset:3072
	global_load_lds_dwordx4 v[140:141], off
	v_lshl_add_u64 v[140:141], v[154:155], 0, s[34:35]
	s_add_i32 m0, s28, 0x2000
	s_nop 0
	global_load_lds_dwordx4 v[140:141], off
	s_barrier
; #define PG8_STAGE(bufoff, gbase, voff) do { _Pragma("unroll") for (int _i = 0; _i < 2; ++_i) \
;         __builtin_amdgcn_global_load_lds((const unsigned*)((const char*)(gbase) + (voff)[_i]), (LAS unsigned*)(lds + (bufoff) + ldsw + _i * 8192), 16, 0, 0); } while (0)
; #define PG8_LDA(dst, b, h) do { _Pragma("unroll") for (int m = 0; m < 4; ++m) _Pragma("unroll") for (int k = 0; k < 2; ++k) dst[m][k] = *(const LAS bf16x8*)(lds + PG8_SA(b, h) + aoff + m * 2048 + k * 1024); } while (0)
; #define PG8_MMA(ai, bj, At, Bt) do { __builtin_amdgcn_s_setprio(1); _Pragma("unroll") for (int m = 0; m < 4; ++m) _Pragma("unroll") for (int n = 0; n < 2; ++n) _Pragma("unroll") for (int k = 0; k < 2; ++k) \
;         acc[ai][bj][m][n] = __builtin_amdgcn_mfma_f32_16x16x32_bf16(Bt[n][k], At[m][k], acc[ai][bj][m][n], 0, 0, 0); __builtin_amdgcn_s_setprio(0); } while (0)
; #define PG8_WAIT_V(n) asm volatile("s_waitcnt vmcnt(" #n ")" ::: "memory")
; #define PG8_WAIT_L(n) asm volatile("s_waitcnt lgkmcnt(" #n ")" ::: "memory")
; #define PG8_BAR __builtin_amdgcn_s_barrier()
; #define PG8_SCHED __builtin_amdgcn_sched_barrier(0)
; template <class Epi>
; __device__ __forceinline__ void gemm_phase(LAS unsigned char* lds, const Gemm g, const StaticOrder S, const Epi E) {
;     ...
;         for (int t = 0; t < nt; t += 2) {
;     ...
;             PG8_LDA(At, 1, 1); PG8_STAGE(PG8_SA(1, 0), a3, voffA);
;             PG8_BAR; PG8_WAIT_L(0); PG8_MMA(1, 0, At, B0); PG8_BAR; PG8_SCHED;
;             PG8_STAGE(PG8_SB(1, 1), b3 + hstep, voffA);
;             PG8_WAIT_V(6); PG8_BAR; PG8_MMA(1, 1, At, B1); PG8_BAR;
;         }
	s_waitcnt lgkmcnt(0)
	s_setprio 1
	v_mfma_f32_16x16x32_bf16 v[116:119], v[232:235], v[168:171], v[116:119]
	v_mfma_f32_16x16x32_bf16 v[112:115], v[240:243], v[168:171], v[112:115]
	v_mfma_f32_16x16x32_bf16 v[100:103], v[232:235], v[194:197], v[100:103]
	v_mfma_f32_16x16x32_bf16 v[96:99], v[240:243], v[194:197], v[96:99]
	v_mfma_f32_16x16x32_bf16 v[84:87], v[232:235], v[202:205], v[84:87]
	v_mfma_f32_16x16x32_bf16 v[80:83], v[240:243], v[202:205], v[80:83]
	v_mfma_f32_16x16x32_bf16 v[68:71], v[232:235], v[220:223], v[68:71]
	v_mfma_f32_16x16x32_bf16 v[64:67], v[240:243], v[220:223], v[64:67]
	v_mfma_f32_16x16x32_bf16 v[116:119], v[236:239], v[172:175], v[116:119]
	v_mfma_f32_16x16x32_bf16 v[112:115], v[244:247], v[172:175], v[112:115]
	v_mfma_f32_16x16x32_bf16 v[100:103], v[236:239], v[198:201], v[100:103]
	v_mfma_f32_16x16x32_bf16 v[96:99], v[244:247], v[198:201], v[96:99]
	v_mfma_f32_16x16x32_bf16 v[84:87], v[236:239], v[206:209], v[84:87]
	v_mfma_f32_16x16x32_bf16 v[80:83], v[244:247], v[206:209], v[80:83]
	v_mfma_f32_16x16x32_bf16 v[68:71], v[236:239], v[228:231], v[68:71]
	v_mfma_f32_16x16x32_bf16 v[64:67], v[244:247], v[228:231], v[64:67]
	s_setprio 0
	s_barrier
	s_mov_b32 m0, s61
	v_lshl_add_u64 v[140:141], v[210:211], 0, s[34:35]
	ds_read_b128 v[168:171], v162 offset:49152
	ds_read_b128 v[172:175], v162 offset:50176
	ds_read_b128 v[194:197], v162 offset:51200
	ds_read_b128 v[198:201], v162 offset:52224
	ds_read_b128 v[202:205], v162 offset:53248
	ds_read_b128 v[206:209], v162 offset:54272
	ds_read_b128 v[220:223], v162 offset:55296
	ds_read_b128 v[228:231], v162 offset:56320
	global_load_lds_dwordx4 v[140:141], off
	v_lshl_add_u64 v[140:141], v[248:249], 0, s[34:35]
	s_mov_b32 m0, s62
	s_nop 0
	global_load_lds_dwordx4 v[140:141], off
	s_barrier
	s_waitcnt lgkmcnt(0)
	s_setprio 1
	v_mfma_f32_16x16x32_bf16 v[60:63], v[128:131], v[168:171], v[60:63]
	v_mfma_f32_16x16x32_bf16 v[56:59], v[136:139], v[168:171], v[56:59]
	v_mfma_f32_16x16x32_bf16 v[44:47], v[128:131], v[194:197], v[44:47]
	v_mfma_f32_16x16x32_bf16 v[40:43], v[136:139], v[194:197], v[40:43]
	v_mfma_f32_16x16x32_bf16 v[28:31], v[128:131], v[202:205], v[28:31]
	v_mfma_f32_16x16x32_bf16 v[24:27], v[136:139], v[202:205], v[24:27]
	v_mfma_f32_16x16x32_bf16 v[12:15], v[128:131], v[220:223], v[12:15]
	v_mfma_f32_16x16x32_bf16 v[8:11], v[136:139], v[220:223], v[8:11]
	v_mfma_f32_16x16x32_bf16 v[60:63], v[132:135], v[172:175], v[60:63]
	v_mfma_f32_16x16x32_bf16 v[56:59], v[164:167], v[172:175], v[56:59]
	v_mfma_f32_16x16x32_bf16 v[44:47], v[132:135], v[198:201], v[44:47]
	v_mfma_f32_16x16x32_bf16 v[40:43], v[164:167], v[198:201], v[40:43]
	v_mfma_f32_16x16x32_bf16 v[28:31], v[132:135], v[206:209], v[28:31]
	v_mfma_f32_16x16x32_bf16 v[24:27], v[164:167], v[206:209], v[24:27]
	v_mfma_f32_16x16x32_bf16 v[12:15], v[132:135], v[228:231], v[12:15]
	v_mfma_f32_16x16x32_bf16 v[8:11], v[164:167], v[228:231], v[8:11]
	s_setprio 0
	s_barrier
	s_add_u32 s28, s56, 0x20080
	s_addc_u32 s29, s57, 0
	s_add_i32 s30, s31, s22
	v_lshl_add_u64 v[128:129], s[28:29], 0, v[142:143]
	s_mov_b32 m0, s30
	s_nop 0
	global_load_lds_dwordx4 v[128:129], off
	v_lshl_add_u64 v[128:129], s[28:29], 0, v[144:145]
	s_add_i32 m0, s30, 0x2000
	s_nop 0
	global_load_lds_dwordx4 v[128:129], off
	s_waitcnt vmcnt(6)
	s_barrier
	s_setprio 1
	v_mfma_f32_16x16x32_bf16 v[52:55], v[232:235], v[168:171], v[52:55]
	v_mfma_f32_16x16x32_bf16 v[48:51], v[240:243], v[168:171], v[48:51]
	v_mfma_f32_16x16x32_bf16 v[36:39], v[232:235], v[194:197], v[36:39]
	v_mfma_f32_16x16x32_bf16 v[32:35], v[240:243], v[194:197], v[32:35]
	v_mfma_f32_16x16x32_bf16 v[20:23], v[232:235], v[202:205], v[20:23]
	v_mfma_f32_16x16x32_bf16 v[16:19], v[240:243], v[202:205], v[16:19]
	v_mfma_f32_16x16x32_bf16 v[4:7], v[232:235], v[220:223], v[4:7]
	v_mfma_f32_16x16x32_bf16 v[0:3], v[240:243], v[220:223], v[0:3]
	v_mfma_f32_16x16x32_bf16 v[52:55], v[236:239], v[172:175], v[52:55]
	v_mfma_f32_16x16x32_bf16 v[48:51], v[244:247], v[172:175], v[48:51]
	v_mfma_f32_16x16x32_bf16 v[36:39], v[236:239], v[198:201], v[36:39]
	v_mfma_f32_16x16x32_bf16 v[32:35], v[244:247], v[198:201], v[32:35]
	v_mfma_f32_16x16x32_bf16 v[20:23], v[236:239], v[206:209], v[20:23]
	v_mfma_f32_16x16x32_bf16 v[16:19], v[244:247], v[206:209], v[16:19]
	v_mfma_f32_16x16x32_bf16 v[4:7], v[236:239], v[228:231], v[4:7]
	v_mfma_f32_16x16x32_bf16 v[0:3], v[244:247], v[228:231], v[0:3]
	s_setprio 0
	s_barrier
	s_add_i32 s27, s27, 2
	s_add_u32 s1, s1, 0x100
	s_addc_u32 s3, s3, 0
	s_cmp_gt_u32 s27, 5
	s_mov_b64 s[52:53], s[54:55]
	s_cbranch_scc0 .LBB0_3278
	s_branch .Lpeel_exit_3

;     __device__ __forceinline__ void operator()(AccRef acc, const pg8::Unit& u, int wr, int wc, int fr, int fq) const {
;         const int row0 = u.pm * 256 + wr * 64 + fr, col0 = u.pn * 256 + wc * 32 + 4 * fq;
;         const bool rope = (u.pn == rope_pn) && (u.pm < 32);
; #pragma unroll
;         for (int ai = 0; ai < 2; ++ai)
; #pragma unroll
;             for (int m = 0; m < 4; ++m) { const int row = row0 + ai * 128 + m * 16; bf16_t* rowp = O + (size_t)row * ldc + col0;
;                 f32x4 cs = {1.f, 1.f, 1.f, 1.f}, sn = {0.f, 0.f, 0.f, 0.f};
;                 if (rope) { const int t = row & 2047; const int pos = (wc & 1) ? (t & 63) : (t >> 6); cs = *(const f32x4*)(cos64 + pos * 16 + 4 * fq); sn = *(const f32x4*)(sin64 + pos * 16 + 4 * fq); }
.Lpeel_exit_3:
	s_lshl_b32 s3, s42, 8
	s_add_i32 s3, s3, s60
	s_cmp_eq_u32 s50, 2
	s_cselect_b64 s[28:29], -1, 0
	s_cmp_lt_i32 s42, 32
	s_cselect_b64 s[30:31], -1, 0
	s_and_b64 s[28:29], s[28:29], s[30:31]
	v_cndmask_b32_e64 v129, 0, 1, s[28:29]
	s_bfe_u32 s1, s3, 0x50006
	v_mov_b32_e32 v128, 1.0
	v_mov_b32_e32 v132, 0
	v_cmp_ne_u32_e64 s[42:43], 1, v129
	s_andn2_b64 vcc, exec, s[28:29]
	v_mov_b32_e32 v134, 0
	v_mov_b32_e32 v135, 0
	v_mov_b32_e32 v136, 0
	v_mov_b32_e32 v137, 0
	v_mov_b32_e32 v138, 1.0
	v_mov_b32_e32 v139, 1.0
	v_mov_b32_e32 v140, 1.0
	v_mov_b32_e32 v141, 1.0
	s_cbranch_vccnz .LBB0_3281
	v_mov_b32_e32 v129, s1
	v_cndmask_b32_e64 v129, v156, v129, s[38:39]
	v_lshlrev_b32_e32 v178, 6, v129
	v_lshl_add_u64 v[130:131], v[148:149], 0, v[178:179]
	v_lshl_add_u64 v[134:135], v[146:147], 0, v[178:179]
	global_load_dwordx4 v[138:141], v[130:131], off
	s_nop 0
	global_load_dwordx4 v[134:137], v[134:135], off

; #define PG8_STAGE(bufoff, gbase, voff) do { _Pragma("unroll") for (int _i = 0; _i < 2; ++_i) \
;         __builtin_amdgcn_global_load_lds((const unsigned*)((const char*)(gbase) + (voff)[_i]), (LAS unsigned*)(lds + (bufoff) + ldsw + _i * 8192), 16, 0, 0); } while (0)
; #define PG8_LDA(dst, b, h) do { _Pragma("unroll") for (int m = 0; m < 4; ++m) _Pragma("unroll") for (int k = 0; k < 2; ++k) dst[m][k] = *(const LAS bf16x8*)(lds + PG8_SA(b, h) + aoff + m * 2048 + k * 1024); } while (0)
; #define PG8_LDB(dst, b, h) do { _Pragma("unroll") for (int n = 0; n < 2; ++n) _Pragma("unroll") for (int k = 0; k < 2; ++k) dst[n][k] = *(const LAS bf16x8*)(lds + PG8_SB(b, h) + boff + n * 2048 + k * 1024); } while (0)
; #define PG8_MMA(ai, bj, At, Bt) do { __builtin_amdgcn_s_setprio(1); _Pragma("unroll") for (int m = 0; m < 4; ++m) _Pragma("unroll") for (int n = 0; n < 2; ++n) _Pragma("unroll") for (int k = 0; k < 2; ++k) \
;         acc[ai][bj][m][n] = __builtin_amdgcn_mfma_f32_16x16x32_bf16(Bt[n][k], At[m][k], acc[ai][bj][m][n], 0, 0, 0); __builtin_amdgcn_s_setprio(0); } while (0)
; template <class Epi>
; __device__ __forceinline__ void gemm_phase(LAS unsigned char* lds, const Gemm g, const StaticOrder S, const Epi E) {
;     ...
;         const bool has_next = S.next(ui + 1, nxt);
;         const char* nA = has_next ? (const char*)g.A + (size_t)nxt.pm * tstep + (size_t)nxt.k0 * kstep : cA; const char* nB = has_next ? (const char*)g.Bt + (size_t)nxt.pn * tstep + (size_t)nxt.k0 * kstep : cB;
;         const int nt = cur.nk;
;         for (int t = 0; t < nt; t += 2) {
;             const bool last = (t == nt - 2);
;             const char* a1 = cA + (size_t)(t + 1) * kstep;
;             const char* a2 = last ? nA : cA + (size_t)(t + 2) * kstep; const char* b2 = last ? nB : cB + (size_t)(t + 2) * kstep;
;             const char* a3 = a2 + kstep; const char* b3 = b2 + kstep;
;             PG8_LDB(B0, 0, 0); PG8_SCHED; PG8_LDA(At, 0, 0); PG8_STAGE(PG8_SA(1, 1), a1 + hstep, voffA);
;             PG8_WAIT_L(8); PG8_BAR; PG8_WAIT_L(0); PG8_MMA(0, 0, At, B0); PG8_BAR; PG8_SCHED;
;             PG8_LDB(B1, 0, 1); PG8_STAGE(PG8_SB(0, 0), b2, voffA);
;             PG8_BAR; PG8_WAIT_L(0); PG8_MMA(0, 1, At, B1); PG8_BAR;
;             PG8_LDA(At, 0, 1); PG8_STAGE(PG8_SA(0, 0), a2, voffA);
;             PG8_BAR; PG8_WAIT_L(0); PG8_MMA(1, 0, At, B0); PG8_BAR; PG8_SCHED;
.LBB0_3305:
	s_ashr_i32 s3, s2, 31
	s_lshl_b64 s[30:31], s[2:3], 17
	v_readlane_b32 s1, v255, 16
	s_add_u32 s1, s1, s30
	v_readlane_b32 s3, v255, 17
	v_cmp_lt_i64_e32 vcc, s[46:47], v[192:193]
	s_addc_u32 s3, s3, s31
	s_and_b64 s[30:31], vcc, exec
	s_cselect_b32 s47, s3, s51
	s_cselect_b32 s46, s1, s50
	s_ashr_i32 s1, s0, 31
	s_lshl_b64 s[30:31], s[0:1], 17
	s_add_u32 s1, s6, s30
	s_addc_u32 s3, s7, s31
	s_and_b64 s[30:31], vcc, exec
	s_cselect_b32 s49, s3, s43
	s_cselect_b32 s48, s1, s42
	s_mov_b32 s1, 0
	s_mov_b64 s[52:53], -1
	s_mov_b64 s[54:55], 0
	s_add_u32 s3, s50, s1
	s_addc_u32 s29, s51, 0
	s_add_u32 s44, s3, 0x100
	s_addc_u32 s45, s29, 0
	s_and_b64 s[30:31], s[54:55], exec
	s_cselect_b32 s61, s47, s45
	s_cselect_b32 s60, s46, s44
	s_add_u32 s1, s42, s1
	s_addc_u32 s30, s43, 0
	s_add_u32 s1, s1, 0x100
	s_addc_u32 s44, s30, 0
	s_add_i32 s45, 0, 0x10000
	s_and_b64 s[30:31], s[54:55], exec
	s_cselect_b32 s63, s49, s44
	s_cselect_b32 s62, s48, s1
	s_add_u32 s64, s3, 0x10080
	s_addc_u32 s65, s29, 0
	s_add_i32 s73, s45, s22
	s_add_i32 m0, s14, 0xc000
	s_add_i32 s23, s14, 0xe000
	s_add_i32 vcc_hi, 0, 0x14000
	s_add_i32 s31, s73, 0x2000
	s_add_u32 s58, s62, 0x10000
	v_add_u32_e32 v140, s45, v155
	s_addc_u32 s59, s63, 0
	s_add_i32 s44, vcc_hi, s22
	ds_read_b128 v[128:131], v140
	ds_read_b128 v[132:135], v140 offset:1024
	ds_read_b128 v[136:139], v140 offset:2048
	ds_read_b128 v[150:153], v140 offset:3072
	s_add_i32 s72, s44, 0x2000
	s_add_i32 vcc_lo, 0, 0x18000
	s_add_u32 s56, s60, 0x10000
	s_addc_u32 s57, s61, 0
	s_add_i32 s29, vcc_lo, s22
	s_add_i32 s3, 0, 0x1c000
	s_add_i32 s1, s29, 0x2000
	s_add_u32 s54, s62, 0x10080
	s_addc_u32 s55, s63, 0
	s_add_i32 s45, s3, s22
	s_add_i32 s30, s45, 0x2000
	v_lshl_add_u64 v[140:141], s[64:65], 0, v[144:145]
	ds_read_b128 v[162:165], v160
	ds_read_b128 v[166:169], v160 offset:1024
	ds_read_b128 v[170:173], v160 offset:2048
	ds_read_b128 v[194:197], v160 offset:3072
	ds_read_b128 v[198:201], v160 offset:4096
	ds_read_b128 v[202:205], v160 offset:5120
	ds_read_b128 v[206:209], v160 offset:6144
	ds_read_b128 v[220:223], v160 offset:7168
	global_load_lds_dwordx4 v[140:141], off
	v_lshl_add_u64 v[140:141], s[64:65], 0, v[142:143]
	s_mov_b32 m0, s23
	s_nop 0
	global_load_lds_dwordx4 v[140:141], off
	s_waitcnt lgkmcnt(8)
	s_barrier
	s_waitcnt lgkmcnt(0)
	s_setprio 1
	v_mfma_f32_16x16x32_bf16 v[124:127], v[128:131], v[162:165], 0
	v_mfma_f32_16x16x32_bf16 v[120:123], v[136:139], v[162:165], 0
	v_mfma_f32_16x16x32_bf16 v[108:111], v[128:131], v[170:173], 0
	v_mfma_f32_16x16x32_bf16 v[104:107], v[136:139], v[170:173], 0
	v_mfma_f32_16x16x32_bf16 v[92:95], v[128:131], v[198:201], 0
	v_mfma_f32_16x16x32_bf16 v[88:91], v[136:139], v[198:201], 0
	v_mfma_f32_16x16x32_bf16 v[76:79], v[128:131], v[206:209], 0
	v_mfma_f32_16x16x32_bf16 v[72:75], v[136:139], v[206:209], 0
	v_mfma_f32_16x16x32_bf16 v[124:127], v[132:135], v[166:169], v[124:127]
	v_mfma_f32_16x16x32_bf16 v[120:123], v[150:153], v[166:169], v[120:123]
	v_mfma_f32_16x16x32_bf16 v[108:111], v[132:135], v[194:197], v[108:111]
	v_mfma_f32_16x16x32_bf16 v[104:107], v[150:153], v[194:197], v[104:107]
	v_mfma_f32_16x16x32_bf16 v[92:95], v[132:135], v[202:205], v[92:95]
	v_mfma_f32_16x16x32_bf16 v[88:91], v[150:153], v[202:205], v[88:91]
	v_mfma_f32_16x16x32_bf16 v[76:79], v[132:135], v[220:223], v[76:79]
	v_mfma_f32_16x16x32_bf16 v[72:75], v[150:153], v[220:223], v[72:75]
	s_setprio 0
	s_barrier
	v_add_u32_e32 v140, vcc_hi, v155
	s_mov_b32 m0, s73
	ds_read_b128 v[228:231], v140
	ds_read_b128 v[232:235], v140 offset:1024
	ds_read_b128 v[236:239], v140 offset:2048
	ds_read_b128 v[240:243], v140 offset:3072
	v_lshl_add_u64 v[140:141], s[62:63], 0, v[144:145]
	global_load_lds_dwordx4 v[140:141], off
	v_lshl_add_u64 v[174:175], s[62:63], 0, v[142:143]
	s_mov_b32 m0, s31
	s_nop 0
	global_load_lds_dwordx4 v[174:175], off
	s_barrier
	s_waitcnt lgkmcnt(0)
	s_setprio 1
	v_mfma_f32_16x16x32_bf16 v[116:119], v[228:231], v[162:165], 0
	v_mfma_f32_16x16x32_bf16 v[112:115], v[236:239], v[162:165], 0
	v_mfma_f32_16x16x32_bf16 v[100:103], v[228:231], v[170:173], 0
	v_mfma_f32_16x16x32_bf16 v[96:99], v[236:239], v[170:173], 0
	v_mfma_f32_16x16x32_bf16 v[84:87], v[228:231], v[198:201], 0
	v_mfma_f32_16x16x32_bf16 v[80:83], v[236:239], v[198:201], 0
	v_mfma_f32_16x16x32_bf16 v[68:71], v[228:231], v[206:209], 0
	v_mfma_f32_16x16x32_bf16 v[64:67], v[236:239], v[206:209], 0
	v_mfma_f32_16x16x32_bf16 v[116:119], v[232:235], v[166:169], v[116:119]
	v_mfma_f32_16x16x32_bf16 v[112:115], v[240:243], v[166:169], v[112:115]
	v_mfma_f32_16x16x32_bf16 v[100:103], v[232:235], v[194:197], v[100:103]
	v_mfma_f32_16x16x32_bf16 v[96:99], v[240:243], v[194:197], v[96:99]
	v_mfma_f32_16x16x32_bf16 v[84:87], v[232:235], v[202:205], v[84:87]
	v_mfma_f32_16x16x32_bf16 v[80:83], v[240:243], v[202:205], v[80:83]
	v_mfma_f32_16x16x32_bf16 v[68:71], v[232:235], v[220:223], v[68:71]
	v_mfma_f32_16x16x32_bf16 v[64:67], v[240:243], v[220:223], v[64:67]
	s_setprio 0
	s_barrier
	s_mov_b32 m0, s14
	v_lshl_add_u64 v[210:211], s[60:61], 0, v[144:145]
	ds_read_b128 v[162:165], v160 offset:16384
	ds_read_b128 v[166:169], v160 offset:17408
	ds_read_b128 v[170:173], v160 offset:18432
	ds_read_b128 v[194:197], v160 offset:19456
	ds_read_b128 v[198:201], v160 offset:20480
	ds_read_b128 v[202:205], v160 offset:21504
	ds_read_b128 v[206:209], v160 offset:22528
	ds_read_b128 v[220:223], v160 offset:23552
	global_load_lds_dwordx4 v[210:211], off
	v_lshl_add_u64 v[244:245], s[60:61], 0, v[142:143]
	s_mov_b32 m0, s24
	s_nop 0
	global_load_lds_dwordx4 v[244:245], off
	s_barrier
; #define PG8_STAGE(bufoff, gbase, voff) do { _Pragma("unroll") for (int _i = 0; _i < 2; ++_i) \
;         __builtin_amdgcn_global_load_lds((const unsigned*)((const char*)(gbase) + (voff)[_i]), (LAS unsigned*)(lds + (bufoff) + ldsw + _i * 8192), 16, 0, 0); } while (0)
; #define PG8_LDA(dst, b, h) do { _Pragma("unroll") for (int m = 0; m < 4; ++m) _Pragma("unroll") for (int k = 0; k < 2; ++k) dst[m][k] = *(const LAS bf16x8*)(lds + PG8_SA(b, h) + aoff + m * 2048 + k * 1024); } while (0)
; #define PG8_LDB(dst, b, h) do { _Pragma("unroll") for (int n = 0; n < 2; ++n) _Pragma("unroll") for (int k = 0; k < 2; ++k) dst[n][k] = *(const LAS bf16x8*)(lds + PG8_SB(b, h) + boff + n * 2048 + k * 1024); } while (0)
; #define PG8_MMA(ai, bj, At, Bt) do { __builtin_amdgcn_s_setprio(1); _Pragma("unroll") for (int m = 0; m < 4; ++m) _Pragma("unroll") for (int n = 0; n < 2; ++n) _Pragma("unroll") for (int k = 0; k < 2; ++k) \
;         acc[ai][bj][m][n] = __builtin_amdgcn_mfma_f32_16x16x32_bf16(Bt[n][k], At[m][k], acc[ai][bj][m][n], 0, 0, 0); __builtin_amdgcn_s_setprio(0); } while (0)
; #define PG8_WAIT_V(n) asm volatile("s_waitcnt vmcnt(" #n ")" ::: "memory")
; #define PG8_WAIT_L(n) asm volatile("s_waitcnt lgkmcnt(" #n ")" ::: "memory")
; #define PG8_BAR __builtin_amdgcn_s_barrier()
; #define PG8_SCHED __builtin_amdgcn_sched_barrier(0)
; template <class Epi>
; __device__ __forceinline__ void gemm_phase(LAS unsigned char* lds, const Gemm g, const StaticOrder S, const Epi E) {
;     ...
;             PG8_BAR; PG8_WAIT_L(0); PG8_MMA(1, 0, At, B0); PG8_BAR; PG8_SCHED;
;             PG8_STAGE(PG8_SB(0, 1), b2 + hstep, voffA);
;             PG8_WAIT_V(6); PG8_BAR; PG8_MMA(1, 1, At, B1); PG8_BAR;
;             PG8_LDB(B0, 1, 0); PG8_SCHED; PG8_LDA(At, 1, 0); PG8_STAGE(PG8_SA(0, 1), a2 + hstep, voffA);
;             PG8_WAIT_L(8); PG8_BAR; PG8_WAIT_L(0); PG8_MMA(0, 0, At, B0); PG8_BAR; PG8_SCHED;
;             PG8_LDB(B1, 1, 1); PG8_STAGE(PG8_SB(1, 0), b3, voffA);
;             PG8_BAR; PG8_WAIT_L(0); PG8_MMA(0, 1, At, B1); PG8_BAR;
;             PG8_LDA(At, 1, 1); PG8_STAGE(PG8_SA(1, 0), a3, voffA);
	s_waitcnt lgkmcnt(0)
	s_setprio 1
	v_mfma_f32_16x16x32_bf16 v[60:63], v[128:131], v[162:165], 0
	v_mfma_f32_16x16x32_bf16 v[56:59], v[136:139], v[162:165], 0
	v_mfma_f32_16x16x32_bf16 v[44:47], v[128:131], v[170:173], 0
	v_mfma_f32_16x16x32_bf16 v[40:43], v[136:139], v[170:173], 0
	v_mfma_f32_16x16x32_bf16 v[28:31], v[128:131], v[198:201], 0
	v_mfma_f32_16x16x32_bf16 v[24:27], v[136:139], v[198:201], 0
	v_mfma_f32_16x16x32_bf16 v[12:15], v[128:131], v[206:209], 0
	v_mfma_f32_16x16x32_bf16 v[8:11], v[136:139], v[206:209], 0
	v_mfma_f32_16x16x32_bf16 v[60:63], v[132:135], v[166:169], v[60:63]
	v_mfma_f32_16x16x32_bf16 v[56:59], v[150:153], v[166:169], v[56:59]
	v_mfma_f32_16x16x32_bf16 v[44:47], v[132:135], v[194:197], v[44:47]
	v_mfma_f32_16x16x32_bf16 v[40:43], v[150:153], v[194:197], v[40:43]
	v_mfma_f32_16x16x32_bf16 v[28:31], v[132:135], v[202:205], v[28:31]
	v_mfma_f32_16x16x32_bf16 v[24:27], v[150:153], v[202:205], v[24:27]
	v_mfma_f32_16x16x32_bf16 v[12:15], v[132:135], v[220:223], v[12:15]
	v_mfma_f32_16x16x32_bf16 v[8:11], v[150:153], v[220:223], v[8:11]
	s_setprio 0
	s_barrier
	s_mov_b32 m0, s44
	v_lshl_add_u64 v[128:129], s[58:59], 0, v[144:145]
	global_load_lds_dwordx4 v[128:129], off
	v_lshl_add_u64 v[128:129], s[58:59], 0, v[142:143]
	s_mov_b32 m0, s72
	s_nop 0
	global_load_lds_dwordx4 v[128:129], off
	s_waitcnt vmcnt(6)
	s_barrier
	s_setprio 1
	v_mfma_f32_16x16x32_bf16 v[52:55], v[228:231], v[162:165], 0
	v_mfma_f32_16x16x32_bf16 v[48:51], v[236:239], v[162:165], 0
	v_mfma_f32_16x16x32_bf16 v[36:39], v[228:231], v[170:173], 0
	v_mfma_f32_16x16x32_bf16 v[32:35], v[236:239], v[170:173], 0
	v_mfma_f32_16x16x32_bf16 v[20:23], v[228:231], v[198:201], 0
	v_mfma_f32_16x16x32_bf16 v[16:19], v[236:239], v[198:201], 0
	v_mfma_f32_16x16x32_bf16 v[4:7], v[228:231], v[206:209], 0
	v_mfma_f32_16x16x32_bf16 v[0:3], v[236:239], v[206:209], 0
	v_mfma_f32_16x16x32_bf16 v[52:55], v[232:235], v[166:169], v[52:55]
	v_mfma_f32_16x16x32_bf16 v[48:51], v[240:243], v[166:169], v[48:51]
	v_mfma_f32_16x16x32_bf16 v[36:39], v[232:235], v[194:197], v[36:39]
	v_mfma_f32_16x16x32_bf16 v[32:35], v[240:243], v[194:197], v[32:35]
	v_mfma_f32_16x16x32_bf16 v[20:23], v[232:235], v[202:205], v[20:23]
	v_mfma_f32_16x16x32_bf16 v[16:19], v[240:243], v[202:205], v[16:19]
	v_mfma_f32_16x16x32_bf16 v[4:7], v[232:235], v[220:223], v[4:7]
	v_mfma_f32_16x16x32_bf16 v[0:3], v[240:243], v[220:223], v[0:3]
	s_setprio 0
	s_barrier
	v_add_u32_e32 v150, vcc_lo, v155
	ds_read_b128 v[128:131], v150
	ds_read_b128 v[132:135], v150 offset:1024
	ds_read_b128 v[136:139], v150 offset:2048
	ds_read_b128 v[150:153], v150 offset:3072
	s_mov_b32 m0, s25
	v_lshl_add_u64 v[228:229], s[56:57], 0, v[144:145]
	ds_read_b128 v[162:165], v160 offset:32768
	ds_read_b128 v[166:169], v160 offset:33792
	ds_read_b128 v[170:173], v160 offset:34816
	ds_read_b128 v[194:197], v160 offset:35840
	ds_read_b128 v[198:201], v160 offset:36864
	ds_read_b128 v[202:205], v160 offset:37888
	ds_read_b128 v[206:209], v160 offset:38912
	ds_read_b128 v[220:223], v160 offset:39936
	global_load_lds_dwordx4 v[228:229], off
	v_lshl_add_u64 v[228:229], s[56:57], 0, v[142:143]
	s_mov_b32 m0, s66
	s_nop 0
	global_load_lds_dwordx4 v[228:229], off
	s_waitcnt lgkmcnt(8)
	s_barrier
	s_waitcnt lgkmcnt(0)
	s_setprio 1
	v_mfma_f32_16x16x32_bf16 v[124:127], v[128:131], v[162:165], v[124:127]
	v_mfma_f32_16x16x32_bf16 v[120:123], v[136:139], v[162:165], v[120:123]
	v_mfma_f32_16x16x32_bf16 v[108:111], v[128:131], v[170:173], v[108:111]
	v_mfma_f32_16x16x32_bf16 v[104:107], v[136:139], v[170:173], v[104:107]
	v_mfma_f32_16x16x32_bf16 v[92:95], v[128:131], v[198:201], v[92:95]
	v_mfma_f32_16x16x32_bf16 v[88:91], v[136:139], v[198:201], v[88:91]
	v_mfma_f32_16x16x32_bf16 v[76:79], v[128:131], v[206:209], v[76:79]
	v_mfma_f32_16x16x32_bf16 v[72:75], v[136:139], v[206:209], v[72:75]
	v_mfma_f32_16x16x32_bf16 v[124:127], v[132:135], v[166:169], v[124:127]
	v_mfma_f32_16x16x32_bf16 v[120:123], v[150:153], v[166:169], v[120:123]
	v_mfma_f32_16x16x32_bf16 v[108:111], v[132:135], v[194:197], v[108:111]
	v_mfma_f32_16x16x32_bf16 v[104:107], v[150:153], v[194:197], v[104:107]
	v_mfma_f32_16x16x32_bf16 v[92:95], v[132:135], v[202:205], v[92:95]
	v_mfma_f32_16x16x32_bf16 v[88:91], v[150:153], v[202:205], v[88:91]
	v_mfma_f32_16x16x32_bf16 v[76:79], v[132:135], v[220:223], v[76:79]
	v_mfma_f32_16x16x32_bf16 v[72:75], v[150:153], v[220:223], v[72:75]
	s_setprio 0
	s_barrier
	s_mov_b32 m0, s29
	v_add_u32_e32 v161, s3, v155
	v_lshl_add_u64 v[140:141], v[140:141], 0, s[34:35]
	ds_read_b128 v[228:231], v161
	ds_read_b128 v[232:235], v161 offset:1024
	ds_read_b128 v[236:239], v161 offset:2048
	ds_read_b128 v[240:243], v161 offset:3072
	global_load_lds_dwordx4 v[140:141], off
	v_lshl_add_u64 v[140:141], v[174:175], 0, s[34:35]
	s_mov_b32 m0, s1
	s_nop 0
	global_load_lds_dwordx4 v[140:141], off
	s_barrier
; #define PG8_STAGE(bufoff, gbase, voff) do { _Pragma("unroll") for (int _i = 0; _i < 2; ++_i) \
;         __builtin_amdgcn_global_load_lds((const unsigned*)((const char*)(gbase) + (voff)[_i]), (LAS unsigned*)(lds + (bufoff) + ldsw + _i * 8192), 16, 0, 0); } while (0)
; #define PG8_LDA(dst, b, h) do { _Pragma("unroll") for (int m = 0; m < 4; ++m) _Pragma("unroll") for (int k = 0; k < 2; ++k) dst[m][k] = *(const LAS bf16x8*)(lds + PG8_SA(b, h) + aoff + m * 2048 + k * 1024); } while (0)
; #define PG8_MMA(ai, bj, At, Bt) do { __builtin_amdgcn_s_setprio(1); _Pragma("unroll") for (int m = 0; m < 4; ++m) _Pragma("unroll") for (int n = 0; n < 2; ++n) _Pragma("unroll") for (int k = 0; k < 2; ++k) \
;         acc[ai][bj][m][n] = __builtin_amdgcn_mfma_f32_16x16x32_bf16(Bt[n][k], At[m][k], acc[ai][bj][m][n], 0, 0, 0); __builtin_amdgcn_s_setprio(0); } while (0)
; #define PG8_WAIT_V(n) asm volatile("s_waitcnt vmcnt(" #n ")" ::: "memory")
; #define PG8_WAIT_L(n) asm volatile("s_waitcnt lgkmcnt(" #n ")" ::: "memory")
; #define PG8_BAR __builtin_amdgcn_s_barrier()
; #define PG8_SCHED __builtin_amdgcn_sched_barrier(0)
; template <class Epi>
; __device__ __forceinline__ void gemm_phase(LAS unsigned char* lds, const Gemm g, const StaticOrder S, const Epi E) {
;     ...
;         for (int t = 0; t < nt; t += 2) {
;     ...
;             PG8_LDA(At, 1, 1); PG8_STAGE(PG8_SA(1, 0), a3, voffA);
;             PG8_BAR; PG8_WAIT_L(0); PG8_MMA(1, 0, At, B0); PG8_BAR; PG8_SCHED;
;             PG8_STAGE(PG8_SB(1, 1), b3 + hstep, voffA);
;             PG8_WAIT_V(6); PG8_BAR; PG8_MMA(1, 1, At, B1); PG8_BAR;
;         }
	s_waitcnt lgkmcnt(0)
	s_setprio 1
	v_mfma_f32_16x16x32_bf16 v[116:119], v[228:231], v[162:165], v[116:119]
	v_mfma_f32_16x16x32_bf16 v[112:115], v[236:239], v[162:165], v[112:115]
	v_mfma_f32_16x16x32_bf16 v[100:103], v[228:231], v[170:173], v[100:103]
	v_mfma_f32_16x16x32_bf16 v[96:99], v[236:239], v[170:173], v[96:99]
	v_mfma_f32_16x16x32_bf16 v[84:87], v[228:231], v[198:201], v[84:87]
	v_mfma_f32_16x16x32_bf16 v[80:83], v[236:239], v[198:201], v[80:83]
	v_mfma_f32_16x16x32_bf16 v[68:71], v[228:231], v[206:209], v[68:71]
	v_mfma_f32_16x16x32_bf16 v[64:67], v[236:239], v[206:209], v[64:67]
	v_mfma_f32_16x16x32_bf16 v[116:119], v[232:235], v[166:169], v[116:119]
	v_mfma_f32_16x16x32_bf16 v[112:115], v[240:243], v[166:169], v[112:115]
	v_mfma_f32_16x16x32_bf16 v[100:103], v[232:235], v[194:197], v[100:103]
	v_mfma_f32_16x16x32_bf16 v[96:99], v[240:243], v[194:197], v[96:99]
	v_mfma_f32_16x16x32_bf16 v[84:87], v[232:235], v[202:205], v[84:87]
	v_mfma_f32_16x16x32_bf16 v[80:83], v[240:243], v[202:205], v[80:83]
	v_mfma_f32_16x16x32_bf16 v[68:71], v[232:235], v[220:223], v[68:71]
	v_mfma_f32_16x16x32_bf16 v[64:67], v[240:243], v[220:223], v[64:67]
	s_setprio 0
	s_barrier
	s_mov_b32 m0, s68
	v_lshl_add_u64 v[140:141], v[210:211], 0, s[34:35]
	ds_read_b128 v[162:165], v160 offset:49152
	ds_read_b128 v[166:169], v160 offset:50176
	ds_read_b128 v[170:173], v160 offset:51200
	ds_read_b128 v[194:197], v160 offset:52224
	ds_read_b128 v[198:201], v160 offset:53248
	ds_read_b128 v[202:205], v160 offset:54272
	ds_read_b128 v[206:209], v160 offset:55296
	ds_read_b128 v[220:223], v160 offset:56320
	global_load_lds_dwordx4 v[140:141], off
	v_lshl_add_u64 v[140:141], v[244:245], 0, s[34:35]
	s_mov_b32 m0, s69
	s_nop 0
	global_load_lds_dwordx4 v[140:141], off
	s_barrier
	s_waitcnt lgkmcnt(0)
	s_setprio 1
	v_mfma_f32_16x16x32_bf16 v[60:63], v[128:131], v[162:165], v[60:63]
	v_mfma_f32_16x16x32_bf16 v[56:59], v[136:139], v[162:165], v[56:59]
	v_mfma_f32_16x16x32_bf16 v[44:47], v[128:131], v[170:173], v[44:47]
	v_mfma_f32_16x16x32_bf16 v[40:43], v[136:139], v[170:173], v[40:43]
	v_mfma_f32_16x16x32_bf16 v[28:31], v[128:131], v[198:201], v[28:31]
	v_mfma_f32_16x16x32_bf16 v[24:27], v[136:139], v[198:201], v[24:27]
	v_mfma_f32_16x16x32_bf16 v[12:15], v[128:131], v[206:209], v[12:15]
	v_mfma_f32_16x16x32_bf16 v[8:11], v[136:139], v[206:209], v[8:11]
	v_mfma_f32_16x16x32_bf16 v[60:63], v[132:135], v[166:169], v[60:63]
	v_mfma_f32_16x16x32_bf16 v[56:59], v[150:153], v[166:169], v[56:59]
	v_mfma_f32_16x16x32_bf16 v[44:47], v[132:135], v[194:197], v[44:47]
	v_mfma_f32_16x16x32_bf16 v[40:43], v[150:153], v[194:197], v[40:43]
	v_mfma_f32_16x16x32_bf16 v[28:31], v[132:135], v[202:205], v[28:31]
	v_mfma_f32_16x16x32_bf16 v[24:27], v[150:153], v[202:205], v[24:27]
	v_mfma_f32_16x16x32_bf16 v[12:15], v[132:135], v[220:223], v[12:15]
	v_mfma_f32_16x16x32_bf16 v[8:11], v[150:153], v[220:223], v[8:11]
	s_setprio 0
	s_barrier
	s_mov_b32 m0, s45
	v_lshl_add_u64 v[128:129], s[54:55], 0, v[144:145]
	global_load_lds_dwordx4 v[128:129], off
	v_lshl_add_u64 v[128:129], s[54:55], 0, v[142:143]
	s_mov_b32 m0, s30
	s_nop 0
	global_load_lds_dwordx4 v[128:129], off
	s_waitcnt vmcnt(6)
	s_barrier
	s_setprio 1
	v_mfma_f32_16x16x32_bf16 v[52:55], v[228:231], v[162:165], v[52:55]
	v_mfma_f32_16x16x32_bf16 v[48:51], v[236:239], v[162:165], v[48:51]
	v_mfma_f32_16x16x32_bf16 v[36:39], v[228:231], v[170:173], v[36:39]
	v_mfma_f32_16x16x32_bf16 v[32:35], v[236:239], v[170:173], v[32:35]
	v_mfma_f32_16x16x32_bf16 v[20:23], v[228:231], v[198:201], v[20:23]
	v_mfma_f32_16x16x32_bf16 v[16:19], v[236:239], v[198:201], v[16:19]
	v_mfma_f32_16x16x32_bf16 v[4:7], v[228:231], v[206:209], v[4:7]
	v_mfma_f32_16x16x32_bf16 v[0:3], v[236:239], v[206:209], v[0:3]
	v_mfma_f32_16x16x32_bf16 v[52:55], v[232:235], v[166:169], v[52:55]
	v_mfma_f32_16x16x32_bf16 v[48:51], v[240:243], v[166:169], v[48:51]
	v_mfma_f32_16x16x32_bf16 v[36:39], v[232:235], v[194:197], v[36:39]
	v_mfma_f32_16x16x32_bf16 v[32:35], v[240:243], v[194:197], v[32:35]
	v_mfma_f32_16x16x32_bf16 v[20:23], v[232:235], v[202:205], v[20:23]
	v_mfma_f32_16x16x32_bf16 v[16:19], v[240:243], v[202:205], v[16:19]
	v_mfma_f32_16x16x32_bf16 v[4:7], v[232:235], v[220:223], v[4:7]
	v_mfma_f32_16x16x32_bf16 v[0:3], v[240:243], v[220:223], v[0:3]
	s_setprio 0
	s_barrier
	s_movk_i32 s1, 0x100
	s_andn2_b64 vcc, exec, s[52:53]
	s_mov_b64 s[54:55], -1
	s_mov_b64 s[52:53], 0
	s_cbranch_vccz .LBB0_3306
	s_branch .Lpeel_exit_4

;     __device__ __forceinline__ void operator()(AccRef acc, const pg8::Unit& u, int wr, int wc, int fr, int fq) const {
;         const int row0 = u.pm * 256 + wr * 64 + fr, col0 = u.pn * 256 + wc * 32 + 4 * fq;
;         const bool rope = (u.pn == rope_pn) && (u.pm < 32);
; #pragma unroll
;         for (int ai = 0; ai < 2; ++ai)
; #pragma unroll
;             for (int m = 0; m < 4; ++m) { const int row = row0 + ai * 128 + m * 16; bf16_t* rowp = O + (size_t)row * ldc + col0;
;                 f32x4 cs = {1.f, 1.f, 1.f, 1.f}, sn = {0.f, 0.f, 0.f, 0.f};
;                 if (rope) { const int t = row & 2047; const int pos = (wc & 1) ? (t & 63) : (t >> 6); cs = *(const f32x4*)(cos64 + pos * 16 + 4 * fq); sn = *(const f32x4*)(sin64 + pos * 16 + 4 * fq); }
.Lpeel_exit_4:
	s_lshl_b32 s3, s28, 8
	s_add_i32 s3, s3, s67
	s_cmp_eq_u32 s27, -1
	s_cselect_b64 s[30:31], -1, 0
	s_cmp_lt_i32 s28, 32
	s_cselect_b64 s[28:29], -1, 0
	s_and_b64 s[28:29], s[30:31], s[28:29]
	v_cndmask_b32_e64 v129, 0, 1, s[28:29]
	s_bfe_u32 s1, s3, 0x50006
	v_mov_b32_e32 v128, 1.0
	v_mov_b32_e32 v132, 0
	v_cmp_ne_u32_e64 s[42:43], 1, v129
	s_andn2_b64 vcc, exec, s[28:29]
	v_mov_b32_e32 v134, 0
	v_mov_b32_e32 v135, 0
	v_mov_b32_e32 v136, 0
	v_mov_b32_e32 v137, 0
	v_mov_b32_e32 v138, 1.0
	v_mov_b32_e32 v139, 1.0
	v_mov_b32_e32 v140, 1.0
	v_mov_b32_e32 v141, 1.0
	s_cbranch_vccnz .LBB0_3309
	v_mov_b32_e32 v129, s1
	v_cndmask_b32_e64 v129, v154, v129, s[38:39]
	v_lshlrev_b32_e32 v178, 6, v129
	v_lshl_add_u64 v[130:131], v[148:149], 0, v[178:179]
	v_lshl_add_u64 v[134:135], v[146:147], 0, v[178:179]
	global_load_dwordx4 v[138:141], v[130:131], off
	s_nop 0
	global_load_dwordx4 v[134:137], v[134:135], off

; #define PG8_STAGE(bufoff, gbase, voff) do { _Pragma("unroll") for (int _i = 0; _i < 2; ++_i) \
;         __builtin_amdgcn_global_load_lds((const unsigned*)((const char*)(gbase) + (voff)[_i]), (LAS unsigned*)(lds + (bufoff) + ldsw + _i * 8192), 16, 0, 0); } while (0)
; #define PG8_LDA(dst, b, h) do { _Pragma("unroll") for (int m = 0; m < 4; ++m) _Pragma("unroll") for (int k = 0; k < 2; ++k) dst[m][k] = *(const LAS bf16x8*)(lds + PG8_SA(b, h) + aoff + m * 2048 + k * 1024); } while (0)
; #define PG8_LDB(dst, b, h) do { _Pragma("unroll") for (int n = 0; n < 2; ++n) _Pragma("unroll") for (int k = 0; k < 2; ++k) dst[n][k] = *(const LAS bf16x8*)(lds + PG8_SB(b, h) + boff + n * 2048 + k * 1024); } while (0)
; #define PG8_MMA(ai, bj, At, Bt) do { __builtin_amdgcn_s_setprio(1); _Pragma("unroll") for (int m = 0; m < 4; ++m) _Pragma("unroll") for (int n = 0; n < 2; ++n) _Pragma("unroll") for (int k = 0; k < 2; ++k) \
;         acc[ai][bj][m][n] = __builtin_amdgcn_mfma_f32_16x16x32_bf16(Bt[n][k], At[m][k], acc[ai][bj][m][n], 0, 0, 0); __builtin_amdgcn_s_setprio(0); } while (0)
; #define PG8_WAIT_L(n) asm volatile("s_waitcnt lgkmcnt(" #n ")" ::: "memory")
; #define PG8_BAR __builtin_amdgcn_s_barrier()
; #define PG8_SCHED __builtin_amdgcn_sched_barrier(0)
; template <class Epi>
; __device__ __forceinline__ void gemm_phase(LAS unsigned char* lds, const Gemm g, const StaticOrder S, const Epi E) {
;     ...
;         for (int t = 0; t < nt; t += 2) {
;             const bool last = (t == nt - 2);
;             const char* a1 = cA + (size_t)(t + 1) * kstep;
;             const char* a2 = last ? nA : cA + (size_t)(t + 2) * kstep; const char* b2 = last ? nB : cB + (size_t)(t + 2) * kstep;
;             const char* a3 = a2 + kstep; const char* b3 = b2 + kstep;
;             PG8_LDB(B0, 0, 0); PG8_SCHED; PG8_LDA(At, 0, 0); PG8_STAGE(PG8_SA(1, 1), a1 + hstep, voffA);
;             PG8_WAIT_L(8); PG8_BAR; PG8_WAIT_L(0); PG8_MMA(0, 0, At, B0); PG8_BAR; PG8_SCHED;
;             PG8_LDB(B1, 0, 1); PG8_STAGE(PG8_SB(0, 0), b2, voffA);
;             PG8_BAR; PG8_WAIT_L(0); PG8_MMA(0, 1, At, B1); PG8_BAR;
;             PG8_LDA(At, 0, 1); PG8_STAGE(PG8_SA(0, 0), a2, voffA);
;             PG8_BAR; PG8_WAIT_L(0); PG8_MMA(1, 0, At, B0); PG8_BAR; PG8_SCHED;
.LBB0_3567:
	s_add_i32 s43, s39, -2
	s_add_u32 s45, s58, 0x100
	s_addc_u32 s47, s59, 0
	s_mov_b32 s55, 0
	s_add_i32 vcc_lo, s55, 2
	s_add_u32 s58, s56, 0x100
	s_addc_u32 s59, s57, 0
	s_add_i32 s14, 0, 0x10000
	v_add_u32_e32 v132, s14, v228
	ds_read_b128 v[116:119], v132
	ds_read_b128 v[124:127], v132 offset:1024
	ds_read_b128 v[128:131], v132 offset:2048
	ds_read_b128 v[132:135], v132 offset:3072
	s_cmp_eq_u32 s43, s55
	s_cselect_b32 s63, s51, s59
	s_cselect_b32 s62, s50, s58
	s_cselect_b32 s61, s53, s47
	s_cselect_b32 s60, s52, s45
	v_lshl_add_u64 v[200:201], s[56:57], 0, v[196:197]
	s_add_i32 m0, s25, 0xc000
	ds_read_b128 v[144:147], v230
	ds_read_b128 v[148:151], v230 offset:1024
	ds_read_b128 v[152:155], v230 offset:2048
	ds_read_b128 v[156:159], v230 offset:3072
	ds_read_b128 v[160:163], v230 offset:4096
	ds_read_b128 v[164:167], v230 offset:5120
	ds_read_b128 v[168:171], v230 offset:6144
	ds_read_b128 v[172:175], v230 offset:7168
	global_load_lds_dwordx4 v[200:201], off
	v_lshl_add_u64 v[200:201], s[56:57], 0, v[198:199]
	s_add_i32 m0, s25, 0xe000
	s_nop 0
	global_load_lds_dwordx4 v[200:201], off
	s_waitcnt lgkmcnt(8)
	s_barrier
	s_waitcnt lgkmcnt(0)
	s_setprio 1
	v_mfma_f32_16x16x32_bf16 v[140:143], v[116:119], v[144:147], 0
	v_mfma_f32_16x16x32_bf16 v[136:139], v[128:131], v[144:147], 0
	v_mfma_f32_16x16x32_bf16 v[112:115], v[116:119], v[152:155], 0
	v_mfma_f32_16x16x32_bf16 v[104:107], v[128:131], v[152:155], 0
	v_mfma_f32_16x16x32_bf16 v[92:95], v[116:119], v[160:163], 0
	v_mfma_f32_16x16x32_bf16 v[88:91], v[128:131], v[160:163], 0
	v_mfma_f32_16x16x32_bf16 v[80:83], v[116:119], v[168:171], 0
	v_mfma_f32_16x16x32_bf16 v[72:75], v[128:131], v[168:171], 0
	v_mfma_f32_16x16x32_bf16 v[140:143], v[124:127], v[148:151], v[140:143]
	v_mfma_f32_16x16x32_bf16 v[136:139], v[132:135], v[148:151], v[136:139]
	v_mfma_f32_16x16x32_bf16 v[112:115], v[124:127], v[156:159], v[112:115]
	v_mfma_f32_16x16x32_bf16 v[104:107], v[132:135], v[156:159], v[104:107]
	v_mfma_f32_16x16x32_bf16 v[92:95], v[124:127], v[164:167], v[92:95]
	v_mfma_f32_16x16x32_bf16 v[88:91], v[132:135], v[164:167], v[88:91]
	v_mfma_f32_16x16x32_bf16 v[80:83], v[124:127], v[172:175], v[80:83]
	v_mfma_f32_16x16x32_bf16 v[72:75], v[132:135], v[172:175], v[72:75]
	s_setprio 0
	s_barrier
	s_add_i32 s55, 0, 0x14000
	s_add_i32 s14, s14, s24
	v_add_u32_e32 v220, s55, v228
	v_lshl_add_u64 v[232:233], s[60:61], 0, v[178:179]
	s_mov_b32 m0, s14
	ds_read_b128 v[200:203], v220
	ds_read_b128 v[204:207], v220 offset:1024
	ds_read_b128 v[208:211], v220 offset:2048
	ds_read_b128 v[220:223], v220 offset:3072
	global_load_lds_dwordx4 v[232:233], off
	v_lshl_add_u64 v[234:235], s[60:61], 0, v[194:195]
	s_add_i32 m0, s14, 0x2000
	s_nop 0
	global_load_lds_dwordx4 v[234:235], off
	s_barrier
	s_waitcnt lgkmcnt(0)
	s_setprio 1
	v_mfma_f32_16x16x32_bf16 v[120:123], v[200:203], v[144:147], 0
	v_mfma_f32_16x16x32_bf16 v[108:111], v[208:211], v[144:147], 0
	v_mfma_f32_16x16x32_bf16 v[100:103], v[200:203], v[152:155], 0
	v_mfma_f32_16x16x32_bf16 v[96:99], v[208:211], v[152:155], 0
	v_mfma_f32_16x16x32_bf16 v[84:87], v[200:203], v[160:163], 0
	v_mfma_f32_16x16x32_bf16 v[76:79], v[208:211], v[160:163], 0
	v_mfma_f32_16x16x32_bf16 v[68:71], v[200:203], v[168:171], 0
	v_mfma_f32_16x16x32_bf16 v[64:67], v[208:211], v[168:171], 0
	v_mfma_f32_16x16x32_bf16 v[120:123], v[204:207], v[148:151], v[120:123]
	v_mfma_f32_16x16x32_bf16 v[108:111], v[220:223], v[148:151], v[108:111]
	v_mfma_f32_16x16x32_bf16 v[100:103], v[204:207], v[156:159], v[100:103]
	v_mfma_f32_16x16x32_bf16 v[96:99], v[220:223], v[156:159], v[96:99]
	v_mfma_f32_16x16x32_bf16 v[84:87], v[204:207], v[164:167], v[84:87]
	v_mfma_f32_16x16x32_bf16 v[76:79], v[220:223], v[164:167], v[76:79]
	v_mfma_f32_16x16x32_bf16 v[68:71], v[204:207], v[172:175], v[68:71]
	v_mfma_f32_16x16x32_bf16 v[64:67], v[220:223], v[172:175], v[64:67]
	s_setprio 0
	s_barrier
	s_mov_b32 m0, s25
	v_lshl_add_u64 v[236:237], s[62:63], 0, v[178:179]
	ds_read_b128 v[144:147], v230 offset:16384
	ds_read_b128 v[148:151], v230 offset:17408
	ds_read_b128 v[152:155], v230 offset:18432
	ds_read_b128 v[156:159], v230 offset:19456
	ds_read_b128 v[160:163], v230 offset:20480
	ds_read_b128 v[164:167], v230 offset:21504
	ds_read_b128 v[168:171], v230 offset:22528
	ds_read_b128 v[172:175], v230 offset:23552
	global_load_lds_dwordx4 v[236:237], off
	v_lshl_add_u64 v[238:239], s[62:63], 0, v[194:195]
	s_mov_b32 m0, s64
	s_nop 0
	global_load_lds_dwordx4 v[238:239], off
	s_barrier
	s_waitcnt lgkmcnt(0)
	s_setprio 1
	v_mfma_f32_16x16x32_bf16 v[60:63], v[116:119], v[144:147], 0
	v_mfma_f32_16x16x32_bf16 v[56:59], v[128:131], v[144:147], 0
	v_mfma_f32_16x16x32_bf16 v[48:51], v[116:119], v[152:155], 0
	v_mfma_f32_16x16x32_bf16 v[40:43], v[128:131], v[152:155], 0
	v_mfma_f32_16x16x32_bf16 v[28:31], v[116:119], v[160:163], 0
	v_mfma_f32_16x16x32_bf16 v[24:27], v[128:131], v[160:163], 0
	v_mfma_f32_16x16x32_bf16 v[16:19], v[116:119], v[168:171], 0
	v_mfma_f32_16x16x32_bf16 v[8:11], v[128:131], v[168:171], 0
	v_mfma_f32_16x16x32_bf16 v[60:63], v[124:127], v[148:151], v[60:63]
	v_mfma_f32_16x16x32_bf16 v[56:59], v[132:135], v[148:151], v[56:59]
	v_mfma_f32_16x16x32_bf16 v[48:51], v[124:127], v[156:159], v[48:51]
	v_mfma_f32_16x16x32_bf16 v[40:43], v[132:135], v[156:159], v[40:43]
	v_mfma_f32_16x16x32_bf16 v[28:31], v[124:127], v[164:167], v[28:31]
	v_mfma_f32_16x16x32_bf16 v[24:27], v[132:135], v[164:167], v[24:27]
	v_mfma_f32_16x16x32_bf16 v[16:19], v[124:127], v[172:175], v[16:19]
	v_mfma_f32_16x16x32_bf16 v[8:11], v[132:135], v[172:175], v[8:11]
	s_setprio 0
	s_barrier
; #define PG8_STAGE(bufoff, gbase, voff) do { _Pragma("unroll") for (int _i = 0; _i < 2; ++_i) \
;         __builtin_amdgcn_global_load_lds((const unsigned*)((const char*)(gbase) + (voff)[_i]), (LAS unsigned*)(lds + (bufoff) + ldsw + _i * 8192), 16, 0, 0); } while (0)
; #define PG8_LDA(dst, b, h) do { _Pragma("unroll") for (int m = 0; m < 4; ++m) _Pragma("unroll") for (int k = 0; k < 2; ++k) dst[m][k] = *(const LAS bf16x8*)(lds + PG8_SA(b, h) + aoff + m * 2048 + k * 1024); } while (0)
; #define PG8_LDB(dst, b, h) do { _Pragma("unroll") for (int n = 0; n < 2; ++n) _Pragma("unroll") for (int k = 0; k < 2; ++k) dst[n][k] = *(const LAS bf16x8*)(lds + PG8_SB(b, h) + boff + n * 2048 + k * 1024); } while (0)
; #define PG8_MMA(ai, bj, At, Bt) do { __builtin_amdgcn_s_setprio(1); _Pragma("unroll") for (int m = 0; m < 4; ++m) _Pragma("unroll") for (int n = 0; n < 2; ++n) _Pragma("unroll") for (int k = 0; k < 2; ++k) \
;         acc[ai][bj][m][n] = __builtin_amdgcn_mfma_f32_16x16x32_bf16(Bt[n][k], At[m][k], acc[ai][bj][m][n], 0, 0, 0); __builtin_amdgcn_s_setprio(0); } while (0)
; #define PG8_WAIT_V(n) asm volatile("s_waitcnt vmcnt(" #n ")" ::: "memory")
; #define PG8_WAIT_L(n) asm volatile("s_waitcnt lgkmcnt(" #n ")" ::: "memory")
; #define PG8_BAR __builtin_amdgcn_s_barrier()
; #define PG8_SCHED __builtin_amdgcn_sched_barrier(0)
; template <class Epi>
; __device__ __forceinline__ void gemm_phase(LAS unsigned char* lds, const Gemm g, const StaticOrder S, const Epi E) {
;     ...
;             PG8_STAGE(PG8_SB(0, 1), b2 + hstep, voffA);
;             PG8_WAIT_V(6); PG8_BAR; PG8_MMA(1, 1, At, B1); PG8_BAR;
;             PG8_LDB(B0, 1, 0); PG8_SCHED; PG8_LDA(At, 1, 0); PG8_STAGE(PG8_SA(0, 1), a2 + hstep, voffA);
;             PG8_WAIT_L(8); PG8_BAR; PG8_WAIT_L(0); PG8_MMA(0, 0, At, B0); PG8_BAR; PG8_SCHED;
;             PG8_LDB(B1, 1, 1); PG8_STAGE(PG8_SB(1, 0), b3, voffA);
;             PG8_BAR; PG8_WAIT_L(0); PG8_MMA(0, 1, At, B1); PG8_BAR;
;             PG8_LDA(At, 1, 1); PG8_STAGE(PG8_SA(1, 0), a3, voffA);
	s_add_u32 s30, s60, 0x80000
	s_addc_u32 s31, s61, 0
	s_add_i32 s14, s55, s24
	v_lshl_add_u64 v[116:117], s[30:31], 0, v[178:179]
	s_mov_b32 m0, s14
	s_nop 0
	global_load_lds_dwordx4 v[116:117], off
	v_lshl_add_u64 v[116:117], s[30:31], 0, v[194:195]
	s_add_i32 m0, s14, 0x2000
	s_nop 0
	global_load_lds_dwordx4 v[116:117], off
	s_waitcnt vmcnt(6)
	s_barrier
	s_setprio 1
	v_mfma_f32_16x16x32_bf16 v[52:55], v[200:203], v[144:147], 0
	v_mfma_f32_16x16x32_bf16 v[44:47], v[208:211], v[144:147], 0
	v_mfma_f32_16x16x32_bf16 v[36:39], v[200:203], v[152:155], 0
	v_mfma_f32_16x16x32_bf16 v[32:35], v[208:211], v[152:155], 0
	v_mfma_f32_16x16x32_bf16 v[20:23], v[200:203], v[160:163], 0
	v_mfma_f32_16x16x32_bf16 v[12:15], v[208:211], v[160:163], 0
	v_mfma_f32_16x16x32_bf16 v[4:7], v[200:203], v[168:171], 0
	v_mfma_f32_16x16x32_bf16 v[0:3], v[208:211], v[168:171], 0
	v_mfma_f32_16x16x32_bf16 v[52:55], v[204:207], v[148:151], v[52:55]
	v_mfma_f32_16x16x32_bf16 v[44:47], v[220:223], v[148:151], v[44:47]
	v_mfma_f32_16x16x32_bf16 v[36:39], v[204:207], v[156:159], v[36:39]
	v_mfma_f32_16x16x32_bf16 v[32:35], v[220:223], v[156:159], v[32:35]
	v_mfma_f32_16x16x32_bf16 v[20:23], v[204:207], v[164:167], v[20:23]
	v_mfma_f32_16x16x32_bf16 v[12:15], v[220:223], v[164:167], v[12:15]
	v_mfma_f32_16x16x32_bf16 v[4:7], v[204:207], v[172:175], v[4:7]
	v_mfma_f32_16x16x32_bf16 v[0:3], v[220:223], v[172:175], v[0:3]
	s_setprio 0
	s_barrier
	s_add_i32 s14, 0, 0x18000
	v_add_u32_e32 v132, s14, v228
	ds_read_b128 v[116:119], v132
	ds_read_b128 v[124:127], v132 offset:1024
	ds_read_b128 v[128:131], v132 offset:2048
	ds_read_b128 v[132:135], v132 offset:3072
	s_add_u32 s30, s62, 0x80000
	s_addc_u32 s31, s63, 0
	s_mov_b32 m0, s65
	v_lshl_add_u64 v[200:201], s[30:31], 0, v[178:179]
	ds_read_b128 v[144:147], v230 offset:32768
	ds_read_b128 v[148:151], v230 offset:33792
	ds_read_b128 v[152:155], v230 offset:34816
	ds_read_b128 v[156:159], v230 offset:35840
	ds_read_b128 v[160:163], v230 offset:36864
	ds_read_b128 v[164:167], v230 offset:37888
	ds_read_b128 v[168:171], v230 offset:38912
	ds_read_b128 v[172:175], v230 offset:39936
	global_load_lds_dwordx4 v[200:201], off
	v_lshl_add_u64 v[200:201], s[30:31], 0, v[194:195]
	s_mov_b32 m0, s66
	s_nop 0
	global_load_lds_dwordx4 v[200:201], off
	s_waitcnt lgkmcnt(8)
	s_barrier
	s_waitcnt lgkmcnt(0)
	s_setprio 1
	v_mfma_f32_16x16x32_bf16 v[140:143], v[116:119], v[144:147], v[140:143]
	v_mfma_f32_16x16x32_bf16 v[136:139], v[128:131], v[144:147], v[136:139]
	v_mfma_f32_16x16x32_bf16 v[112:115], v[116:119], v[152:155], v[112:115]
	v_mfma_f32_16x16x32_bf16 v[104:107], v[128:131], v[152:155], v[104:107]
	v_mfma_f32_16x16x32_bf16 v[92:95], v[116:119], v[160:163], v[92:95]
	v_mfma_f32_16x16x32_bf16 v[88:91], v[128:131], v[160:163], v[88:91]
	v_mfma_f32_16x16x32_bf16 v[80:83], v[116:119], v[168:171], v[80:83]
	v_mfma_f32_16x16x32_bf16 v[72:75], v[128:131], v[168:171], v[72:75]
	v_mfma_f32_16x16x32_bf16 v[140:143], v[124:127], v[148:151], v[140:143]
	v_mfma_f32_16x16x32_bf16 v[136:139], v[132:135], v[148:151], v[136:139]
	v_mfma_f32_16x16x32_bf16 v[112:115], v[124:127], v[156:159], v[112:115]
	v_mfma_f32_16x16x32_bf16 v[104:107], v[132:135], v[156:159], v[104:107]
	v_mfma_f32_16x16x32_bf16 v[92:95], v[124:127], v[164:167], v[92:95]
	v_mfma_f32_16x16x32_bf16 v[88:91], v[132:135], v[164:167], v[88:91]
	v_mfma_f32_16x16x32_bf16 v[80:83], v[124:127], v[172:175], v[80:83]
	v_mfma_f32_16x16x32_bf16 v[72:75], v[132:135], v[172:175], v[72:75]
	s_setprio 0
	s_barrier
	s_add_i32 s55, 0, 0x1c000
	s_add_i32 s14, s14, s24
	v_add_u32_e32 v220, s55, v228
	v_lshl_add_u64 v[232:233], v[232:233], 0, s[34:35]
	s_mov_b32 m0, s14
	ds_read_b128 v[200:203], v220
	ds_read_b128 v[204:207], v220 offset:1024
	ds_read_b128 v[208:211], v220 offset:2048
	ds_read_b128 v[220:223], v220 offset:3072
	global_load_lds_dwordx4 v[232:233], off
	v_lshl_add_u64 v[232:233], v[234:235], 0, s[34:35]
	s_add_i32 m0, s14, 0x2000
	s_nop 0
	global_load_lds_dwordx4 v[232:233], off
	s_barrier
; #define PG8_STAGE(bufoff, gbase, voff) do { _Pragma("unroll") for (int _i = 0; _i < 2; ++_i) \
;         __builtin_amdgcn_global_load_lds((const unsigned*)((const char*)(gbase) + (voff)[_i]), (LAS unsigned*)(lds + (bufoff) + ldsw + _i * 8192), 16, 0, 0); } while (0)
; #define PG8_LDA(dst, b, h) do { _Pragma("unroll") for (int m = 0; m < 4; ++m) _Pragma("unroll") for (int k = 0; k < 2; ++k) dst[m][k] = *(const LAS bf16x8*)(lds + PG8_SA(b, h) + aoff + m * 2048 + k * 1024); } while (0)
; #define PG8_MMA(ai, bj, At, Bt) do { __builtin_amdgcn_s_setprio(1); _Pragma("unroll") for (int m = 0; m < 4; ++m) _Pragma("unroll") for (int n = 0; n < 2; ++n) _Pragma("unroll") for (int k = 0; k < 2; ++k) \
;         acc[ai][bj][m][n] = __builtin_amdgcn_mfma_f32_16x16x32_bf16(Bt[n][k], At[m][k], acc[ai][bj][m][n], 0, 0, 0); __builtin_amdgcn_s_setprio(0); } while (0)
; #define PG8_WAIT_V(n) asm volatile("s_waitcnt vmcnt(" #n ")" ::: "memory")
; #define PG8_WAIT_L(n) asm volatile("s_waitcnt lgkmcnt(" #n ")" ::: "memory")
; #define PG8_BAR __builtin_amdgcn_s_barrier()
; #define PG8_SCHED __builtin_amdgcn_sched_barrier(0)
; template <class Epi>
; __device__ __forceinline__ void gemm_phase(LAS unsigned char* lds, const Gemm g, const StaticOrder S, const Epi E) {
;     ...
;         for (int t = 0; t < nt; t += 2) {
;     ...
;             PG8_LDA(At, 1, 1); PG8_STAGE(PG8_SA(1, 0), a3, voffA);
;             PG8_BAR; PG8_WAIT_L(0); PG8_MMA(1, 0, At, B0); PG8_BAR; PG8_SCHED;
;             PG8_STAGE(PG8_SB(1, 1), b3 + hstep, voffA);
;             PG8_WAIT_V(6); PG8_BAR; PG8_MMA(1, 1, At, B1); PG8_BAR;
;         }
	s_waitcnt lgkmcnt(0)
	s_setprio 1
	v_mfma_f32_16x16x32_bf16 v[120:123], v[200:203], v[144:147], v[120:123]
	v_mfma_f32_16x16x32_bf16 v[108:111], v[208:211], v[144:147], v[108:111]
	v_mfma_f32_16x16x32_bf16 v[100:103], v[200:203], v[152:155], v[100:103]
	v_mfma_f32_16x16x32_bf16 v[96:99], v[208:211], v[152:155], v[96:99]
	v_mfma_f32_16x16x32_bf16 v[84:87], v[200:203], v[160:163], v[84:87]
	v_mfma_f32_16x16x32_bf16 v[76:79], v[208:211], v[160:163], v[76:79]
	v_mfma_f32_16x16x32_bf16 v[68:71], v[200:203], v[168:171], v[68:71]
	v_mfma_f32_16x16x32_bf16 v[64:67], v[208:211], v[168:171], v[64:67]
	v_mfma_f32_16x16x32_bf16 v[120:123], v[204:207], v[148:151], v[120:123]
	v_mfma_f32_16x16x32_bf16 v[108:111], v[220:223], v[148:151], v[108:111]
	v_mfma_f32_16x16x32_bf16 v[100:103], v[204:207], v[156:159], v[100:103]
	v_mfma_f32_16x16x32_bf16 v[96:99], v[220:223], v[156:159], v[96:99]
	v_mfma_f32_16x16x32_bf16 v[84:87], v[204:207], v[164:167], v[84:87]
	v_mfma_f32_16x16x32_bf16 v[76:79], v[220:223], v[164:167], v[76:79]
	v_mfma_f32_16x16x32_bf16 v[68:71], v[204:207], v[172:175], v[68:71]
	v_mfma_f32_16x16x32_bf16 v[64:67], v[220:223], v[172:175], v[64:67]
	s_setprio 0
	s_barrier
	s_mov_b32 m0, s69
	v_lshl_add_u64 v[232:233], v[236:237], 0, s[34:35]
	ds_read_b128 v[144:147], v230 offset:49152
	ds_read_b128 v[148:151], v230 offset:50176
	ds_read_b128 v[152:155], v230 offset:51200
	ds_read_b128 v[156:159], v230 offset:52224
	ds_read_b128 v[160:163], v230 offset:53248
	ds_read_b128 v[164:167], v230 offset:54272
	ds_read_b128 v[168:171], v230 offset:55296
	ds_read_b128 v[172:175], v230 offset:56320
	global_load_lds_dwordx4 v[232:233], off
	v_lshl_add_u64 v[232:233], v[238:239], 0, s[34:35]
	s_mov_b32 m0, s7
	s_nop 0
	global_load_lds_dwordx4 v[232:233], off
	s_barrier
	s_waitcnt lgkmcnt(0)
	s_setprio 1
	v_mfma_f32_16x16x32_bf16 v[60:63], v[116:119], v[144:147], v[60:63]
	v_mfma_f32_16x16x32_bf16 v[56:59], v[128:131], v[144:147], v[56:59]
	v_mfma_f32_16x16x32_bf16 v[48:51], v[116:119], v[152:155], v[48:51]
	v_mfma_f32_16x16x32_bf16 v[40:43], v[128:131], v[152:155], v[40:43]
	v_mfma_f32_16x16x32_bf16 v[28:31], v[116:119], v[160:163], v[28:31]
	v_mfma_f32_16x16x32_bf16 v[24:27], v[128:131], v[160:163], v[24:27]
	v_mfma_f32_16x16x32_bf16 v[16:19], v[116:119], v[168:171], v[16:19]
	v_mfma_f32_16x16x32_bf16 v[8:11], v[128:131], v[168:171], v[8:11]
	v_mfma_f32_16x16x32_bf16 v[60:63], v[124:127], v[148:151], v[60:63]
	v_mfma_f32_16x16x32_bf16 v[56:59], v[132:135], v[148:151], v[56:59]
	v_mfma_f32_16x16x32_bf16 v[48:51], v[124:127], v[156:159], v[48:51]
	v_mfma_f32_16x16x32_bf16 v[40:43], v[132:135], v[156:159], v[40:43]
	v_mfma_f32_16x16x32_bf16 v[28:31], v[124:127], v[164:167], v[28:31]
	v_mfma_f32_16x16x32_bf16 v[24:27], v[132:135], v[164:167], v[24:27]
	v_mfma_f32_16x16x32_bf16 v[16:19], v[124:127], v[172:175], v[16:19]
	v_mfma_f32_16x16x32_bf16 v[8:11], v[132:135], v[172:175], v[8:11]
	s_setprio 0
	s_barrier
	s_add_u32 s30, s60, 0x80080
	s_addc_u32 s31, s61, 0
	s_add_i32 s14, s55, s24
	v_lshl_add_u64 v[116:117], s[30:31], 0, v[178:179]
	s_mov_b32 m0, s14
	s_nop 0
	global_load_lds_dwordx4 v[116:117], off
	v_lshl_add_u64 v[116:117], s[30:31], 0, v[194:195]
	s_add_i32 m0, s14, 0x2000
	s_nop 0
	global_load_lds_dwordx4 v[116:117], off
	s_waitcnt vmcnt(6)
	s_barrier
	s_setprio 1
	v_mfma_f32_16x16x32_bf16 v[52:55], v[200:203], v[144:147], v[52:55]
	v_mfma_f32_16x16x32_bf16 v[44:47], v[208:211], v[144:147], v[44:47]
	v_mfma_f32_16x16x32_bf16 v[36:39], v[200:203], v[152:155], v[36:39]
	v_mfma_f32_16x16x32_bf16 v[32:35], v[208:211], v[152:155], v[32:35]
	v_mfma_f32_16x16x32_bf16 v[20:23], v[200:203], v[160:163], v[20:23]
	v_mfma_f32_16x16x32_bf16 v[12:15], v[208:211], v[160:163], v[12:15]
	v_mfma_f32_16x16x32_bf16 v[4:7], v[200:203], v[168:171], v[4:7]
	v_mfma_f32_16x16x32_bf16 v[0:3], v[208:211], v[168:171], v[0:3]
	v_mfma_f32_16x16x32_bf16 v[52:55], v[204:207], v[148:151], v[52:55]
	v_mfma_f32_16x16x32_bf16 v[44:47], v[220:223], v[148:151], v[44:47]
	v_mfma_f32_16x16x32_bf16 v[36:39], v[204:207], v[156:159], v[36:39]
	v_mfma_f32_16x16x32_bf16 v[32:35], v[220:223], v[156:159], v[32:35]
	v_mfma_f32_16x16x32_bf16 v[20:23], v[204:207], v[164:167], v[20:23]
	v_mfma_f32_16x16x32_bf16 v[12:15], v[220:223], v[164:167], v[12:15]
	v_mfma_f32_16x16x32_bf16 v[4:7], v[204:207], v[172:175], v[4:7]
	v_mfma_f32_16x16x32_bf16 v[0:3], v[220:223], v[172:175], v[0:3]
	s_setprio 0
	s_barrier
	s_add_u32 s45, s45, 0x100
	s_addc_u32 s47, s47, 0
	s_cmp_ge_i32 vcc_lo, s39
	s_mov_b64 s[56:57], s[58:59]
	s_mov_b32 s55, vcc_lo
	s_cbranch_scc0 .LBB0_3568
	s_branch .Lpeel_exit_5

;     __device__ __forceinline__ void operator()(AccRef acc, const pg8::Unit& u, int wr, int wc, int fr, int fq) const {
;         const int row0 = u.pm * 256 + wr * 64 + fr, col0 = u.pn * 256 + wc * 32 + 4 * fq;
;         const int v = u.pm < 32 ? (u.pm >> 3) : 4;
;         f32x4 gv[2][2];
; #pragma unroll
;         for (int bj = 0; bj < 2; ++bj)
; #pragma unroll
;             for (int n = 0; n < 2; ++n) gv[bj][n] = *(const f32x4*)(gate + (size_t)v * MODW + col0 + bj * 128 + n * 16) * coef;
;         const bool part = u.part != 0;
;         float* base = part ? PART + ((size_t)u.ks * NCTX - NLAT) * DM : X;
.Lpeel_exit_5:
	s_cmp_gt_i32 s38, 31
	s_mov_b64 s[56:57], 0x12000
	s_cbranch_scc1 .LBB0_3571
	s_ashr_i32 s14, s38, 3
	s_mul_hi_i32 s57, s14, 0x4800
	s_mul_i32 s56, s14, 0x4800

; #define PG8_STAGE(bufoff, gbase, voff) do { _Pragma("unroll") for (int _i = 0; _i < 2; ++_i) \
;         __builtin_amdgcn_global_load_lds((const unsigned*)((const char*)(gbase) + (voff)[_i]), (LAS unsigned*)(lds + (bufoff) + ldsw + _i * 8192), 16, 0, 0); } while (0)
; #define PG8_LDA(dst, b, h) do { _Pragma("unroll") for (int m = 0; m < 4; ++m) _Pragma("unroll") for (int k = 0; k < 2; ++k) dst[m][k] = *(const LAS bf16x8*)(lds + PG8_SA(b, h) + aoff + m * 2048 + k * 1024); } while (0)
; #define PG8_LDB(dst, b, h) do { _Pragma("unroll") for (int n = 0; n < 2; ++n) _Pragma("unroll") for (int k = 0; k < 2; ++k) dst[n][k] = *(const LAS bf16x8*)(lds + PG8_SB(b, h) + boff + n * 2048 + k * 1024); } while (0)
; #define PG8_MMA(ai, bj, At, Bt) do { __builtin_amdgcn_s_setprio(1); _Pragma("unroll") for (int m = 0; m < 4; ++m) _Pragma("unroll") for (int n = 0; n < 2; ++n) _Pragma("unroll") for (int k = 0; k < 2; ++k) \
;         acc[ai][bj][m][n] = __builtin_amdgcn_mfma_f32_16x16x32_bf16(Bt[n][k], At[m][k], acc[ai][bj][m][n], 0, 0, 0); __builtin_amdgcn_s_setprio(0); } while (0)
; template <class Epi>
; __device__ __forceinline__ void gemm_phase(LAS unsigned char* lds, const Gemm g, const StaticOrder S, const Epi E) {
;     ...
;         const bool has_next = S.next(ui + 1, nxt);
;         const char* nA = has_next ? (const char*)g.A + (size_t)nxt.pm * tstep + (size_t)nxt.k0 * kstep : cA; const char* nB = has_next ? (const char*)g.Bt + (size_t)nxt.pn * tstep + (size_t)nxt.k0 * kstep : cB;
;         const int nt = cur.nk;
;         for (int t = 0; t < nt; t += 2) {
;             const bool last = (t == nt - 2);
;             const char* a1 = cA + (size_t)(t + 1) * kstep;
;             const char* a2 = last ? nA : cA + (size_t)(t + 2) * kstep; const char* b2 = last ? nB : cB + (size_t)(t + 2) * kstep;
;             const char* a3 = a2 + kstep; const char* b3 = b2 + kstep;
;             PG8_LDB(B0, 0, 0); PG8_SCHED; PG8_LDA(At, 0, 0); PG8_STAGE(PG8_SA(1, 1), a1 + hstep, voffA);
;             PG8_WAIT_L(8); PG8_BAR; PG8_WAIT_L(0); PG8_MMA(0, 0, At, B0); PG8_BAR; PG8_SCHED;
;             PG8_LDB(B1, 0, 1); PG8_STAGE(PG8_SB(0, 0), b2, voffA);
;             PG8_BAR; PG8_WAIT_L(0); PG8_MMA(0, 1, At, B1); PG8_BAR;
;             PG8_LDA(At, 0, 1); PG8_STAGE(PG8_SA(0, 0), a2, voffA);
;             PG8_BAR; PG8_WAIT_L(0); PG8_MMA(1, 0, At, B0); PG8_BAR; PG8_SCHED;
.LBB0_3722:
	s_ashr_i32 s3, s2, 31
	v_mov_b64_e32 v[0:1], s[4:5]
	s_lshl_b64 s[26:27], s[2:3], 20
	v_readlane_b32 s1, v255, 1
	v_cmp_lt_i64_e32 vcc, s[42:43], v[0:1]
	s_add_u32 s42, s1, s26
	v_readlane_b32 s1, v255, 2
	s_addc_u32 s43, s1, s27
	s_and_b64 s[26:27], vcc, exec
	s_cselect_b32 s3, s43, s51
	s_cselect_b32 s26, s42, s50
	s_ashr_i32 s1, s0, 31
	s_lshl_b64 s[28:29], s[0:1], 20
	s_add_u32 s44, s56, s28
	s_addc_u32 s45, s57, s29
	s_and_b64 s[28:29], vcc, exec
	s_cselect_b32 s1, s45, s53
	s_cselect_b32 s27, s44, s52
	s_add_u32 s50, s50, 0x80080
	s_addc_u32 s51, s51, 0
	s_add_u32 s28, s52, 0x100
	s_addc_u32 s29, s53, 0
	s_mov_b32 s64, -2
	s_add_u32 s14, s50, 0xfff80080
	s_addc_u32 s30, s51, -1
	s_add_i32 s31, 0, 0x10000
	v_add_u32_e32 v134, s31, v137
	ds_read_b128 v[140:143], v134
	ds_read_b128 v[144:147], v134 offset:1024
	ds_read_b128 v[148:151], v134 offset:2048
	ds_read_b128 v[152:155], v134 offset:3072
	s_cmp_eq_u32 s64, 28
	s_cselect_b32 s55, s3, s30
	s_cselect_b32 s54, s26, s14
	s_cselect_b32 s53, s1, s29
	s_cselect_b32 s52, s27, s28
	v_lshl_add_u64 v[134:135], s[50:51], 0, v[130:131]
	s_add_i32 m0, s47, 0xc000
	ds_read_b128 v[156:159], v139
	ds_read_b128 v[160:163], v139 offset:1024
	ds_read_b128 v[164:167], v139 offset:2048
	ds_read_b128 v[168:171], v139 offset:3072
	ds_read_b128 v[172:175], v139 offset:4096
	ds_read_b128 v[194:197], v139 offset:5120
	ds_read_b128 v[198:201], v139 offset:6144
	ds_read_b128 v[202:205], v139 offset:7168
	global_load_lds_dwordx4 v[134:135], off
	v_lshl_add_u64 v[134:135], s[50:51], 0, v[132:133]
	s_add_i32 m0, s47, 0xe000
	s_nop 0
	global_load_lds_dwordx4 v[134:135], off
	s_waitcnt lgkmcnt(8)
	s_barrier
	s_waitcnt lgkmcnt(0)
	s_setprio 1
	v_mfma_f32_16x16x32_bf16 v[120:123], v[140:143], v[156:159], 0
	v_mfma_f32_16x16x32_bf16 v[124:127], v[148:151], v[156:159], 0
	v_mfma_f32_16x16x32_bf16 v[104:107], v[140:143], v[164:167], 0
	v_mfma_f32_16x16x32_bf16 v[108:111], v[148:151], v[164:167], 0
	v_mfma_f32_16x16x32_bf16 v[88:91], v[140:143], v[172:175], 0
	v_mfma_f32_16x16x32_bf16 v[92:95], v[148:151], v[172:175], 0
	v_mfma_f32_16x16x32_bf16 v[72:75], v[140:143], v[198:201], 0
	v_mfma_f32_16x16x32_bf16 v[76:79], v[148:151], v[198:201], 0
	v_mfma_f32_16x16x32_bf16 v[120:123], v[144:147], v[160:163], v[120:123]
	v_mfma_f32_16x16x32_bf16 v[124:127], v[152:155], v[160:163], v[124:127]
	v_mfma_f32_16x16x32_bf16 v[104:107], v[144:147], v[168:171], v[104:107]
	v_mfma_f32_16x16x32_bf16 v[108:111], v[152:155], v[168:171], v[108:111]
	v_mfma_f32_16x16x32_bf16 v[88:91], v[144:147], v[194:197], v[88:91]
	v_mfma_f32_16x16x32_bf16 v[92:95], v[152:155], v[194:197], v[92:95]
	v_mfma_f32_16x16x32_bf16 v[72:75], v[144:147], v[202:205], v[72:75]
	v_mfma_f32_16x16x32_bf16 v[76:79], v[152:155], v[202:205], v[76:79]
	s_setprio 0
	s_barrier
	s_add_i32 s14, 0, 0x14000
	v_add_u32_e32 v134, s14, v137
	s_add_i32 s30, s31, s58
	ds_read_b128 v[206:209], v134
	ds_read_b128 v[220:223], v134 offset:1024
	ds_read_b128 v[228:231], v134 offset:2048
	ds_read_b128 v[232:235], v134 offset:3072
	v_lshl_add_u64 v[134:135], s[52:53], 0, v[178:179]
	s_mov_b32 m0, s30
	v_lshl_add_u64 v[210:211], s[52:53], 0, v[128:129]
	global_load_lds_dwordx4 v[134:135], off
	s_add_i32 m0, s30, 0x2000
	s_nop 0
	global_load_lds_dwordx4 v[210:211], off
	s_barrier
	s_waitcnt lgkmcnt(0)
	s_setprio 1
	v_mfma_f32_16x16x32_bf16 v[112:115], v[206:209], v[156:159], 0
	v_mfma_f32_16x16x32_bf16 v[116:119], v[228:231], v[156:159], 0
	v_mfma_f32_16x16x32_bf16 v[96:99], v[206:209], v[164:167], 0
	v_mfma_f32_16x16x32_bf16 v[100:103], v[228:231], v[164:167], 0
	v_mfma_f32_16x16x32_bf16 v[80:83], v[206:209], v[172:175], 0
	v_mfma_f32_16x16x32_bf16 v[84:87], v[228:231], v[172:175], 0
	v_mfma_f32_16x16x32_bf16 v[64:67], v[206:209], v[198:201], 0
	v_mfma_f32_16x16x32_bf16 v[68:71], v[228:231], v[198:201], 0
	v_mfma_f32_16x16x32_bf16 v[112:115], v[220:223], v[160:163], v[112:115]
	v_mfma_f32_16x16x32_bf16 v[116:119], v[232:235], v[160:163], v[116:119]
	v_mfma_f32_16x16x32_bf16 v[96:99], v[220:223], v[168:171], v[96:99]
	v_mfma_f32_16x16x32_bf16 v[100:103], v[232:235], v[168:171], v[100:103]
	v_mfma_f32_16x16x32_bf16 v[80:83], v[220:223], v[194:197], v[80:83]
	v_mfma_f32_16x16x32_bf16 v[84:87], v[232:235], v[194:197], v[84:87]
	v_mfma_f32_16x16x32_bf16 v[64:67], v[220:223], v[202:205], v[64:67]
	v_mfma_f32_16x16x32_bf16 v[68:71], v[232:235], v[202:205], v[68:71]
	s_setprio 0
	s_barrier
	s_mov_b32 m0, s47
	v_lshl_add_u64 v[236:237], s[54:55], 0, v[178:179]
	ds_read_b128 v[156:159], v139 offset:16384
	ds_read_b128 v[160:163], v139 offset:17408
	ds_read_b128 v[164:167], v139 offset:18432
	ds_read_b128 v[168:171], v139 offset:19456
	ds_read_b128 v[172:175], v139 offset:20480
	ds_read_b128 v[194:197], v139 offset:21504
	ds_read_b128 v[198:201], v139 offset:22528
	ds_read_b128 v[202:205], v139 offset:23552
	global_load_lds_dwordx4 v[236:237], off
	v_lshl_add_u64 v[238:239], s[54:55], 0, v[128:129]
	s_mov_b32 m0, s49
	s_nop 0
	global_load_lds_dwordx4 v[238:239], off
	s_barrier
	s_waitcnt lgkmcnt(0)
	s_setprio 1
	v_mfma_f32_16x16x32_bf16 v[56:59], v[140:143], v[156:159], 0
	v_mfma_f32_16x16x32_bf16 v[60:63], v[148:151], v[156:159], 0
	v_mfma_f32_16x16x32_bf16 v[40:43], v[140:143], v[164:167], 0
	v_mfma_f32_16x16x32_bf16 v[44:47], v[148:151], v[164:167], 0
	v_mfma_f32_16x16x32_bf16 v[24:27], v[140:143], v[172:175], 0
	v_mfma_f32_16x16x32_bf16 v[28:31], v[148:151], v[172:175], 0
	v_mfma_f32_16x16x32_bf16 v[8:11], v[140:143], v[198:201], 0
	v_mfma_f32_16x16x32_bf16 v[12:15], v[148:151], v[198:201], 0
	v_mfma_f32_16x16x32_bf16 v[56:59], v[144:147], v[160:163], v[56:59]
	v_mfma_f32_16x16x32_bf16 v[60:63], v[152:155], v[160:163], v[60:63]
	v_mfma_f32_16x16x32_bf16 v[40:43], v[144:147], v[168:171], v[40:43]
	v_mfma_f32_16x16x32_bf16 v[44:47], v[152:155], v[168:171], v[44:47]
	v_mfma_f32_16x16x32_bf16 v[24:27], v[144:147], v[194:197], v[24:27]
	v_mfma_f32_16x16x32_bf16 v[28:31], v[152:155], v[194:197], v[28:31]
	v_mfma_f32_16x16x32_bf16 v[8:11], v[144:147], v[202:205], v[8:11]
	v_mfma_f32_16x16x32_bf16 v[12:15], v[152:155], v[202:205], v[12:15]
	s_setprio 0
	s_barrier
; #define PG8_STAGE(bufoff, gbase, voff) do { _Pragma("unroll") for (int _i = 0; _i < 2; ++_i) \
;         __builtin_amdgcn_global_load_lds((const unsigned*)((const char*)(gbase) + (voff)[_i]), (LAS unsigned*)(lds + (bufoff) + ldsw + _i * 8192), 16, 0, 0); } while (0)
; #define PG8_LDA(dst, b, h) do { _Pragma("unroll") for (int m = 0; m < 4; ++m) _Pragma("unroll") for (int k = 0; k < 2; ++k) dst[m][k] = *(const LAS bf16x8*)(lds + PG8_SA(b, h) + aoff + m * 2048 + k * 1024); } while (0)
; #define PG8_LDB(dst, b, h) do { _Pragma("unroll") for (int n = 0; n < 2; ++n) _Pragma("unroll") for (int k = 0; k < 2; ++k) dst[n][k] = *(const LAS bf16x8*)(lds + PG8_SB(b, h) + boff + n * 2048 + k * 1024); } while (0)
; #define PG8_MMA(ai, bj, At, Bt) do { __builtin_amdgcn_s_setprio(1); _Pragma("unroll") for (int m = 0; m < 4; ++m) _Pragma("unroll") for (int n = 0; n < 2; ++n) _Pragma("unroll") for (int k = 0; k < 2; ++k) \
;         acc[ai][bj][m][n] = __builtin_amdgcn_mfma_f32_16x16x32_bf16(Bt[n][k], At[m][k], acc[ai][bj][m][n], 0, 0, 0); __builtin_amdgcn_s_setprio(0); } while (0)
; #define PG8_WAIT_V(n) asm volatile("s_waitcnt vmcnt(" #n ")" ::: "memory")
; #define PG8_WAIT_L(n) asm volatile("s_waitcnt lgkmcnt(" #n ")" ::: "memory")
; #define PG8_BAR __builtin_amdgcn_s_barrier()
; #define PG8_SCHED __builtin_amdgcn_sched_barrier(0)
; template <class Epi>
; __device__ __forceinline__ void gemm_phase(LAS unsigned char* lds, const Gemm g, const StaticOrder S, const Epi E) {
;     ...
;             PG8_STAGE(PG8_SB(0, 1), b2 + hstep, voffA);
;             PG8_WAIT_V(6); PG8_BAR; PG8_MMA(1, 1, At, B1); PG8_BAR;
;             PG8_LDB(B0, 1, 0); PG8_SCHED; PG8_LDA(At, 1, 0); PG8_STAGE(PG8_SA(0, 1), a2 + hstep, voffA);
;             PG8_WAIT_L(8); PG8_BAR; PG8_WAIT_L(0); PG8_MMA(0, 0, At, B0); PG8_BAR; PG8_SCHED;
;             PG8_LDB(B1, 1, 1); PG8_STAGE(PG8_SB(1, 0), b3, voffA);
;             PG8_BAR; PG8_WAIT_L(0); PG8_MMA(0, 1, At, B1); PG8_BAR;
;             PG8_LDA(At, 1, 1); PG8_STAGE(PG8_SA(1, 0), a3, voffA);
	s_add_u32 s30, s52, 0x80000
	s_addc_u32 s31, s53, 0
	s_add_i32 s14, s14, s58
	v_lshl_add_u64 v[140:141], s[30:31], 0, v[178:179]
	s_mov_b32 m0, s14
	s_nop 0
	global_load_lds_dwordx4 v[140:141], off
	v_lshl_add_u64 v[140:141], s[30:31], 0, v[128:129]
	s_add_i32 m0, s14, 0x2000
	s_nop 0
	global_load_lds_dwordx4 v[140:141], off
	s_waitcnt vmcnt(6)
	s_barrier
	s_setprio 1
	v_mfma_f32_16x16x32_bf16 v[48:51], v[206:209], v[156:159], 0
	v_mfma_f32_16x16x32_bf16 v[52:55], v[228:231], v[156:159], 0
	v_mfma_f32_16x16x32_bf16 v[32:35], v[206:209], v[164:167], 0
	v_mfma_f32_16x16x32_bf16 v[36:39], v[228:231], v[164:167], 0
	v_mfma_f32_16x16x32_bf16 v[16:19], v[206:209], v[172:175], 0
	v_mfma_f32_16x16x32_bf16 v[20:23], v[228:231], v[172:175], 0
	v_mfma_f32_16x16x32_bf16 v[0:3], v[206:209], v[198:201], 0
	v_mfma_f32_16x16x32_bf16 v[4:7], v[228:231], v[198:201], 0
	v_mfma_f32_16x16x32_bf16 v[48:51], v[220:223], v[160:163], v[48:51]
	v_mfma_f32_16x16x32_bf16 v[52:55], v[232:235], v[160:163], v[52:55]
	v_mfma_f32_16x16x32_bf16 v[32:35], v[220:223], v[168:171], v[32:35]
	v_mfma_f32_16x16x32_bf16 v[36:39], v[232:235], v[168:171], v[36:39]
	v_mfma_f32_16x16x32_bf16 v[16:19], v[220:223], v[194:197], v[16:19]
	v_mfma_f32_16x16x32_bf16 v[20:23], v[232:235], v[194:197], v[20:23]
	v_mfma_f32_16x16x32_bf16 v[0:3], v[220:223], v[202:205], v[0:3]
	v_mfma_f32_16x16x32_bf16 v[4:7], v[232:235], v[202:205], v[4:7]
	s_setprio 0
	s_barrier
	s_add_i32 s14, 0, 0x18000
	v_add_u32_e32 v152, s14, v137
	ds_read_b128 v[140:143], v152
	ds_read_b128 v[144:147], v152 offset:1024
	ds_read_b128 v[148:151], v152 offset:2048
	ds_read_b128 v[152:155], v152 offset:3072
	s_add_u32 s30, s54, 0x80000
	s_addc_u32 s31, s55, 0
	s_mov_b32 m0, s59
	v_lshl_add_u64 v[206:207], s[30:31], 0, v[178:179]
	ds_read_b128 v[156:159], v139 offset:32768
	ds_read_b128 v[160:163], v139 offset:33792
	ds_read_b128 v[164:167], v139 offset:34816
	ds_read_b128 v[168:171], v139 offset:35840
	ds_read_b128 v[172:175], v139 offset:36864
	ds_read_b128 v[194:197], v139 offset:37888
	ds_read_b128 v[198:201], v139 offset:38912
	ds_read_b128 v[202:205], v139 offset:39936
	global_load_lds_dwordx4 v[206:207], off
	v_lshl_add_u64 v[206:207], s[30:31], 0, v[128:129]
	s_mov_b32 m0, s60
	s_nop 0
	global_load_lds_dwordx4 v[206:207], off
	s_waitcnt lgkmcnt(8)
	s_barrier
	s_waitcnt lgkmcnt(0)
	s_setprio 1
	v_mfma_f32_16x16x32_bf16 v[120:123], v[140:143], v[156:159], v[120:123]
	v_mfma_f32_16x16x32_bf16 v[124:127], v[148:151], v[156:159], v[124:127]
	v_mfma_f32_16x16x32_bf16 v[104:107], v[140:143], v[164:167], v[104:107]
	v_mfma_f32_16x16x32_bf16 v[108:111], v[148:151], v[164:167], v[108:111]
	v_mfma_f32_16x16x32_bf16 v[88:91], v[140:143], v[172:175], v[88:91]
	v_mfma_f32_16x16x32_bf16 v[92:95], v[148:151], v[172:175], v[92:95]
	v_mfma_f32_16x16x32_bf16 v[72:75], v[140:143], v[198:201], v[72:75]
	v_mfma_f32_16x16x32_bf16 v[76:79], v[148:151], v[198:201], v[76:79]
	v_mfma_f32_16x16x32_bf16 v[120:123], v[144:147], v[160:163], v[120:123]
	v_mfma_f32_16x16x32_bf16 v[124:127], v[152:155], v[160:163], v[124:127]
	v_mfma_f32_16x16x32_bf16 v[104:107], v[144:147], v[168:171], v[104:107]
	v_mfma_f32_16x16x32_bf16 v[108:111], v[152:155], v[168:171], v[108:111]
	v_mfma_f32_16x16x32_bf16 v[88:91], v[144:147], v[194:197], v[88:91]
	v_mfma_f32_16x16x32_bf16 v[92:95], v[152:155], v[194:197], v[92:95]
	v_mfma_f32_16x16x32_bf16 v[72:75], v[144:147], v[202:205], v[72:75]
	v_mfma_f32_16x16x32_bf16 v[76:79], v[152:155], v[202:205], v[76:79]
	s_setprio 0
	s_barrier
	s_add_i32 s54, 0, 0x1c000
	s_add_i32 s14, s14, s58
	v_add_u32_e32 v227, s54, v137
	v_lshl_add_u64 v[134:135], v[134:135], 0, s[34:35]
	s_mov_b32 m0, s14
	ds_read_b128 v[206:209], v227
	ds_read_b128 v[220:223], v227 offset:1024
	ds_read_b128 v[228:231], v227 offset:2048
	ds_read_b128 v[232:235], v227 offset:3072
	global_load_lds_dwordx4 v[134:135], off
	v_lshl_add_u64 v[134:135], v[210:211], 0, s[34:35]
	s_add_i32 m0, s14, 0x2000
	s_nop 0
	global_load_lds_dwordx4 v[134:135], off
	s_barrier
; #define PG8_STAGE(bufoff, gbase, voff) do { _Pragma("unroll") for (int _i = 0; _i < 2; ++_i) \
;         __builtin_amdgcn_global_load_lds((const unsigned*)((const char*)(gbase) + (voff)[_i]), (LAS unsigned*)(lds + (bufoff) + ldsw + _i * 8192), 16, 0, 0); } while (0)
; #define PG8_LDA(dst, b, h) do { _Pragma("unroll") for (int m = 0; m < 4; ++m) _Pragma("unroll") for (int k = 0; k < 2; ++k) dst[m][k] = *(const LAS bf16x8*)(lds + PG8_SA(b, h) + aoff + m * 2048 + k * 1024); } while (0)
; #define PG8_MMA(ai, bj, At, Bt) do { __builtin_amdgcn_s_setprio(1); _Pragma("unroll") for (int m = 0; m < 4; ++m) _Pragma("unroll") for (int n = 0; n < 2; ++n) _Pragma("unroll") for (int k = 0; k < 2; ++k) \
;         acc[ai][bj][m][n] = __builtin_amdgcn_mfma_f32_16x16x32_bf16(Bt[n][k], At[m][k], acc[ai][bj][m][n], 0, 0, 0); __builtin_amdgcn_s_setprio(0); } while (0)
; #define PG8_WAIT_V(n) asm volatile("s_waitcnt vmcnt(" #n ")" ::: "memory")
; #define PG8_WAIT_L(n) asm volatile("s_waitcnt lgkmcnt(" #n ")" ::: "memory")
; #define PG8_BAR __builtin_amdgcn_s_barrier()
; #define PG8_SCHED __builtin_amdgcn_sched_barrier(0)
; template <class Epi>
; __device__ __forceinline__ void gemm_phase(LAS unsigned char* lds, const Gemm g, const StaticOrder S, const Epi E) {
;     ...
;         for (int t = 0; t < nt; t += 2) {
;     ...
;             PG8_LDA(At, 1, 1); PG8_STAGE(PG8_SA(1, 0), a3, voffA);
;             PG8_BAR; PG8_WAIT_L(0); PG8_MMA(1, 0, At, B0); PG8_BAR; PG8_SCHED;
;             PG8_STAGE(PG8_SB(1, 1), b3 + hstep, voffA);
;             PG8_WAIT_V(6); PG8_BAR; PG8_MMA(1, 1, At, B1); PG8_BAR;
;         }
	s_waitcnt lgkmcnt(0)
	s_setprio 1
	v_mfma_f32_16x16x32_bf16 v[112:115], v[206:209], v[156:159], v[112:115]
	v_mfma_f32_16x16x32_bf16 v[116:119], v[228:231], v[156:159], v[116:119]
	v_mfma_f32_16x16x32_bf16 v[96:99], v[206:209], v[164:167], v[96:99]
	v_mfma_f32_16x16x32_bf16 v[100:103], v[228:231], v[164:167], v[100:103]
	v_mfma_f32_16x16x32_bf16 v[80:83], v[206:209], v[172:175], v[80:83]
	v_mfma_f32_16x16x32_bf16 v[84:87], v[228:231], v[172:175], v[84:87]
	v_mfma_f32_16x16x32_bf16 v[64:67], v[206:209], v[198:201], v[64:67]
	v_mfma_f32_16x16x32_bf16 v[68:71], v[228:231], v[198:201], v[68:71]
	v_mfma_f32_16x16x32_bf16 v[112:115], v[220:223], v[160:163], v[112:115]
	v_mfma_f32_16x16x32_bf16 v[116:119], v[232:235], v[160:163], v[116:119]
	v_mfma_f32_16x16x32_bf16 v[96:99], v[220:223], v[168:171], v[96:99]
	v_mfma_f32_16x16x32_bf16 v[100:103], v[232:235], v[168:171], v[100:103]
	v_mfma_f32_16x16x32_bf16 v[80:83], v[220:223], v[194:197], v[80:83]
	v_mfma_f32_16x16x32_bf16 v[84:87], v[232:235], v[194:197], v[84:87]
	v_mfma_f32_16x16x32_bf16 v[64:67], v[220:223], v[202:205], v[64:67]
	v_mfma_f32_16x16x32_bf16 v[68:71], v[232:235], v[202:205], v[68:71]
	s_setprio 0
	s_barrier
	s_mov_b32 m0, s61
	v_lshl_add_u64 v[134:135], v[236:237], 0, s[34:35]
	ds_read_b128 v[156:159], v139 offset:49152
	ds_read_b128 v[160:163], v139 offset:50176
	ds_read_b128 v[164:167], v139 offset:51200
	ds_read_b128 v[168:171], v139 offset:52224
	ds_read_b128 v[172:175], v139 offset:53248
	ds_read_b128 v[194:197], v139 offset:54272
	ds_read_b128 v[198:201], v139 offset:55296
	ds_read_b128 v[202:205], v139 offset:56320
	global_load_lds_dwordx4 v[134:135], off
	v_lshl_add_u64 v[134:135], v[238:239], 0, s[34:35]
	s_mov_b32 m0, s62
	s_nop 0
	global_load_lds_dwordx4 v[134:135], off
	s_barrier
	s_waitcnt lgkmcnt(0)
	s_setprio 1
	v_mfma_f32_16x16x32_bf16 v[56:59], v[140:143], v[156:159], v[56:59]
	v_mfma_f32_16x16x32_bf16 v[60:63], v[148:151], v[156:159], v[60:63]
	v_mfma_f32_16x16x32_bf16 v[40:43], v[140:143], v[164:167], v[40:43]
	v_mfma_f32_16x16x32_bf16 v[44:47], v[148:151], v[164:167], v[44:47]
	v_mfma_f32_16x16x32_bf16 v[24:27], v[140:143], v[172:175], v[24:27]
	v_mfma_f32_16x16x32_bf16 v[28:31], v[148:151], v[172:175], v[28:31]
	v_mfma_f32_16x16x32_bf16 v[8:11], v[140:143], v[198:201], v[8:11]
	v_mfma_f32_16x16x32_bf16 v[12:15], v[148:151], v[198:201], v[12:15]
	v_mfma_f32_16x16x32_bf16 v[56:59], v[144:147], v[160:163], v[56:59]
	v_mfma_f32_16x16x32_bf16 v[60:63], v[152:155], v[160:163], v[60:63]
	v_mfma_f32_16x16x32_bf16 v[40:43], v[144:147], v[168:171], v[40:43]
	v_mfma_f32_16x16x32_bf16 v[44:47], v[152:155], v[168:171], v[44:47]
	v_mfma_f32_16x16x32_bf16 v[24:27], v[144:147], v[194:197], v[24:27]
	v_mfma_f32_16x16x32_bf16 v[28:31], v[152:155], v[194:197], v[28:31]
	v_mfma_f32_16x16x32_bf16 v[8:11], v[144:147], v[202:205], v[8:11]
	v_mfma_f32_16x16x32_bf16 v[12:15], v[152:155], v[202:205], v[12:15]
	s_setprio 0
	s_barrier
	s_add_u32 s30, s52, 0x80080
	s_addc_u32 s31, s53, 0
	s_add_i32 s14, s54, s58
	v_lshl_add_u64 v[134:135], s[30:31], 0, v[178:179]
	s_mov_b32 m0, s14
	s_nop 0
	global_load_lds_dwordx4 v[134:135], off
	v_lshl_add_u64 v[134:135], s[30:31], 0, v[128:129]
	s_add_i32 m0, s14, 0x2000
	s_nop 0
	global_load_lds_dwordx4 v[134:135], off
	s_waitcnt vmcnt(6)
	s_barrier
	s_setprio 1
	v_mfma_f32_16x16x32_bf16 v[48:51], v[206:209], v[156:159], v[48:51]
	v_mfma_f32_16x16x32_bf16 v[52:55], v[228:231], v[156:159], v[52:55]
	v_mfma_f32_16x16x32_bf16 v[32:35], v[206:209], v[164:167], v[32:35]
	v_mfma_f32_16x16x32_bf16 v[36:39], v[228:231], v[164:167], v[36:39]
	v_mfma_f32_16x16x32_bf16 v[16:19], v[206:209], v[172:175], v[16:19]
	v_mfma_f32_16x16x32_bf16 v[20:23], v[228:231], v[172:175], v[20:23]
	v_mfma_f32_16x16x32_bf16 v[0:3], v[206:209], v[198:201], v[0:3]
	v_mfma_f32_16x16x32_bf16 v[4:7], v[228:231], v[198:201], v[4:7]
	v_mfma_f32_16x16x32_bf16 v[48:51], v[220:223], v[160:163], v[48:51]
	v_mfma_f32_16x16x32_bf16 v[52:55], v[232:235], v[160:163], v[52:55]
	v_mfma_f32_16x16x32_bf16 v[32:35], v[220:223], v[168:171], v[32:35]
	v_mfma_f32_16x16x32_bf16 v[36:39], v[232:235], v[168:171], v[36:39]
	v_mfma_f32_16x16x32_bf16 v[16:19], v[220:223], v[194:197], v[16:19]
	v_mfma_f32_16x16x32_bf16 v[20:23], v[232:235], v[194:197], v[20:23]
	v_mfma_f32_16x16x32_bf16 v[0:3], v[220:223], v[202:205], v[0:3]
	v_mfma_f32_16x16x32_bf16 v[4:7], v[232:235], v[202:205], v[4:7]
	s_setprio 0
	s_barrier
	s_add_i32 s64, s64, 2
	s_add_u32 s50, s50, 0x100
	s_addc_u32 s51, s51, 0
	s_add_u32 s28, s28, 0x100
	s_addc_u32 s29, s29, 0
	s_cmp_gt_u32 s64, 29
	s_cbranch_scc0 .LBB0_3723
	s_branch .Lpeel_exit_6

; __device__ __forceinline__ unsigned cvt_pk_bf16(float lo, float hi) { unsigned r; asm("v_cvt_pk_bf16_f32 %0, %1, %2" : "=v"(r) : "v"(lo), "v"(hi)); return r; }
;     __device__ __forceinline__ void operator()(AccRef acc, const pg8::Unit& u, int wr, int wc, int fr, int fq) const {
;     ...
;             for (int m = 0; m < 4; ++m) { bf16_t* rowp = G + (size_t)(row0 + ai * 128 + m * 16) * FH + col0;
; #pragma unroll
;                 for (int bj = 0; bj < 2; ++bj) { const f32x4 gq = acc[ai][bj][m][0], uq = acc[ai][bj][m][1]; float v[4];
; #pragma unroll
;                     for (int i = 0; i < 4; ++i) v[i] = gq[i] * uq[i] * __builtin_amdgcn_rcpf(1.f + __builtin_amdgcn_exp2f(-gq[i] * LOG2E));
;                     u32x2 w; w.x = cvt_pk_bf16(v[0], v[1]); w.y = cvt_pk_bf16(v[2], v[3]);
;                     *(u32x2*)(rowp + bj * 64) = w; } }
.Lpeel_exit_6:
	v_mul_f32_e32 v116, v116, v112
	v_mul_f32_e32 v112, 0xbfb8aa3b, v112
	v_exp_f32_e32 v112, v112
	v_mul_f32_e32 v100, v100, v96
	v_mul_f32_e32 v96, 0xbfb8aa3b, v96
	v_exp_f32_e32 v96, v96
	v_mul_f32_e32 v84, v84, v80
	v_mul_f32_e32 v80, 0xbfb8aa3b, v80
	v_add_f32_e32 v112, 1.0, v112
	v_exp_f32_e32 v80, v80
	v_rcp_f32_e32 v112, v112
	v_mul_f32_e32 v68, v68, v64
	v_mul_f32_e32 v64, 0xbfb8aa3b, v64
	v_add_f32_e32 v96, 1.0, v96
	v_exp_f32_e32 v64, v64
	v_rcp_f32_e32 v96, v96
	v_mul_f32_e32 v52, v52, v48
	v_mul_f32_e32 v48, 0xbfb8aa3b, v48
	v_add_f32_e32 v80, 1.0, v80
	v_exp_f32_e32 v48, v48
	v_mul_f32_e32 v112, v116, v112
	v_mul_f32_e32 v116, v117, v113
	v_mul_f32_e32 v113, 0xbfb8aa3b, v113
	v_rcp_f32_e32 v80, v80
	v_mul_f32_e32 v36, v36, v32
	v_mul_f32_e32 v32, 0xbfb8aa3b, v32
	v_exp_f32_e32 v113, v113
	v_add_f32_e32 v64, 1.0, v64
	v_exp_f32_e32 v32, v32
	v_mul_f32_e32 v96, v100, v96
	v_mul_f32_e32 v100, v101, v97
	v_mul_f32_e32 v97, 0xbfb8aa3b, v97
	v_rcp_f32_e32 v64, v64
	v_mul_f32_e32 v20, v20, v16
	v_mul_f32_e32 v16, 0xbfb8aa3b, v16
	v_exp_f32_e32 v97, v97
	v_add_f32_e32 v48, 1.0, v48
	v_exp_f32_e32 v16, v16
	v_mul_f32_e32 v124, v124, v120
	v_mul_f32_e32 v120, 0xbfb8aa3b, v120
	v_mul_f32_e32 v108, v108, v104
	v_mul_f32_e32 v104, 0xbfb8aa3b, v104
	v_mul_f32_e32 v92, v92, v88
	v_mul_f32_e32 v88, 0xbfb8aa3b, v88
	v_mul_f32_e32 v80, v84, v80
	v_mul_f32_e32 v84, v85, v81
	v_mul_f32_e32 v81, 0xbfb8aa3b, v81
	v_mul_f32_e32 v76, v76, v72
	v_mul_f32_e32 v72, 0xbfb8aa3b, v72
	v_mul_f32_e32 v60, v60, v56
	v_mul_f32_e32 v56, 0xbfb8aa3b, v56
	v_rcp_f32_e32 v48, v48
	v_mul_f32_e32 v44, v44, v40
	v_mul_f32_e32 v40, 0xbfb8aa3b, v40
	v_mul_f32_e32 v28, v28, v24
	v_mul_f32_e32 v24, 0xbfb8aa3b, v24
	v_mul_f32_e32 v12, v12, v8
	v_mul_f32_e32 v8, 0xbfb8aa3b, v8
	v_mul_f32_e32 v4, v4, v0
	v_mul_f32_e32 v0, 0xbfb8aa3b, v0
	v_exp_f32_e32 v120, v120
	v_add_f32_e32 v113, 1.0, v113
	v_exp_f32_e32 v104, v104
	v_exp_f32_e32 v88, v88
	v_exp_f32_e32 v81, v81
	v_exp_f32_e32 v72, v72
	v_exp_f32_e32 v56, v56
	v_exp_f32_e32 v40, v40
	v_add_f32_e32 v32, 1.0, v32
	v_exp_f32_e32 v24, v24
	v_exp_f32_e32 v8, v8
	v_exp_f32_e32 v0, v0
	v_rcp_f32_e32 v113, v113
	v_mul_f32_e32 v64, v68, v64
	v_mul_f32_e32 v68, v69, v65
	v_mul_f32_e32 v65, 0xbfb8aa3b, v65
	v_rcp_f32_e32 v32, v32
	v_add_f32_e32 v97, 1.0, v97
	v_exp_f32_e32 v65, v65
	v_add_f32_e32 v16, 1.0, v16
	v_rcp_f32_e32 v97, v97
	v_mul_f32_e32 v48, v52, v48
	v_mul_f32_e32 v52, v53, v49
	v_mul_f32_e32 v49, 0xbfb8aa3b, v49
	v_rcp_f32_e32 v16, v16
	v_add_f32_e32 v120, 1.0, v120
	v_add_f32_e32 v104, 1.0, v104
	v_add_f32_e32 v88, 1.0, v88
	v_add_f32_e32 v81, 1.0, v81
	v_add_f32_e32 v72, 1.0, v72
	v_add_f32_e32 v56, 1.0, v56
	v_exp_f32_e32 v49, v49
	v_add_f32_e32 v40, 1.0, v40
	v_add_f32_e32 v24, 1.0, v24
	v_add_f32_e32 v8, 1.0, v8
	v_add_f32_e32 v0, 1.0, v0
	v_rcp_f32_e32 v120, v120
	v_mul_f32_e32 v113, v116, v113
	v_mul_f32_e32 v116, v118, v114
	v_mul_f32_e32 v114, 0xbfb8aa3b, v114
	v_rcp_f32_e32 v104, v104
	v_rcp_f32_e32 v88, v88
	v_rcp_f32_e32 v81, v81
	v_rcp_f32_e32 v72, v72
	v_rcp_f32_e32 v56, v56
	v_rcp_f32_e32 v40, v40
	v_mul_f32_e32 v32, v36, v32
	v_mul_f32_e32 v36, v37, v33
	v_mul_f32_e32 v33, 0xbfb8aa3b, v33
	v_rcp_f32_e32 v24, v24
	v_rcp_f32_e32 v8, v8
	v_rcp_f32_e32 v0, v0
	v_exp_f32_e32 v114, v114
	v_add_f32_e32 v65, 1.0, v65
	v_exp_f32_e32 v33, v33
	v_mul_f32_e32 v97, v100, v97
	v_mul_f32_e32 v100, v102, v98
	v_mul_f32_e32 v98, 0xbfb8aa3b, v98
	v_rcp_f32_e32 v65, v65
	v_mul_f32_e32 v16, v20, v16
	v_mul_f32_e32 v20, v21, v17
	v_mul_f32_e32 v17, 0xbfb8aa3b, v17
	v_exp_f32_e32 v98, v98
	v_add_f32_e32 v49, 1.0, v49
	v_exp_f32_e32 v17, v17
	v_mul_f32_e32 v120, v124, v120
	v_mul_f32_e32 v124, v125, v121
	v_mul_f32_e32 v121, 0xbfb8aa3b, v121
	v_mul_f32_e32 v104, v108, v104
	v_mul_f32_e32 v108, v109, v105
	v_mul_f32_e32 v105, 0xbfb8aa3b, v105
	v_mul_f32_e32 v88, v92, v88
	v_mul_f32_e32 v92, v93, v89
	v_mul_f32_e32 v89, 0xbfb8aa3b, v89
	v_mul_f32_e32 v81, v84, v81
	v_mul_f32_e32 v84, v86, v82
	v_mul_f32_e32 v82, 0xbfb8aa3b, v82
	v_mul_f32_e32 v72, v76, v72
	v_mul_f32_e32 v76, v77, v73
	v_mul_f32_e32 v73, 0xbfb8aa3b, v73
	v_mul_f32_e32 v56, v60, v56
	v_mul_f32_e32 v60, v61, v57
	v_mul_f32_e32 v57, 0xbfb8aa3b, v57
	v_rcp_f32_e32 v49, v49
	v_mul_f32_e32 v40, v44, v40
	v_mul_f32_e32 v44, v45, v41
	v_mul_f32_e32 v41, 0xbfb8aa3b, v41
	v_mul_f32_e32 v24, v28, v24
	v_mul_f32_e32 v28, v29, v25
	v_mul_f32_e32 v25, 0xbfb8aa3b, v25
	v_mul_f32_e32 v8, v12, v8
	v_mul_f32_e32 v12, v13, v9
	v_mul_f32_e32 v9, 0xbfb8aa3b, v9
	v_mul_f32_e32 v0, v4, v0
	v_mul_f32_e32 v4, v5, v1
	v_mul_f32_e32 v1, 0xbfb8aa3b, v1
	v_exp_f32_e32 v121, v121
	v_add_f32_e32 v114, 1.0, v114
	v_exp_f32_e32 v105, v105
	v_exp_f32_e32 v89, v89
	v_exp_f32_e32 v82, v82
	v_exp_f32_e32 v73, v73
	v_exp_f32_e32 v57, v57
	v_exp_f32_e32 v41, v41
	v_add_f32_e32 v33, 1.0, v33
	v_exp_f32_e32 v25, v25
	v_exp_f32_e32 v9, v9
	v_exp_f32_e32 v1, v1
	v_rcp_f32_e32 v114, v114
	v_mul_f32_e32 v65, v68, v65
	v_mul_f32_e32 v68, v70, v66
	v_mul_f32_e32 v66, 0xbfb8aa3b, v66
	v_rcp_f32_e32 v33, v33
	v_add_f32_e32 v98, 1.0, v98
	v_exp_f32_e32 v66, v66
	v_add_f32_e32 v17, 1.0, v17
	v_rcp_f32_e32 v98, v98
	v_mul_f32_e32 v49, v52, v49
	v_mul_f32_e32 v52, v54, v50
	v_mul_f32_e32 v50, 0xbfb8aa3b, v50
	v_rcp_f32_e32 v17, v17
	v_add_f32_e32 v121, 1.0, v121
	v_add_f32_e32 v105, 1.0, v105
	v_add_f32_e32 v89, 1.0, v89
	v_add_f32_e32 v82, 1.0, v82
	v_add_f32_e32 v73, 1.0, v73
	v_add_f32_e32 v57, 1.0, v57
	v_exp_f32_e32 v50, v50
	v_add_f32_e32 v41, 1.0, v41
	v_add_f32_e32 v25, 1.0, v25
	v_add_f32_e32 v9, 1.0, v9
	v_add_f32_e32 v1, 1.0, v1
	v_rcp_f32_e32 v121, v121
	v_mul_f32_e32 v114, v116, v114
; __device__ __forceinline__ unsigned cvt_pk_bf16(float lo, float hi) { unsigned r; asm("v_cvt_pk_bf16_f32 %0, %1, %2" : "=v"(r) : "v"(lo), "v"(hi)); return r; }
;     __device__ __forceinline__ void operator()(AccRef acc, const pg8::Unit& u, int wr, int wc, int fr, int fq) const {
;     ...
;             for (int m = 0; m < 4; ++m) { bf16_t* rowp = G + (size_t)(row0 + ai * 128 + m * 16) * FH + col0;
; #pragma unroll
;                 for (int bj = 0; bj < 2; ++bj) { const f32x4 gq = acc[ai][bj][m][0], uq = acc[ai][bj][m][1]; float v[4];
; #pragma unroll
;                     for (int i = 0; i < 4; ++i) v[i] = gq[i] * uq[i] * __builtin_amdgcn_rcpf(1.f + __builtin_amdgcn_exp2f(-gq[i] * LOG2E));
;                     u32x2 w; w.x = cvt_pk_bf16(v[0], v[1]); w.y = cvt_pk_bf16(v[2], v[3]);
;                     *(u32x2*)(rowp + bj * 64) = w; } }
	v_mul_f32_e32 v116, v119, v115
	v_mul_f32_e32 v115, 0xbfb8aa3b, v115
	v_rcp_f32_e32 v105, v105
	v_rcp_f32_e32 v89, v89
	v_rcp_f32_e32 v82, v82
	v_rcp_f32_e32 v73, v73
	v_rcp_f32_e32 v57, v57
	v_rcp_f32_e32 v41, v41
	v_mul_f32_e32 v33, v36, v33
	v_mul_f32_e32 v36, v38, v34
	v_mul_f32_e32 v34, 0xbfb8aa3b, v34
	v_rcp_f32_e32 v25, v25
	v_rcp_f32_e32 v9, v9
	v_rcp_f32_e32 v1, v1
	v_exp_f32_e32 v115, v115
	v_add_f32_e32 v66, 1.0, v66
	v_exp_f32_e32 v34, v34
	v_mul_f32_e32 v98, v100, v98
	v_mul_f32_e32 v100, v103, v99
	v_mul_f32_e32 v99, 0xbfb8aa3b, v99
	v_rcp_f32_e32 v66, v66
	v_mul_f32_e32 v17, v20, v17
	v_mul_f32_e32 v20, v22, v18
	v_mul_f32_e32 v18, 0xbfb8aa3b, v18
	v_exp_f32_e32 v99, v99
	v_add_f32_e32 v50, 1.0, v50
	v_exp_f32_e32 v18, v18
	v_mul_f32_e32 v121, v124, v121
	v_mul_f32_e32 v124, v126, v122
	v_mul_f32_e32 v122, 0xbfb8aa3b, v122
	v_mul_f32_e32 v105, v108, v105
	v_mul_f32_e32 v108, v110, v106
	v_mul_f32_e32 v106, 0xbfb8aa3b, v106
	v_mul_f32_e32 v89, v92, v89
	v_mul_f32_e32 v92, v94, v90
	v_mul_f32_e32 v90, 0xbfb8aa3b, v90
	v_mul_f32_e32 v82, v84, v82
	v_mul_f32_e32 v84, v87, v83
	v_mul_f32_e32 v83, 0xbfb8aa3b, v83
	v_mul_f32_e32 v73, v76, v73
	v_mul_f32_e32 v76, v78, v74
	v_mul_f32_e32 v74, 0xbfb8aa3b, v74
	v_mul_f32_e32 v57, v60, v57
	v_mul_f32_e32 v60, v62, v58
	v_mul_f32_e32 v58, 0xbfb8aa3b, v58
	v_rcp_f32_e32 v50, v50
	v_mul_f32_e32 v41, v44, v41
	v_mul_f32_e32 v44, v46, v42
	v_mul_f32_e32 v42, 0xbfb8aa3b, v42
	v_mul_f32_e32 v25, v28, v25
	v_mul_f32_e32 v28, v30, v26
	v_mul_f32_e32 v26, 0xbfb8aa3b, v26
	v_mul_f32_e32 v9, v12, v9
	v_mul_f32_e32 v12, v14, v10
	v_mul_f32_e32 v10, 0xbfb8aa3b, v10
	v_mul_f32_e32 v1, v4, v1
	v_mul_f32_e32 v4, v6, v2
	v_mul_f32_e32 v2, 0xbfb8aa3b, v2
	v_exp_f32_e32 v122, v122
	v_add_f32_e32 v115, 1.0, v115
	v_exp_f32_e32 v106, v106
	v_exp_f32_e32 v90, v90
	v_exp_f32_e32 v83, v83
	v_exp_f32_e32 v74, v74
	v_exp_f32_e32 v58, v58
	v_exp_f32_e32 v42, v42
	v_add_f32_e32 v34, 1.0, v34
	v_exp_f32_e32 v26, v26
	v_exp_f32_e32 v10, v10
	v_exp_f32_e32 v2, v2
	v_lshl_or_b32 v134, s46, 7, v138
	v_rcp_f32_e32 v115, v115
	v_mul_f32_e32 v66, v68, v66
	v_mul_f32_e32 v68, v71, v67
	v_mul_f32_e32 v67, 0xbfb8aa3b, v67
	v_rcp_f32_e32 v34, v34
	v_ashrrev_i32_e32 v135, 31, v134
	v_add_f32_e32 v99, 1.0, v99
	v_exp_f32_e32 v67, v67
	v_add_f32_e32 v18, 1.0, v18
	v_lshl_add_u32 v140, s48, 8, v136
	v_lshl_add_u64 v[134:135], v[134:135], 1, s[74:75]
	v_rcp_f32_e32 v99, v99
	v_mul_f32_e32 v50, v52, v50
	v_mul_f32_e32 v52, v55, v51
	v_mul_f32_e32 v51, 0xbfb8aa3b, v51
	v_rcp_f32_e32 v18, v18
	v_mad_i64_i32 v[142:143], s[26:27], v140, s33, v[134:135]
	v_add_f32_e32 v122, 1.0, v122
	v_cvt_pk_bf16_f32 v112, v112, v113
	v_add_f32_e32 v106, 1.0, v106
	v_add_f32_e32 v90, 1.0, v90
	v_add_f32_e32 v83, 1.0, v83
	v_add_f32_e32 v74, 1.0, v74
	v_add_f32_e32 v58, 1.0, v58
	v_exp_f32_e32 v51, v51
	v_add_f32_e32 v42, 1.0, v42
	v_add_f32_e32 v26, 1.0, v26
	v_add_f32_e32 v10, 1.0, v10
	v_add_f32_e32 v2, 1.0, v2
	v_rcp_f32_e32 v122, v122
	v_mul_f32_e32 v115, v116, v115
	v_cvt_pk_bf16_f32 v113, v114, v115
	global_store_dwordx2 v[142:143], v[112:113], off offset:128
	v_or_b32_e32 v112, 16, v140
	v_rcp_f32_e32 v106, v106
	v_rcp_f32_e32 v90, v90
	v_rcp_f32_e32 v83, v83
	v_rcp_f32_e32 v74, v74
	v_rcp_f32_e32 v58, v58
	v_rcp_f32_e32 v42, v42
	v_mul_f32_e32 v34, v36, v34
	v_mul_f32_e32 v36, v39, v35
	v_mul_f32_e32 v35, 0xbfb8aa3b, v35
	v_rcp_f32_e32 v26, v26
	v_rcp_f32_e32 v10, v10
	v_rcp_f32_e32 v2, v2
	v_mad_i64_i32 v[112:113], s[26:27], v112, s33, v[134:135]
	v_cvt_pk_bf16_f32 v96, v96, v97
	v_add_f32_e32 v67, 1.0, v67
	v_exp_f32_e32 v35, v35
	v_mul_f32_e32 v99, v100, v99
	v_cvt_pk_bf16_f32 v97, v98, v99
	global_store_dwordx2 v[112:113], v[96:97], off offset:128
	v_or_b32_e32 v96, 32, v140
	v_rcp_f32_e32 v67, v67
	v_mul_f32_e32 v18, v20, v18
	v_mul_f32_e32 v20, v23, v19
	v_mul_f32_e32 v19, 0xbfb8aa3b, v19
	v_mad_i64_i32 v[96:97], s[26:27], v96, s33, v[134:135]
	v_cvt_pk_bf16_f32 v80, v80, v81
	v_add_f32_e32 v51, 1.0, v51
	v_exp_f32_e32 v19, v19
	v_mul_f32_e32 v122, v124, v122
	v_mul_f32_e32 v124, v127, v123
	v_mul_f32_e32 v123, 0xbfb8aa3b, v123
	v_mul_f32_e32 v106, v108, v106
	v_mul_f32_e32 v108, v111, v107
	v_mul_f32_e32 v107, 0xbfb8aa3b, v107
; __device__ __forceinline__ unsigned cvt_pk_bf16(float lo, float hi) { unsigned r; asm("v_cvt_pk_bf16_f32 %0, %1, %2" : "=v"(r) : "v"(lo), "v"(hi)); return r; }
; #define PG8_WAIT_V(n) asm volatile("s_waitcnt vmcnt(" #n ")" ::: "memory")
; #define PG8_BAR __builtin_amdgcn_s_barrier()
; template <class Epi>
; __device__ __forceinline__ void gemm_phase(LAS unsigned char* lds, const Gemm g, const StaticOrder S, const Epi E) {
;     ...
;         if (!has_next) break;
; #pragma unroll
;         for (int a = 0; a < 2; ++a)
; #pragma unroll
;             for (int b = 0; b < 2; ++b)
; #pragma unroll
;                 for (int m = 0; m < 4; ++m)
; #pragma unroll
;                     for (int n = 0; n < 2; ++n) acc[a][b][m][n] = (f32x4){0.f, 0.f, 0.f, 0.f};
;         cur = nxt; cA = nA; cB = nB; ++ui;
;     }
;     PG8_WAIT_V(0);
;     if (wr == 0) PG8_BAR;
;     PG8_BAR;
;     __device__ __forceinline__ void operator()(AccRef acc, const pg8::Unit& u, int wr, int wc, int fr, int fq) const {
;     ...
;             for (int m = 0; m < 4; ++m) { bf16_t* rowp = G + (size_t)(row0 + ai * 128 + m * 16) * FH + col0;
; #pragma unroll
;                 for (int bj = 0; bj < 2; ++bj) { const f32x4 gq = acc[ai][bj][m][0], uq = acc[ai][bj][m][1]; float v[4];
; #pragma unroll
;                     for (int i = 0; i < 4; ++i) v[i] = gq[i] * uq[i] * __builtin_amdgcn_rcpf(1.f + __builtin_amdgcn_exp2f(-gq[i] * LOG2E));
;                     u32x2 w; w.x = cvt_pk_bf16(v[0], v[1]); w.y = cvt_pk_bf16(v[2], v[3]);
;                     *(u32x2*)(rowp + bj * 64) = w; } }
	v_mul_f32_e32 v90, v92, v90
	v_mul_f32_e32 v92, v95, v91
	v_mul_f32_e32 v91, 0xbfb8aa3b, v91
	v_mul_f32_e32 v83, v84, v83
	v_cvt_pk_bf16_f32 v81, v82, v83
	global_store_dwordx2 v[96:97], v[80:81], off offset:128
	v_or_b32_e32 v80, 48, v140
	v_mul_f32_e32 v74, v76, v74
	v_mul_f32_e32 v76, v79, v75
	v_mul_f32_e32 v75, 0xbfb8aa3b, v75
	v_mul_f32_e32 v58, v60, v58
	v_mul_f32_e32 v60, v63, v59
	v_mul_f32_e32 v59, 0xbfb8aa3b, v59
	v_rcp_f32_e32 v51, v51
	v_mul_f32_e32 v42, v44, v42
	v_mul_f32_e32 v44, v47, v43
	v_mul_f32_e32 v43, 0xbfb8aa3b, v43
	v_mul_f32_e32 v26, v28, v26
	v_mul_f32_e32 v28, v31, v27
	v_mul_f32_e32 v27, 0xbfb8aa3b, v27
	v_mul_f32_e32 v10, v12, v10
	v_mul_f32_e32 v12, v15, v11
	v_mul_f32_e32 v11, 0xbfb8aa3b, v11
	v_mul_f32_e32 v2, v4, v2
	v_mul_f32_e32 v4, v7, v3
	v_mul_f32_e32 v3, 0xbfb8aa3b, v3
	v_exp_f32_e32 v123, v123
	v_exp_f32_e32 v107, v107
	v_exp_f32_e32 v91, v91
	v_mad_i64_i32 v[80:81], s[26:27], v80, s33, v[134:135]
	v_exp_f32_e32 v75, v75
	v_cvt_pk_bf16_f32 v64, v64, v65
	v_exp_f32_e32 v59, v59
	v_exp_f32_e32 v43, v43
	v_add_f32_e32 v35, 1.0, v35
	v_exp_f32_e32 v27, v27
	v_exp_f32_e32 v11, v11
	v_exp_f32_e32 v3, v3
	v_mul_f32_e32 v67, v68, v67
	v_cvt_pk_bf16_f32 v65, v66, v67
	global_store_dwordx2 v[80:81], v[64:65], off offset:128
	v_add_u32_e32 v64, 0x80, v140
	v_rcp_f32_e32 v35, v35
	v_mad_i64_i32 v[64:65], s[26:27], v64, s33, v[134:135]
	v_cvt_pk_bf16_f32 v48, v48, v49
	v_add_f32_e32 v19, 1.0, v19
	v_mul_f32_e32 v51, v52, v51
	v_cvt_pk_bf16_f32 v49, v50, v51
	global_store_dwordx2 v[64:65], v[48:49], off offset:128
	v_add_u32_e32 v48, 0x90, v140
	v_rcp_f32_e32 v19, v19
	v_add_f32_e32 v123, 1.0, v123
	v_add_f32_e32 v107, 1.0, v107
	v_add_f32_e32 v91, 1.0, v91
	v_add_f32_e32 v75, 1.0, v75
	v_add_f32_e32 v59, 1.0, v59
	v_mad_i64_i32 v[48:49], s[26:27], v48, s33, v[134:135]
	v_add_f32_e32 v43, 1.0, v43
	v_cvt_pk_bf16_f32 v32, v32, v33
	v_add_f32_e32 v27, 1.0, v27
	v_add_f32_e32 v11, 1.0, v11
	v_add_f32_e32 v3, 1.0, v3
	v_rcp_f32_e32 v123, v123
	v_rcp_f32_e32 v107, v107
	v_rcp_f32_e32 v91, v91
	v_rcp_f32_e32 v75, v75
	v_rcp_f32_e32 v59, v59
	v_rcp_f32_e32 v43, v43
	v_mul_f32_e32 v35, v36, v35
	v_cvt_pk_bf16_f32 v33, v34, v35
	global_store_dwordx2 v[48:49], v[32:33], off offset:128
	v_add_u32_e32 v32, 0xa0, v140
	v_rcp_f32_e32 v27, v27
	v_rcp_f32_e32 v11, v11
	v_rcp_f32_e32 v3, v3
	v_mad_i64_i32 v[32:33], s[26:27], v32, s33, v[134:135]
	v_cvt_pk_bf16_f32 v16, v16, v17
	v_mul_f32_e32 v19, v20, v19
	v_cvt_pk_bf16_f32 v17, v18, v19
	global_store_dwordx2 v[32:33], v[16:17], off offset:128
	v_add_u32_e32 v16, 0xb0, v140
	v_mad_i64_i32 v[16:17], s[26:27], v16, s33, v[134:135]
	s_and_b64 vcc, exec, s[38:39]
	s_mov_b32 s46, s0
	s_mov_b32 s48, s2
	s_mov_b64 s[52:53], s[44:45]
	s_mov_b64 s[50:51], s[42:43]
	v_readlane_b32 s64, v255, 53
	v_mul_f32_e32 v123, v124, v123
	v_cvt_pk_bf16_f32 v120, v120, v121
	v_cvt_pk_bf16_f32 v121, v122, v123
	global_store_dwordx2 v[142:143], v[120:121], off
	v_mul_f32_e32 v107, v108, v107
	v_cvt_pk_bf16_f32 v104, v104, v105
	v_cvt_pk_bf16_f32 v105, v106, v107
	global_store_dwordx2 v[112:113], v[104:105], off
	v_mul_f32_e32 v91, v92, v91
	v_cvt_pk_bf16_f32 v88, v88, v89
	v_cvt_pk_bf16_f32 v89, v90, v91
	global_store_dwordx2 v[96:97], v[88:89], off
	v_mul_f32_e32 v75, v76, v75
	v_cvt_pk_bf16_f32 v72, v72, v73
	v_cvt_pk_bf16_f32 v73, v74, v75
	global_store_dwordx2 v[80:81], v[72:73], off
	v_mul_f32_e32 v59, v60, v59
	v_cvt_pk_bf16_f32 v56, v56, v57
	v_cvt_pk_bf16_f32 v57, v58, v59
	global_store_dwordx2 v[64:65], v[56:57], off
	v_mul_f32_e32 v43, v44, v43
	v_cvt_pk_bf16_f32 v40, v40, v41
	v_cvt_pk_bf16_f32 v41, v42, v43
	global_store_dwordx2 v[48:49], v[40:41], off
	v_mul_f32_e32 v27, v28, v27
	v_cvt_pk_bf16_f32 v24, v24, v25
	v_cvt_pk_bf16_f32 v25, v26, v27
	global_store_dwordx2 v[32:33], v[24:25], off
	v_mul_f32_e32 v11, v12, v11
	v_cvt_pk_bf16_f32 v8, v8, v9
	v_cvt_pk_bf16_f32 v9, v10, v11
	global_store_dwordx2 v[16:17], v[8:9], off
	v_mul_f32_e32 v3, v4, v3
	v_cvt_pk_bf16_f32 v0, v0, v1
	v_cvt_pk_bf16_f32 v1, v2, v3
	global_store_dwordx2 v[16:17], v[0:1], off offset:128
	v_readlane_b32 s65, v255, 54
	s_cbranch_vccz .LBB0_3716
	s_waitcnt vmcnt(0)
	s_cmpk_gt_u32 s7, 0xff
	s_cbranch_scc1 .LBB0_3727
	s_barrier

; #define PG8_STAGE(bufoff, gbase, voff) do { _Pragma("unroll") for (int _i = 0; _i < 2; ++_i) \
;         __builtin_amdgcn_global_load_lds((const unsigned*)((const char*)(gbase) + (voff)[_i]), (LAS unsigned*)(lds + (bufoff) + ldsw + _i * 8192), 16, 0, 0); } while (0)
; #define PG8_LDA(dst, b, h) do { _Pragma("unroll") for (int m = 0; m < 4; ++m) _Pragma("unroll") for (int k = 0; k < 2; ++k) dst[m][k] = *(const LAS bf16x8*)(lds + PG8_SA(b, h) + aoff + m * 2048 + k * 1024); } while (0)
; #define PG8_LDB(dst, b, h) do { _Pragma("unroll") for (int n = 0; n < 2; ++n) _Pragma("unroll") for (int k = 0; k < 2; ++k) dst[n][k] = *(const LAS bf16x8*)(lds + PG8_SB(b, h) + boff + n * 2048 + k * 1024); } while (0)
; #define PG8_MMA(ai, bj, At, Bt) do { __builtin_amdgcn_s_setprio(1); _Pragma("unroll") for (int m = 0; m < 4; ++m) _Pragma("unroll") for (int n = 0; n < 2; ++n) _Pragma("unroll") for (int k = 0; k < 2; ++k) \
;         acc[ai][bj][m][n] = __builtin_amdgcn_mfma_f32_16x16x32_bf16(Bt[n][k], At[m][k], acc[ai][bj][m][n], 0, 0, 0); __builtin_amdgcn_s_setprio(0); } while (0)
; #define PG8_WAIT_L(n) asm volatile("s_waitcnt lgkmcnt(" #n ")" ::: "memory")
; #define PG8_BAR __builtin_amdgcn_s_barrier()
; #define PG8_SCHED __builtin_amdgcn_sched_barrier(0)
; template <class Epi>
; __device__ __forceinline__ void gemm_phase(LAS unsigned char* lds, const Gemm g, const StaticOrder S, const Epi E) {
;     ...
;         for (int t = 0; t < nt; t += 2) {
;             const bool last = (t == nt - 2);
;             const char* a1 = cA + (size_t)(t + 1) * kstep;
;             const char* a2 = last ? nA : cA + (size_t)(t + 2) * kstep; const char* b2 = last ? nB : cB + (size_t)(t + 2) * kstep;
;             const char* a3 = a2 + kstep; const char* b3 = b2 + kstep;
;             PG8_LDB(B0, 0, 0); PG8_SCHED; PG8_LDA(At, 0, 0); PG8_STAGE(PG8_SA(1, 1), a1 + hstep, voffA);
;             PG8_WAIT_L(8); PG8_BAR; PG8_WAIT_L(0); PG8_MMA(0, 0, At, B0); PG8_BAR; PG8_SCHED;
;             PG8_LDB(B1, 0, 1); PG8_STAGE(PG8_SB(0, 0), b2, voffA);
;             PG8_BAR; PG8_WAIT_L(0); PG8_MMA(0, 1, At, B1); PG8_BAR;
;             PG8_LDA(At, 0, 1); PG8_STAGE(PG8_SA(0, 0), a2, voffA);
;             PG8_BAR; PG8_WAIT_L(0); PG8_MMA(1, 0, At, B0); PG8_BAR; PG8_SCHED;
.LBB0_3918:
	s_add_i32 s43, s67, -2
	s_add_u32 s68, s50, 0x100
	s_addc_u32 s69, s51, 0
	s_mov_b32 s52, 0
	s_add_i32 vcc_lo, s52, 2
	s_add_u32 s50, s38, 0x100
	s_addc_u32 s51, s39, 0
	s_add_i32 s14, 0, 0x10000
	v_add_u32_e32 v140, s14, v228
	ds_read_b128 v[128:131], v140
	ds_read_b128 v[132:135], v140 offset:1024
	ds_read_b128 v[136:139], v140 offset:2048
	ds_read_b128 v[140:143], v140 offset:3072
	s_cmp_eq_u32 s43, s52
	s_cselect_b32 s52, s48, s68
	s_cselect_b32 s55, s45, s51
	s_cselect_b32 s54, s44, s50
	s_cselect_b32 s53, s49, s69
	v_lshl_add_u64 v[200:201], s[38:39], 0, v[196:197]
	s_add_i32 m0, s25, 0xc000
	ds_read_b128 v[144:147], v230
	ds_read_b128 v[148:151], v230 offset:1024
	ds_read_b128 v[152:155], v230 offset:2048
	ds_read_b128 v[156:159], v230 offset:3072
	ds_read_b128 v[160:163], v230 offset:4096
	ds_read_b128 v[164:167], v230 offset:5120
	ds_read_b128 v[168:171], v230 offset:6144
	ds_read_b128 v[172:175], v230 offset:7168
	global_load_lds_dwordx4 v[200:201], off
	v_lshl_add_u64 v[200:201], s[38:39], 0, v[198:199]
	s_add_i32 m0, s25, 0xe000
	s_nop 0
	global_load_lds_dwordx4 v[200:201], off
	s_waitcnt lgkmcnt(8)
	s_barrier
	s_waitcnt lgkmcnt(0)
	s_setprio 1
	v_mfma_f32_16x16x32_bf16 v[124:127], v[128:131], v[144:147], 0
	v_mfma_f32_16x16x32_bf16 v[120:123], v[136:139], v[144:147], 0
	v_mfma_f32_16x16x32_bf16 v[112:115], v[128:131], v[152:155], 0
	v_mfma_f32_16x16x32_bf16 v[104:107], v[136:139], v[152:155], 0
	v_mfma_f32_16x16x32_bf16 v[92:95], v[128:131], v[160:163], 0
	v_mfma_f32_16x16x32_bf16 v[88:91], v[136:139], v[160:163], 0
	v_mfma_f32_16x16x32_bf16 v[80:83], v[128:131], v[168:171], 0
	v_mfma_f32_16x16x32_bf16 v[72:75], v[136:139], v[168:171], 0
	v_mfma_f32_16x16x32_bf16 v[124:127], v[132:135], v[148:151], v[124:127]
	v_mfma_f32_16x16x32_bf16 v[120:123], v[140:143], v[148:151], v[120:123]
	v_mfma_f32_16x16x32_bf16 v[112:115], v[132:135], v[156:159], v[112:115]
	v_mfma_f32_16x16x32_bf16 v[104:107], v[140:143], v[156:159], v[104:107]
	v_mfma_f32_16x16x32_bf16 v[92:95], v[132:135], v[164:167], v[92:95]
	v_mfma_f32_16x16x32_bf16 v[88:91], v[140:143], v[164:167], v[88:91]
	v_mfma_f32_16x16x32_bf16 v[80:83], v[132:135], v[172:175], v[80:83]
	v_mfma_f32_16x16x32_bf16 v[72:75], v[140:143], v[172:175], v[72:75]
	s_setprio 0
	s_barrier
	s_add_i32 s38, 0, 0x14000
	s_add_i32 s14, s14, s24
	v_add_u32_e32 v220, s38, v228
	v_lshl_add_u64 v[232:233], s[52:53], 0, v[178:179]
	s_mov_b32 m0, s14
	ds_read_b128 v[200:203], v220
	ds_read_b128 v[204:207], v220 offset:1024
	ds_read_b128 v[208:211], v220 offset:2048
	ds_read_b128 v[220:223], v220 offset:3072
	global_load_lds_dwordx4 v[232:233], off
	v_lshl_add_u64 v[234:235], s[52:53], 0, v[194:195]
	s_add_i32 m0, s14, 0x2000
	s_nop 0
	global_load_lds_dwordx4 v[234:235], off
	s_barrier
	s_waitcnt lgkmcnt(0)
	s_setprio 1
	v_mfma_f32_16x16x32_bf16 v[116:119], v[200:203], v[144:147], 0
	v_mfma_f32_16x16x32_bf16 v[108:111], v[208:211], v[144:147], 0
	v_mfma_f32_16x16x32_bf16 v[100:103], v[200:203], v[152:155], 0
	v_mfma_f32_16x16x32_bf16 v[96:99], v[208:211], v[152:155], 0
	v_mfma_f32_16x16x32_bf16 v[84:87], v[200:203], v[160:163], 0
	v_mfma_f32_16x16x32_bf16 v[76:79], v[208:211], v[160:163], 0
	v_mfma_f32_16x16x32_bf16 v[68:71], v[200:203], v[168:171], 0
	v_mfma_f32_16x16x32_bf16 v[64:67], v[208:211], v[168:171], 0
	v_mfma_f32_16x16x32_bf16 v[116:119], v[204:207], v[148:151], v[116:119]
	v_mfma_f32_16x16x32_bf16 v[108:111], v[220:223], v[148:151], v[108:111]
	v_mfma_f32_16x16x32_bf16 v[100:103], v[204:207], v[156:159], v[100:103]
	v_mfma_f32_16x16x32_bf16 v[96:99], v[220:223], v[156:159], v[96:99]
	v_mfma_f32_16x16x32_bf16 v[84:87], v[204:207], v[164:167], v[84:87]
	v_mfma_f32_16x16x32_bf16 v[76:79], v[220:223], v[164:167], v[76:79]
	v_mfma_f32_16x16x32_bf16 v[68:71], v[204:207], v[172:175], v[68:71]
	v_mfma_f32_16x16x32_bf16 v[64:67], v[220:223], v[172:175], v[64:67]
	s_setprio 0
	s_barrier
	s_mov_b32 m0, s25
	v_lshl_add_u64 v[236:237], s[54:55], 0, v[178:179]
	ds_read_b128 v[144:147], v230 offset:16384
	ds_read_b128 v[148:151], v230 offset:17408
	ds_read_b128 v[152:155], v230 offset:18432
	ds_read_b128 v[156:159], v230 offset:19456
	ds_read_b128 v[160:163], v230 offset:20480
	ds_read_b128 v[164:167], v230 offset:21504
	ds_read_b128 v[168:171], v230 offset:22528
	ds_read_b128 v[172:175], v230 offset:23552
	global_load_lds_dwordx4 v[236:237], off
	v_lshl_add_u64 v[238:239], s[54:55], 0, v[194:195]
	s_mov_b32 m0, s56
	s_nop 0
	global_load_lds_dwordx4 v[238:239], off
	s_barrier
	s_waitcnt lgkmcnt(0)
	s_setprio 1
	v_mfma_f32_16x16x32_bf16 v[60:63], v[128:131], v[144:147], 0
	v_mfma_f32_16x16x32_bf16 v[56:59], v[136:139], v[144:147], 0
	v_mfma_f32_16x16x32_bf16 v[48:51], v[128:131], v[152:155], 0
	v_mfma_f32_16x16x32_bf16 v[40:43], v[136:139], v[152:155], 0
	v_mfma_f32_16x16x32_bf16 v[28:31], v[128:131], v[160:163], 0
	v_mfma_f32_16x16x32_bf16 v[24:27], v[136:139], v[160:163], 0
	v_mfma_f32_16x16x32_bf16 v[16:19], v[128:131], v[168:171], 0
	v_mfma_f32_16x16x32_bf16 v[8:11], v[136:139], v[168:171], 0
	v_mfma_f32_16x16x32_bf16 v[60:63], v[132:135], v[148:151], v[60:63]
	v_mfma_f32_16x16x32_bf16 v[56:59], v[140:143], v[148:151], v[56:59]
	v_mfma_f32_16x16x32_bf16 v[48:51], v[132:135], v[156:159], v[48:51]
	v_mfma_f32_16x16x32_bf16 v[40:43], v[140:143], v[156:159], v[40:43]
	v_mfma_f32_16x16x32_bf16 v[28:31], v[132:135], v[164:167], v[28:31]
	v_mfma_f32_16x16x32_bf16 v[24:27], v[140:143], v[164:167], v[24:27]
	v_mfma_f32_16x16x32_bf16 v[16:19], v[132:135], v[172:175], v[16:19]
	v_mfma_f32_16x16x32_bf16 v[8:11], v[140:143], v[172:175], v[8:11]
	s_setprio 0
	s_barrier
; #define PG8_STAGE(bufoff, gbase, voff) do { _Pragma("unroll") for (int _i = 0; _i < 2; ++_i) \
;         __builtin_amdgcn_global_load_lds((const unsigned*)((const char*)(gbase) + (voff)[_i]), (LAS unsigned*)(lds + (bufoff) + ldsw + _i * 8192), 16, 0, 0); } while (0)
; #define PG8_LDA(dst, b, h) do { _Pragma("unroll") for (int m = 0; m < 4; ++m) _Pragma("unroll") for (int k = 0; k < 2; ++k) dst[m][k] = *(const LAS bf16x8*)(lds + PG8_SA(b, h) + aoff + m * 2048 + k * 1024); } while (0)
; #define PG8_LDB(dst, b, h) do { _Pragma("unroll") for (int n = 0; n < 2; ++n) _Pragma("unroll") for (int k = 0; k < 2; ++k) dst[n][k] = *(const LAS bf16x8*)(lds + PG8_SB(b, h) + boff + n * 2048 + k * 1024); } while (0)
; #define PG8_MMA(ai, bj, At, Bt) do { __builtin_amdgcn_s_setprio(1); _Pragma("unroll") for (int m = 0; m < 4; ++m) _Pragma("unroll") for (int n = 0; n < 2; ++n) _Pragma("unroll") for (int k = 0; k < 2; ++k) \
;         acc[ai][bj][m][n] = __builtin_amdgcn_mfma_f32_16x16x32_bf16(Bt[n][k], At[m][k], acc[ai][bj][m][n], 0, 0, 0); __builtin_amdgcn_s_setprio(0); } while (0)
; #define PG8_WAIT_V(n) asm volatile("s_waitcnt vmcnt(" #n ")" ::: "memory")
; #define PG8_WAIT_L(n) asm volatile("s_waitcnt lgkmcnt(" #n ")" ::: "memory")
; #define PG8_BAR __builtin_amdgcn_s_barrier()
; #define PG8_SCHED __builtin_amdgcn_sched_barrier(0)
; template <class Epi>
; __device__ __forceinline__ void gemm_phase(LAS unsigned char* lds, const Gemm g, const StaticOrder S, const Epi E) {
;     ...
;             PG8_STAGE(PG8_SB(0, 1), b2 + hstep, voffA);
;             PG8_WAIT_V(6); PG8_BAR; PG8_MMA(1, 1, At, B1); PG8_BAR;
;             PG8_LDB(B0, 1, 0); PG8_SCHED; PG8_LDA(At, 1, 0); PG8_STAGE(PG8_SA(0, 1), a2 + hstep, voffA);
;             PG8_WAIT_L(8); PG8_BAR; PG8_WAIT_L(0); PG8_MMA(0, 0, At, B0); PG8_BAR; PG8_SCHED;
;             PG8_LDB(B1, 1, 1); PG8_STAGE(PG8_SB(1, 0), b3, voffA);
;             PG8_BAR; PG8_WAIT_L(0); PG8_MMA(0, 1, At, B1); PG8_BAR;
;             PG8_LDA(At, 1, 1); PG8_STAGE(PG8_SA(1, 0), a3, voffA);
	s_add_u32 s30, s52, 0x158000
	s_addc_u32 s31, s53, 0
	s_add_i32 s14, s38, s24
	v_lshl_add_u64 v[128:129], s[30:31], 0, v[178:179]
	s_mov_b32 m0, s14
	s_nop 0
	global_load_lds_dwordx4 v[128:129], off
	v_lshl_add_u64 v[128:129], s[30:31], 0, v[194:195]
	s_add_i32 m0, s14, 0x2000
	s_nop 0
	global_load_lds_dwordx4 v[128:129], off
	s_waitcnt vmcnt(6)
	s_barrier
	s_setprio 1
	v_mfma_f32_16x16x32_bf16 v[52:55], v[200:203], v[144:147], 0
	v_mfma_f32_16x16x32_bf16 v[44:47], v[208:211], v[144:147], 0
	v_mfma_f32_16x16x32_bf16 v[36:39], v[200:203], v[152:155], 0
	v_mfma_f32_16x16x32_bf16 v[32:35], v[208:211], v[152:155], 0
	v_mfma_f32_16x16x32_bf16 v[20:23], v[200:203], v[160:163], 0
	v_mfma_f32_16x16x32_bf16 v[12:15], v[208:211], v[160:163], 0
	v_mfma_f32_16x16x32_bf16 v[4:7], v[200:203], v[168:171], 0
	v_mfma_f32_16x16x32_bf16 v[0:3], v[208:211], v[168:171], 0
	v_mfma_f32_16x16x32_bf16 v[52:55], v[204:207], v[148:151], v[52:55]
	v_mfma_f32_16x16x32_bf16 v[44:47], v[220:223], v[148:151], v[44:47]
	v_mfma_f32_16x16x32_bf16 v[36:39], v[204:207], v[156:159], v[36:39]
	v_mfma_f32_16x16x32_bf16 v[32:35], v[220:223], v[156:159], v[32:35]
	v_mfma_f32_16x16x32_bf16 v[20:23], v[204:207], v[164:167], v[20:23]
	v_mfma_f32_16x16x32_bf16 v[12:15], v[220:223], v[164:167], v[12:15]
	v_mfma_f32_16x16x32_bf16 v[4:7], v[204:207], v[172:175], v[4:7]
	v_mfma_f32_16x16x32_bf16 v[0:3], v[220:223], v[172:175], v[0:3]
	s_setprio 0
	s_barrier
	s_add_i32 s14, 0, 0x18000
	v_add_u32_e32 v140, s14, v228
	ds_read_b128 v[128:131], v140
	ds_read_b128 v[132:135], v140 offset:1024
	ds_read_b128 v[136:139], v140 offset:2048
	ds_read_b128 v[140:143], v140 offset:3072
	s_add_u32 s30, s54, 0x158000
	s_addc_u32 s31, s55, 0
	s_mov_b32 m0, s57
	v_lshl_add_u64 v[200:201], s[30:31], 0, v[178:179]
	ds_read_b128 v[144:147], v230 offset:32768
	ds_read_b128 v[148:151], v230 offset:33792
	ds_read_b128 v[152:155], v230 offset:34816
	ds_read_b128 v[156:159], v230 offset:35840
	ds_read_b128 v[160:163], v230 offset:36864
	ds_read_b128 v[164:167], v230 offset:37888
	ds_read_b128 v[168:171], v230 offset:38912
	ds_read_b128 v[172:175], v230 offset:39936
	global_load_lds_dwordx4 v[200:201], off
	v_lshl_add_u64 v[200:201], s[30:31], 0, v[194:195]
	s_mov_b32 m0, s58
	s_nop 0
	global_load_lds_dwordx4 v[200:201], off
	s_waitcnt lgkmcnt(8)
	s_barrier
	s_waitcnt lgkmcnt(0)
	s_setprio 1
	v_mfma_f32_16x16x32_bf16 v[124:127], v[128:131], v[144:147], v[124:127]
	v_mfma_f32_16x16x32_bf16 v[120:123], v[136:139], v[144:147], v[120:123]
	v_mfma_f32_16x16x32_bf16 v[112:115], v[128:131], v[152:155], v[112:115]
	v_mfma_f32_16x16x32_bf16 v[104:107], v[136:139], v[152:155], v[104:107]
	v_mfma_f32_16x16x32_bf16 v[92:95], v[128:131], v[160:163], v[92:95]
	v_mfma_f32_16x16x32_bf16 v[88:91], v[136:139], v[160:163], v[88:91]
	v_mfma_f32_16x16x32_bf16 v[80:83], v[128:131], v[168:171], v[80:83]
	v_mfma_f32_16x16x32_bf16 v[72:75], v[136:139], v[168:171], v[72:75]
	v_mfma_f32_16x16x32_bf16 v[124:127], v[132:135], v[148:151], v[124:127]
	v_mfma_f32_16x16x32_bf16 v[120:123], v[140:143], v[148:151], v[120:123]
	v_mfma_f32_16x16x32_bf16 v[112:115], v[132:135], v[156:159], v[112:115]
	v_mfma_f32_16x16x32_bf16 v[104:107], v[140:143], v[156:159], v[104:107]
	v_mfma_f32_16x16x32_bf16 v[92:95], v[132:135], v[164:167], v[92:95]
	v_mfma_f32_16x16x32_bf16 v[88:91], v[140:143], v[164:167], v[88:91]
	v_mfma_f32_16x16x32_bf16 v[80:83], v[132:135], v[172:175], v[80:83]
	v_mfma_f32_16x16x32_bf16 v[72:75], v[140:143], v[172:175], v[72:75]
	s_setprio 0
	s_barrier
	s_add_i32 s38, 0, 0x1c000
	s_add_i32 s14, s14, s24
	v_add_u32_e32 v220, s38, v228
	v_lshl_add_u64 v[232:233], v[232:233], 0, s[34:35]
	s_mov_b32 m0, s14
	ds_read_b128 v[200:203], v220
	ds_read_b128 v[204:207], v220 offset:1024
	ds_read_b128 v[208:211], v220 offset:2048
	ds_read_b128 v[220:223], v220 offset:3072
	global_load_lds_dwordx4 v[232:233], off
	v_lshl_add_u64 v[232:233], v[234:235], 0, s[34:35]
	s_add_i32 m0, s14, 0x2000
	s_nop 0
	global_load_lds_dwordx4 v[232:233], off
	s_barrier
; #define PG8_STAGE(bufoff, gbase, voff) do { _Pragma("unroll") for (int _i = 0; _i < 2; ++_i) \
;         __builtin_amdgcn_global_load_lds((const unsigned*)((const char*)(gbase) + (voff)[_i]), (LAS unsigned*)(lds + (bufoff) + ldsw + _i * 8192), 16, 0, 0); } while (0)
; #define PG8_LDA(dst, b, h) do { _Pragma("unroll") for (int m = 0; m < 4; ++m) _Pragma("unroll") for (int k = 0; k < 2; ++k) dst[m][k] = *(const LAS bf16x8*)(lds + PG8_SA(b, h) + aoff + m * 2048 + k * 1024); } while (0)
; #define PG8_MMA(ai, bj, At, Bt) do { __builtin_amdgcn_s_setprio(1); _Pragma("unroll") for (int m = 0; m < 4; ++m) _Pragma("unroll") for (int n = 0; n < 2; ++n) _Pragma("unroll") for (int k = 0; k < 2; ++k) \
;         acc[ai][bj][m][n] = __builtin_amdgcn_mfma_f32_16x16x32_bf16(Bt[n][k], At[m][k], acc[ai][bj][m][n], 0, 0, 0); __builtin_amdgcn_s_setprio(0); } while (0)
; #define PG8_WAIT_V(n) asm volatile("s_waitcnt vmcnt(" #n ")" ::: "memory")
; #define PG8_WAIT_L(n) asm volatile("s_waitcnt lgkmcnt(" #n ")" ::: "memory")
; #define PG8_BAR __builtin_amdgcn_s_barrier()
; #define PG8_SCHED __builtin_amdgcn_sched_barrier(0)
; template <class Epi>
; __device__ __forceinline__ void gemm_phase(LAS unsigned char* lds, const Gemm g, const StaticOrder S, const Epi E) {
;     ...
;             PG8_BAR; PG8_WAIT_L(0); PG8_MMA(0, 1, At, B1); PG8_BAR;
;             PG8_LDA(At, 1, 1); PG8_STAGE(PG8_SA(1, 0), a3, voffA);
;             PG8_BAR; PG8_WAIT_L(0); PG8_MMA(1, 0, At, B0); PG8_BAR; PG8_SCHED;
;             PG8_STAGE(PG8_SB(1, 1), b3 + hstep, voffA);
;             PG8_WAIT_V(6); PG8_BAR; PG8_MMA(1, 1, At, B1); PG8_BAR;
;         }
	s_waitcnt lgkmcnt(0)
	s_setprio 1
	v_mfma_f32_16x16x32_bf16 v[116:119], v[200:203], v[144:147], v[116:119]
	v_mfma_f32_16x16x32_bf16 v[108:111], v[208:211], v[144:147], v[108:111]
	v_mfma_f32_16x16x32_bf16 v[100:103], v[200:203], v[152:155], v[100:103]
	v_mfma_f32_16x16x32_bf16 v[96:99], v[208:211], v[152:155], v[96:99]
	v_mfma_f32_16x16x32_bf16 v[84:87], v[200:203], v[160:163], v[84:87]
	v_mfma_f32_16x16x32_bf16 v[76:79], v[208:211], v[160:163], v[76:79]
	v_mfma_f32_16x16x32_bf16 v[68:71], v[200:203], v[168:171], v[68:71]
	v_mfma_f32_16x16x32_bf16 v[64:67], v[208:211], v[168:171], v[64:67]
	v_mfma_f32_16x16x32_bf16 v[116:119], v[204:207], v[148:151], v[116:119]
	v_mfma_f32_16x16x32_bf16 v[108:111], v[220:223], v[148:151], v[108:111]
	v_mfma_f32_16x16x32_bf16 v[100:103], v[204:207], v[156:159], v[100:103]
	v_mfma_f32_16x16x32_bf16 v[96:99], v[220:223], v[156:159], v[96:99]
	v_mfma_f32_16x16x32_bf16 v[84:87], v[204:207], v[164:167], v[84:87]
	v_mfma_f32_16x16x32_bf16 v[76:79], v[220:223], v[164:167], v[76:79]
	v_mfma_f32_16x16x32_bf16 v[68:71], v[204:207], v[172:175], v[68:71]
	v_mfma_f32_16x16x32_bf16 v[64:67], v[220:223], v[172:175], v[64:67]
	s_setprio 0
	s_barrier
	s_mov_b32 m0, s61
	v_lshl_add_u64 v[232:233], v[236:237], 0, s[34:35]
	ds_read_b128 v[144:147], v230 offset:49152
	ds_read_b128 v[148:151], v230 offset:50176
	ds_read_b128 v[152:155], v230 offset:51200
	ds_read_b128 v[156:159], v230 offset:52224
	ds_read_b128 v[160:163], v230 offset:53248
	ds_read_b128 v[164:167], v230 offset:54272
	ds_read_b128 v[168:171], v230 offset:55296
	ds_read_b128 v[172:175], v230 offset:56320
	global_load_lds_dwordx4 v[232:233], off
	v_lshl_add_u64 v[232:233], v[238:239], 0, s[34:35]
	s_mov_b32 m0, s62
	s_nop 0
	global_load_lds_dwordx4 v[232:233], off
	s_barrier
	s_waitcnt lgkmcnt(0)
	s_setprio 1
	v_mfma_f32_16x16x32_bf16 v[60:63], v[128:131], v[144:147], v[60:63]
	v_mfma_f32_16x16x32_bf16 v[56:59], v[136:139], v[144:147], v[56:59]
	v_mfma_f32_16x16x32_bf16 v[48:51], v[128:131], v[152:155], v[48:51]
	v_mfma_f32_16x16x32_bf16 v[40:43], v[136:139], v[152:155], v[40:43]
	v_mfma_f32_16x16x32_bf16 v[28:31], v[128:131], v[160:163], v[28:31]
	v_mfma_f32_16x16x32_bf16 v[24:27], v[136:139], v[160:163], v[24:27]
	v_mfma_f32_16x16x32_bf16 v[16:19], v[128:131], v[168:171], v[16:19]
	v_mfma_f32_16x16x32_bf16 v[8:11], v[136:139], v[168:171], v[8:11]
	v_mfma_f32_16x16x32_bf16 v[60:63], v[132:135], v[148:151], v[60:63]
	v_mfma_f32_16x16x32_bf16 v[56:59], v[140:143], v[148:151], v[56:59]
	v_mfma_f32_16x16x32_bf16 v[48:51], v[132:135], v[156:159], v[48:51]
	v_mfma_f32_16x16x32_bf16 v[40:43], v[140:143], v[156:159], v[40:43]
	v_mfma_f32_16x16x32_bf16 v[28:31], v[132:135], v[164:167], v[28:31]
	v_mfma_f32_16x16x32_bf16 v[24:27], v[140:143], v[164:167], v[24:27]
	v_mfma_f32_16x16x32_bf16 v[16:19], v[132:135], v[172:175], v[16:19]
	v_mfma_f32_16x16x32_bf16 v[8:11], v[140:143], v[172:175], v[8:11]
	s_setprio 0
	s_barrier
	s_add_u32 s30, s52, 0x158080
	s_addc_u32 s31, s53, 0
	s_add_i32 s14, s38, s24
	v_lshl_add_u64 v[128:129], s[30:31], 0, v[178:179]
	s_mov_b32 m0, s14
	s_nop 0
	global_load_lds_dwordx4 v[128:129], off
	v_lshl_add_u64 v[128:129], s[30:31], 0, v[194:195]
	s_add_i32 m0, s14, 0x2000
	s_nop 0
	global_load_lds_dwordx4 v[128:129], off
	s_waitcnt vmcnt(6)
	s_barrier
	s_setprio 1
	v_mfma_f32_16x16x32_bf16 v[52:55], v[200:203], v[144:147], v[52:55]
	v_mfma_f32_16x16x32_bf16 v[44:47], v[208:211], v[144:147], v[44:47]
	v_mfma_f32_16x16x32_bf16 v[36:39], v[200:203], v[152:155], v[36:39]
	v_mfma_f32_16x16x32_bf16 v[32:35], v[208:211], v[152:155], v[32:35]
	v_mfma_f32_16x16x32_bf16 v[20:23], v[200:203], v[160:163], v[20:23]
	v_mfma_f32_16x16x32_bf16 v[12:15], v[208:211], v[160:163], v[12:15]
	v_mfma_f32_16x16x32_bf16 v[4:7], v[200:203], v[168:171], v[4:7]
	v_mfma_f32_16x16x32_bf16 v[0:3], v[208:211], v[168:171], v[0:3]
	v_mfma_f32_16x16x32_bf16 v[52:55], v[204:207], v[148:151], v[52:55]
	v_mfma_f32_16x16x32_bf16 v[44:47], v[220:223], v[148:151], v[44:47]
	v_mfma_f32_16x16x32_bf16 v[36:39], v[204:207], v[156:159], v[36:39]
	v_mfma_f32_16x16x32_bf16 v[32:35], v[220:223], v[156:159], v[32:35]
	v_mfma_f32_16x16x32_bf16 v[20:23], v[204:207], v[164:167], v[20:23]
	v_mfma_f32_16x16x32_bf16 v[12:15], v[220:223], v[164:167], v[12:15]
	v_mfma_f32_16x16x32_bf16 v[4:7], v[204:207], v[172:175], v[4:7]
	v_mfma_f32_16x16x32_bf16 v[0:3], v[220:223], v[172:175], v[0:3]
	s_setprio 0
	s_barrier
	s_add_u32 s68, s68, 0x100
	s_addc_u32 s69, s69, 0
	s_cmp_ge_i32 vcc_lo, s67
	s_mov_b64 s[38:39], s[50:51]
	s_mov_b32 s52, vcc_lo
	s_cbranch_scc0 .LBB0_3919
	s_branch .Lpeel_exit_7

;     __device__ __forceinline__ void operator()(AccRef acc, const pg8::Unit& u, int wr, int wc, int fr, int fq) const {
;         const int row0 = u.pm * 256 + wr * 64 + fr, col0 = u.pn * 256 + wc * 32 + 4 * fq;
;         const int v = u.pm < 32 ? (u.pm >> 3) : 4;
;         f32x4 gv[2][2];
; #pragma unroll
;         for (int bj = 0; bj < 2; ++bj)
; #pragma unroll
;             for (int n = 0; n < 2; ++n) gv[bj][n] = *(const f32x4*)(gate + (size_t)v * MODW + col0 + bj * 128 + n * 16) * coef;
.Lpeel_exit_7:
	s_cmp_gt_i32 s28, 31
	s_mov_b64 s[38:39], 0x12000
	s_cbranch_scc1 .LBB0_3922
	s_ashr_i32 s14, s28, 3
	s_mul_hi_i32 s39, s14, 0x4800
	s_mul_i32 s38, s14, 0x4800
